# phase-1 row loops: wave sum of squares via DPP adds + readlanes instead of six serialized ds_bpermute round trips (x rows and context rows)
# speedup vs baseline: 1.0062x; 1.0062x over previous
.Lp1_enter:
	s_cmpk_eq_i32 s82, 0x100
	s_cselect_b64 s[2:3], -1, 0
	s_cmpk_lg_i32 s82, 0x100
	s_cselect_b64 s[0:1], -1, 0
	v_writelane_b32 v240, s0, 11
	s_cmp_lt_i32 s81, 32
	v_lshrrev_b32_e32 v205, 6, v193
	v_writelane_b32 v240, s1, 12
	s_cselect_b64 s[0:1], -1, 0
	v_writelane_b32 v240, s2, 23
	v_and_b32_e32 v192, 63, v193
	v_mbcnt_lo_u32_b32 v207, -1, 0
	v_writelane_b32 v240, s3, 24
	s_and_b64 s[2:3], s[0:1], s[2:3]
	s_andn2_b64 vcc, exec, s[2:3]
	s_waitcnt lgkmcnt(0)
	s_barrier
	s_cbranch_vccnz .LBB0_168
	v_readfirstlane_b32 s3, v205
	v_lshlrev_b32_e32 v194, 4, v192
	v_lshlrev_b32_e32 v196, 3, v192
	v_mbcnt_hi_u32_b32 v197, -1, v207
	v_readlane_b32 s18, v241, 2
	v_readlane_b32 s19, v241, 3
	v_add_u32_e32 v195, 0x1000, v194
	v_xor_b32_e32 v198, 32, v197
	v_lshlrev_b32_e32 v198, 2, v198
	v_xor_b32_e32 v199, 16, v197
	v_lshlrev_b32_e32 v199, 2, v199
	v_xor_b32_e32 v200, 8, v197
	v_lshlrev_b32_e32 v200, 2, v200
	v_xor_b32_e32 v201, 4, v197
	v_lshlrev_b32_e32 v201, 2, v201
	v_xor_b32_e32 v202, 2, v197
	v_lshlrev_b32_e32 v202, 2, v202
	v_xor_b32_e32 v203, 1, v197
	v_lshlrev_b32_e32 v203, 2, v203
	v_mov_b32_e32 v208, 0x358637bd
	s_mov_b32 s27, 0x800000
	s_lshr_b32 s2, s81, 2
	s_lshl_b32 s2, s2, 8
	s_lshl_b32 s3, s3, 5
	s_add_u32 s2, s2, s3
	s_lshl_b32 s4, s2, 12
	s_add_u32 s14, s56, s4
	s_addc_u32 s15, s57, 0
	s_add_u32 s2, s2, 0x8000
	s_lshl_b32 s4, s2, 11
	s_add_u32 s10, s94, s4
	s_addc_u32 s11, s95, 0
	s_add_u32 s16, s18, 0x18000
	s_addc_u32 s17, s19, 0
	global_load_dwordx4 v[0:3], v194, s[60:61]
	global_load_dwordx4 v[4:7], v194, s[60:61] offset:1024
	global_load_dwordx4 v[8:11], v194, s[60:61] offset:2048
	global_load_dwordx4 v[12:15], v194, s[60:61] offset:3072
	global_load_dwordx4 v[160:163], v194, s[16:17]
	global_load_dwordx4 v[164:167], v194, s[16:17] offset:1024
	global_load_dwordx4 v[168:171], v194, s[16:17] offset:2048
	global_load_dwordx4 v[172:175], v194, s[16:17] offset:3072
	global_load_dwordx4 v[144:147], v195, s[16:17]
	global_load_dwordx4 v[148:151], v195, s[16:17] offset:1024
	global_load_dwordx4 v[152:155], v195, s[16:17] offset:2048
	global_load_dwordx4 v[156:159], v195, s[16:17] offset:3072
	global_load_dwordx4 v[16:19], v194, s[14:15]
	global_load_dwordx4 v[20:23], v194, s[14:15] offset:1024
	global_load_dwordx4 v[24:27], v194, s[14:15] offset:2048
	global_load_dwordx4 v[28:31], v194, s[14:15] offset:3072
	global_load_dwordx4 v[32:35], v195, s[14:15]
	global_load_dwordx4 v[36:39], v195, s[14:15] offset:1024
	global_load_dwordx4 v[40:43], v195, s[14:15] offset:2048
	global_load_dwordx4 v[44:47], v195, s[14:15] offset:3072
	s_add_u32 s14, s14, 0x2000
	s_addc_u32 s15, s15, 0
	global_load_dwordx4 v[48:51], v194, s[14:15]
	global_load_dwordx4 v[52:55], v194, s[14:15] offset:1024
	global_load_dwordx4 v[56:59], v194, s[14:15] offset:2048
	global_load_dwordx4 v[60:63], v194, s[14:15] offset:3072
	global_load_dwordx4 v[64:67], v195, s[14:15]
	global_load_dwordx4 v[68:71], v195, s[14:15] offset:1024
	global_load_dwordx4 v[72:75], v195, s[14:15] offset:2048
	global_load_dwordx4 v[76:79], v195, s[14:15] offset:3072
	s_add_u32 s14, s14, 0x2000
	s_addc_u32 s15, s15, 0
	global_load_dwordx4 v[80:83], v194, s[14:15]
	global_load_dwordx4 v[84:87], v194, s[14:15] offset:1024
	global_load_dwordx4 v[88:91], v194, s[14:15] offset:2048
	global_load_dwordx4 v[92:95], v194, s[14:15] offset:3072
	global_load_dwordx4 v[96:99], v195, s[14:15]
	global_load_dwordx4 v[100:103], v195, s[14:15] offset:1024
	global_load_dwordx4 v[104:107], v195, s[14:15] offset:2048
	global_load_dwordx4 v[108:111], v195, s[14:15] offset:3072
	s_add_u32 s14, s14, 0x2000
	s_addc_u32 s15, s15, 0
	global_load_dwordx4 v[112:115], v194, s[14:15]
	global_load_dwordx4 v[116:119], v194, s[14:15] offset:1024
	global_load_dwordx4 v[120:123], v194, s[14:15] offset:2048
	global_load_dwordx4 v[124:127], v194, s[14:15] offset:3072
	global_load_dwordx4 v[128:131], v195, s[14:15]
	global_load_dwordx4 v[132:135], v195, s[14:15] offset:1024
	global_load_dwordx4 v[136:139], v195, s[14:15] offset:2048
	global_load_dwordx4 v[140:143], v195, s[14:15] offset:3072
	s_waitcnt vmcnt(32)
	v_add_f32_e32 v144, 1.0, v144
	v_add_f32_e32 v145, 1.0, v145
	v_add_f32_e32 v146, 1.0, v146
	v_add_f32_e32 v147, 1.0, v147
	v_add_f32_e32 v148, 1.0, v148
	v_add_f32_e32 v149, 1.0, v149
	v_add_f32_e32 v150, 1.0, v150
	v_add_f32_e32 v151, 1.0, v151
	v_add_f32_e32 v152, 1.0, v152
	v_add_f32_e32 v153, 1.0, v153
	v_add_f32_e32 v154, 1.0, v154
	v_add_f32_e32 v155, 1.0, v155
	v_add_f32_e32 v156, 1.0, v156
	v_add_f32_e32 v157, 1.0, v157
	v_add_f32_e32 v158, 1.0, v158
	v_add_f32_e32 v159, 1.0, v159
	s_waitcnt vmcnt(24)
	v_pk_mul_f32 v[178:179], v[16:17], v[16:17]
	v_pk_fma_f32 v[178:179], v[18:19], v[18:19], v[178:179]
	v_pk_fma_f32 v[178:179], v[20:21], v[20:21], v[178:179]
	v_pk_fma_f32 v[178:179], v[22:23], v[22:23], v[178:179]
	v_pk_fma_f32 v[178:179], v[24:25], v[24:25], v[178:179]
	v_pk_fma_f32 v[178:179], v[26:27], v[26:27], v[178:179]
	v_pk_fma_f32 v[178:179], v[28:29], v[28:29], v[178:179]
	v_pk_fma_f32 v[178:179], v[30:31], v[30:31], v[178:179]
	v_pk_mul_f32 v[180:181], v[32:33], v[32:33]
	v_pk_fma_f32 v[180:181], v[34:35], v[34:35], v[180:181]
	v_pk_fma_f32 v[180:181], v[36:37], v[36:37], v[180:181]
	v_pk_fma_f32 v[180:181], v[38:39], v[38:39], v[180:181]
	v_pk_fma_f32 v[180:181], v[40:41], v[40:41], v[180:181]
	v_pk_fma_f32 v[180:181], v[42:43], v[42:43], v[180:181]
	v_pk_fma_f32 v[180:181], v[44:45], v[44:45], v[180:181]
	v_pk_fma_f32 v[180:181], v[46:47], v[46:47], v[180:181]
	v_add_f32_e32 v176, v178, v179
	v_add_f32_e32 v177, v180, v181
	v_add_f32_dpp v176, v176, v176 quad_perm:[1,0,3,2] row_mask:0xf bank_mask:0xf bound_ctrl:1
	v_add_f32_dpp v177, v177, v177 quad_perm:[1,0,3,2] row_mask:0xf bank_mask:0xf bound_ctrl:1
	s_nop 0
	v_add_f32_dpp v176, v176, v176 quad_perm:[2,3,0,1] row_mask:0xf bank_mask:0xf bound_ctrl:1
	v_add_f32_dpp v177, v177, v177 quad_perm:[2,3,0,1] row_mask:0xf bank_mask:0xf bound_ctrl:1
	s_nop 0
	v_add_f32_dpp v176, v176, v176 row_half_mirror row_mask:0xf bank_mask:0xf bound_ctrl:1
	v_add_f32_dpp v177, v177, v177 row_half_mirror row_mask:0xf bank_mask:0xf bound_ctrl:1
	s_nop 0
	v_add_f32_dpp v176, v176, v176 row_mirror row_mask:0xf bank_mask:0xf bound_ctrl:1
	v_add_f32_dpp v177, v177, v177 row_mirror row_mask:0xf bank_mask:0xf bound_ctrl:1
	s_nop 1
	v_readlane_b32 s20, v176, 0
	v_readlane_b32 s24, v177, 0
	v_readlane_b32 s21, v176, 16
	v_readlane_b32 s25, v177, 16
	v_readlane_b32 s22, v176, 32
	v_readlane_b32 s26, v177, 32
	v_readlane_b32 s23, v176, 48
	v_readlane_b32 s28, v177, 48
	s_nop 1
	v_mov_b32_e32 v176, s21
	v_mov_b32_e32 v178, s23
	v_mov_b32_e32 v177, s25
	v_mov_b32_e32 v179, s28
	v_add_f32_e32 v176, s20, v176
	v_add_f32_e32 v178, s22, v178
	v_add_f32_e32 v177, s24, v177
	v_add_f32_e32 v179, s26, v179
	v_add_f32_e32 v176, v176, v178
	v_add_f32_e32 v177, v177, v179
	v_fmamk_f32 v176, v176, 0x3a800000, v208
	v_mul_f32_e32 v178, 0x4b800000, v176
	v_cmp_gt_f32_e32 vcc, s27, v176
	s_nop 1
	v_cndmask_b32_e32 v176, v176, v178, vcc
	v_rsq_f32_e32 v209, v176
	s_nop 0
	v_mul_f32_e32 v178, 0x45800000, v209
	v_cndmask_b32_e32 v209, v209, v178, vcc
	v_fmamk_f32 v177, v177, 0x3a800000, v208
	v_mul_f32_e32 v178, 0x4b800000, v177
	v_cmp_gt_f32_e32 vcc, s27, v177
	s_nop 1
	v_cndmask_b32_e32 v177, v177, v178, vcc
	v_rsq_f32_e32 v210, v177
	s_nop 0
	v_mul_f32_e32 v178, 0x45800000, v210
	v_cndmask_b32_e32 v210, v210, v178, vcc
	v_mul_f32_e32 v16, v16, v209
	v_mul_f32_e32 v16, v0, v16
	v_fma_f32 v16, v144, v16, v160
	v_mul_f32_e32 v17, v17, v209
	v_mul_f32_e32 v17, v1, v17
	v_fma_f32 v17, v145, v17, v161
	v_mul_f32_e32 v18, v18, v209
	v_mul_f32_e32 v18, v2, v18
	v_fma_f32 v18, v146, v18, v162
	v_mul_f32_e32 v19, v19, v209
	v_mul_f32_e32 v19, v3, v19
	v_fma_f32 v19, v147, v19, v163
	v_cvt_pk_bf16_f32 v180, v16, v17
	v_cvt_pk_bf16_f32 v181, v18, v19
	global_store_dwordx2 v196, v[180:181], s[10:11]
	s_nop 0
	v_mul_f32_e32 v20, v20, v209
	v_mul_f32_e32 v20, v4, v20
	v_fma_f32 v20, v148, v20, v164
	v_mul_f32_e32 v21, v21, v209
	v_mul_f32_e32 v21, v5, v21
	v_fma_f32 v21, v149, v21, v165
	v_mul_f32_e32 v22, v22, v209
	v_mul_f32_e32 v22, v6, v22
	v_fma_f32 v22, v150, v22, v166
	v_mul_f32_e32 v23, v23, v209
	v_mul_f32_e32 v23, v7, v23
	v_fma_f32 v23, v151, v23, v167
	v_cvt_pk_bf16_f32 v180, v20, v21
	v_cvt_pk_bf16_f32 v181, v22, v23
	global_store_dwordx2 v196, v[180:181], s[10:11] offset:512
	s_nop 0
	v_mul_f32_e32 v24, v24, v209
	v_mul_f32_e32 v24, v8, v24
	v_fma_f32 v24, v152, v24, v168
	v_mul_f32_e32 v25, v25, v209
	v_mul_f32_e32 v25, v9, v25
	v_fma_f32 v25, v153, v25, v169
	v_mul_f32_e32 v26, v26, v209
	v_mul_f32_e32 v26, v10, v26
	v_fma_f32 v26, v154, v26, v170
	v_mul_f32_e32 v27, v27, v209
	v_mul_f32_e32 v27, v11, v27
	v_fma_f32 v27, v155, v27, v171
	v_cvt_pk_bf16_f32 v180, v24, v25
	v_cvt_pk_bf16_f32 v181, v26, v27
	global_store_dwordx2 v196, v[180:181], s[10:11] offset:1024
	s_nop 0
	v_mul_f32_e32 v28, v28, v209
	v_mul_f32_e32 v28, v12, v28
	v_fma_f32 v28, v156, v28, v172
	v_mul_f32_e32 v29, v29, v209
	v_mul_f32_e32 v29, v13, v29
	v_fma_f32 v29, v157, v29, v173
	v_mul_f32_e32 v30, v30, v209
	v_mul_f32_e32 v30, v14, v30
	v_fma_f32 v30, v158, v30, v174
	v_mul_f32_e32 v31, v31, v209
	v_mul_f32_e32 v31, v15, v31
	v_fma_f32 v31, v159, v31, v175
	v_cvt_pk_bf16_f32 v180, v28, v29
	v_cvt_pk_bf16_f32 v181, v30, v31
	global_store_dwordx2 v196, v[180:181], s[10:11] offset:1536
	s_nop 0
	v_mul_f32_e32 v32, v32, v210
	v_mul_f32_e32 v32, v0, v32
	v_fma_f32 v32, v144, v32, v160
	v_mul_f32_e32 v33, v33, v210
	v_mul_f32_e32 v33, v1, v33
	v_fma_f32 v33, v145, v33, v161
	v_mul_f32_e32 v34, v34, v210
	v_mul_f32_e32 v34, v2, v34
	v_fma_f32 v34, v146, v34, v162
	v_mul_f32_e32 v35, v35, v210
	v_mul_f32_e32 v35, v3, v35
	v_fma_f32 v35, v147, v35, v163
	v_cvt_pk_bf16_f32 v180, v32, v33
	v_cvt_pk_bf16_f32 v181, v34, v35
	global_store_dwordx2 v196, v[180:181], s[10:11] offset:2048
	s_nop 0
	v_mul_f32_e32 v36, v36, v210
	v_mul_f32_e32 v36, v4, v36
	v_fma_f32 v36, v148, v36, v164
	v_mul_f32_e32 v37, v37, v210
	v_mul_f32_e32 v37, v5, v37
	v_fma_f32 v37, v149, v37, v165
	v_mul_f32_e32 v38, v38, v210
	v_mul_f32_e32 v38, v6, v38
	v_fma_f32 v38, v150, v38, v166
	v_mul_f32_e32 v39, v39, v210
	v_mul_f32_e32 v39, v7, v39
	v_fma_f32 v39, v151, v39, v167
	v_cvt_pk_bf16_f32 v180, v36, v37
	v_cvt_pk_bf16_f32 v181, v38, v39
	global_store_dwordx2 v196, v[180:181], s[10:11] offset:2560
	s_nop 0
	v_mul_f32_e32 v40, v40, v210
	v_mul_f32_e32 v40, v8, v40
	v_fma_f32 v40, v152, v40, v168
	v_mul_f32_e32 v41, v41, v210
	v_mul_f32_e32 v41, v9, v41
	v_fma_f32 v41, v153, v41, v169
	v_mul_f32_e32 v42, v42, v210
	v_mul_f32_e32 v42, v10, v42
	v_fma_f32 v42, v154, v42, v170
	v_mul_f32_e32 v43, v43, v210
	v_mul_f32_e32 v43, v11, v43
	v_fma_f32 v43, v155, v43, v171
	v_cvt_pk_bf16_f32 v180, v40, v41
	v_cvt_pk_bf16_f32 v181, v42, v43
	global_store_dwordx2 v196, v[180:181], s[10:11] offset:3072
	s_nop 0
	v_mul_f32_e32 v44, v44, v210
	v_mul_f32_e32 v44, v12, v44
	v_fma_f32 v44, v156, v44, v172
	v_mul_f32_e32 v45, v45, v210
	v_mul_f32_e32 v45, v13, v45
	v_fma_f32 v45, v157, v45, v173
	v_mul_f32_e32 v46, v46, v210
	v_mul_f32_e32 v46, v14, v46
	v_fma_f32 v46, v158, v46, v174
	v_mul_f32_e32 v47, v47, v210
	v_mul_f32_e32 v47, v15, v47
	v_fma_f32 v47, v159, v47, v175
	v_cvt_pk_bf16_f32 v180, v44, v45
	v_cvt_pk_bf16_f32 v181, v46, v47
	global_store_dwordx2 v196, v[180:181], s[10:11] offset:3584
	s_nop 0
	s_add_u32 s14, s14, 0x2000
	s_addc_u32 s15, s15, 0
	global_load_dwordx4 v[16:19], v194, s[14:15]
	global_load_dwordx4 v[20:23], v194, s[14:15] offset:1024
	global_load_dwordx4 v[24:27], v194, s[14:15] offset:2048
	global_load_dwordx4 v[28:31], v194, s[14:15] offset:3072
	global_load_dwordx4 v[32:35], v195, s[14:15]
	global_load_dwordx4 v[36:39], v195, s[14:15] offset:1024
	global_load_dwordx4 v[40:43], v195, s[14:15] offset:2048
	global_load_dwordx4 v[44:47], v195, s[14:15] offset:3072
	s_waitcnt vmcnt(32)
	v_pk_mul_f32 v[178:179], v[48:49], v[48:49]
	v_pk_fma_f32 v[178:179], v[50:51], v[50:51], v[178:179]
	v_pk_fma_f32 v[178:179], v[52:53], v[52:53], v[178:179]
	v_pk_fma_f32 v[178:179], v[54:55], v[54:55], v[178:179]
	v_pk_fma_f32 v[178:179], v[56:57], v[56:57], v[178:179]
	v_pk_fma_f32 v[178:179], v[58:59], v[58:59], v[178:179]
	v_pk_fma_f32 v[178:179], v[60:61], v[60:61], v[178:179]
	v_pk_fma_f32 v[178:179], v[62:63], v[62:63], v[178:179]
	v_pk_mul_f32 v[180:181], v[64:65], v[64:65]
	v_pk_fma_f32 v[180:181], v[66:67], v[66:67], v[180:181]
	v_pk_fma_f32 v[180:181], v[68:69], v[68:69], v[180:181]
	v_pk_fma_f32 v[180:181], v[70:71], v[70:71], v[180:181]
	v_pk_fma_f32 v[180:181], v[72:73], v[72:73], v[180:181]
	v_pk_fma_f32 v[180:181], v[74:75], v[74:75], v[180:181]
	v_pk_fma_f32 v[180:181], v[76:77], v[76:77], v[180:181]
	v_pk_fma_f32 v[180:181], v[78:79], v[78:79], v[180:181]
	v_add_f32_e32 v176, v178, v179
	v_add_f32_e32 v177, v180, v181
	v_add_f32_dpp v176, v176, v176 quad_perm:[1,0,3,2] row_mask:0xf bank_mask:0xf bound_ctrl:1
	v_add_f32_dpp v177, v177, v177 quad_perm:[1,0,3,2] row_mask:0xf bank_mask:0xf bound_ctrl:1
	s_nop 0
	v_add_f32_dpp v176, v176, v176 quad_perm:[2,3,0,1] row_mask:0xf bank_mask:0xf bound_ctrl:1
	v_add_f32_dpp v177, v177, v177 quad_perm:[2,3,0,1] row_mask:0xf bank_mask:0xf bound_ctrl:1
	s_nop 0
	v_add_f32_dpp v176, v176, v176 row_half_mirror row_mask:0xf bank_mask:0xf bound_ctrl:1
	v_add_f32_dpp v177, v177, v177 row_half_mirror row_mask:0xf bank_mask:0xf bound_ctrl:1
	s_nop 0
	v_add_f32_dpp v176, v176, v176 row_mirror row_mask:0xf bank_mask:0xf bound_ctrl:1
	v_add_f32_dpp v177, v177, v177 row_mirror row_mask:0xf bank_mask:0xf bound_ctrl:1
	s_nop 1
	v_readlane_b32 s20, v176, 0
	v_readlane_b32 s24, v177, 0
	v_readlane_b32 s21, v176, 16
	v_readlane_b32 s25, v177, 16
	v_readlane_b32 s22, v176, 32
	v_readlane_b32 s26, v177, 32
	v_readlane_b32 s23, v176, 48
	v_readlane_b32 s28, v177, 48
	s_nop 1
	v_mov_b32_e32 v176, s21
	v_mov_b32_e32 v178, s23
	v_mov_b32_e32 v177, s25
	v_mov_b32_e32 v179, s28
	v_add_f32_e32 v176, s20, v176
	v_add_f32_e32 v178, s22, v178
	v_add_f32_e32 v177, s24, v177
	v_add_f32_e32 v179, s26, v179
	v_add_f32_e32 v176, v176, v178
	v_add_f32_e32 v177, v177, v179
	v_fmamk_f32 v176, v176, 0x3a800000, v208
	v_mul_f32_e32 v178, 0x4b800000, v176
	v_cmp_gt_f32_e32 vcc, s27, v176
	s_nop 1
	v_cndmask_b32_e32 v176, v176, v178, vcc
	v_rsq_f32_e32 v209, v176
	s_nop 0
	v_mul_f32_e32 v178, 0x45800000, v209
	v_cndmask_b32_e32 v209, v209, v178, vcc
	v_fmamk_f32 v177, v177, 0x3a800000, v208
	v_mul_f32_e32 v178, 0x4b800000, v177
	v_cmp_gt_f32_e32 vcc, s27, v177
	s_nop 1
	v_cndmask_b32_e32 v177, v177, v178, vcc
	v_rsq_f32_e32 v210, v177
	s_nop 0
	v_mul_f32_e32 v178, 0x45800000, v210
	v_cndmask_b32_e32 v210, v210, v178, vcc
	s_add_u32 s10, s10, 0x1000
	s_addc_u32 s11, s11, 0
	v_mul_f32_e32 v48, v48, v209
	v_mul_f32_e32 v48, v0, v48
	v_fma_f32 v48, v144, v48, v160
	v_mul_f32_e32 v49, v49, v209
	v_mul_f32_e32 v49, v1, v49
	v_fma_f32 v49, v145, v49, v161
	v_mul_f32_e32 v50, v50, v209
	v_mul_f32_e32 v50, v2, v50
	v_fma_f32 v50, v146, v50, v162
	v_mul_f32_e32 v51, v51, v209
	v_mul_f32_e32 v51, v3, v51
	v_fma_f32 v51, v147, v51, v163
	v_cvt_pk_bf16_f32 v180, v48, v49
	v_cvt_pk_bf16_f32 v181, v50, v51
	global_store_dwordx2 v196, v[180:181], s[10:11]
	s_nop 0
	v_mul_f32_e32 v52, v52, v209
	v_mul_f32_e32 v52, v4, v52
	v_fma_f32 v52, v148, v52, v164
	v_mul_f32_e32 v53, v53, v209
	v_mul_f32_e32 v53, v5, v53
	v_fma_f32 v53, v149, v53, v165
	v_mul_f32_e32 v54, v54, v209
	v_mul_f32_e32 v54, v6, v54
	v_fma_f32 v54, v150, v54, v166
	v_mul_f32_e32 v55, v55, v209
	v_mul_f32_e32 v55, v7, v55
	v_fma_f32 v55, v151, v55, v167
	v_cvt_pk_bf16_f32 v180, v52, v53
	v_cvt_pk_bf16_f32 v181, v54, v55
	global_store_dwordx2 v196, v[180:181], s[10:11] offset:512
	s_nop 0
	v_mul_f32_e32 v56, v56, v209
	v_mul_f32_e32 v56, v8, v56
	v_fma_f32 v56, v152, v56, v168
	v_mul_f32_e32 v57, v57, v209
	v_mul_f32_e32 v57, v9, v57
	v_fma_f32 v57, v153, v57, v169
	v_mul_f32_e32 v58, v58, v209
	v_mul_f32_e32 v58, v10, v58
	v_fma_f32 v58, v154, v58, v170
	v_mul_f32_e32 v59, v59, v209
	v_mul_f32_e32 v59, v11, v59
	v_fma_f32 v59, v155, v59, v171
	v_cvt_pk_bf16_f32 v180, v56, v57
	v_cvt_pk_bf16_f32 v181, v58, v59
	global_store_dwordx2 v196, v[180:181], s[10:11] offset:1024
	s_nop 0
	v_mul_f32_e32 v60, v60, v209
	v_mul_f32_e32 v60, v12, v60
	v_fma_f32 v60, v156, v60, v172
	v_mul_f32_e32 v61, v61, v209
	v_mul_f32_e32 v61, v13, v61
	v_fma_f32 v61, v157, v61, v173
	v_mul_f32_e32 v62, v62, v209
	v_mul_f32_e32 v62, v14, v62
	v_fma_f32 v62, v158, v62, v174
	v_mul_f32_e32 v63, v63, v209
	v_mul_f32_e32 v63, v15, v63
	v_fma_f32 v63, v159, v63, v175
	v_cvt_pk_bf16_f32 v180, v60, v61
	v_cvt_pk_bf16_f32 v181, v62, v63
	global_store_dwordx2 v196, v[180:181], s[10:11] offset:1536
	s_nop 0
	v_mul_f32_e32 v64, v64, v210
	v_mul_f32_e32 v64, v0, v64
	v_fma_f32 v64, v144, v64, v160
	v_mul_f32_e32 v65, v65, v210
	v_mul_f32_e32 v65, v1, v65
	v_fma_f32 v65, v145, v65, v161
	v_mul_f32_e32 v66, v66, v210
	v_mul_f32_e32 v66, v2, v66
	v_fma_f32 v66, v146, v66, v162
	v_mul_f32_e32 v67, v67, v210
	v_mul_f32_e32 v67, v3, v67
	v_fma_f32 v67, v147, v67, v163
	v_cvt_pk_bf16_f32 v180, v64, v65
	v_cvt_pk_bf16_f32 v181, v66, v67
	global_store_dwordx2 v196, v[180:181], s[10:11] offset:2048
	s_nop 0
	v_mul_f32_e32 v68, v68, v210
	v_mul_f32_e32 v68, v4, v68
	v_fma_f32 v68, v148, v68, v164
	v_mul_f32_e32 v69, v69, v210
	v_mul_f32_e32 v69, v5, v69
	v_fma_f32 v69, v149, v69, v165
	v_mul_f32_e32 v70, v70, v210
	v_mul_f32_e32 v70, v6, v70
	v_fma_f32 v70, v150, v70, v166
	v_mul_f32_e32 v71, v71, v210
	v_mul_f32_e32 v71, v7, v71
	v_fma_f32 v71, v151, v71, v167
	v_cvt_pk_bf16_f32 v180, v68, v69
	v_cvt_pk_bf16_f32 v181, v70, v71
	global_store_dwordx2 v196, v[180:181], s[10:11] offset:2560
	s_nop 0
	v_mul_f32_e32 v72, v72, v210
	v_mul_f32_e32 v72, v8, v72
	v_fma_f32 v72, v152, v72, v168
	v_mul_f32_e32 v73, v73, v210
	v_mul_f32_e32 v73, v9, v73
	v_fma_f32 v73, v153, v73, v169
	v_mul_f32_e32 v74, v74, v210
	v_mul_f32_e32 v74, v10, v74
	v_fma_f32 v74, v154, v74, v170
	v_mul_f32_e32 v75, v75, v210
	v_mul_f32_e32 v75, v11, v75
	v_fma_f32 v75, v155, v75, v171
	v_cvt_pk_bf16_f32 v180, v72, v73
	v_cvt_pk_bf16_f32 v181, v74, v75
	global_store_dwordx2 v196, v[180:181], s[10:11] offset:3072
	s_nop 0
	v_mul_f32_e32 v76, v76, v210
	v_mul_f32_e32 v76, v12, v76
	v_fma_f32 v76, v156, v76, v172
	v_mul_f32_e32 v77, v77, v210
	v_mul_f32_e32 v77, v13, v77
	v_fma_f32 v77, v157, v77, v173
	v_mul_f32_e32 v78, v78, v210
	v_mul_f32_e32 v78, v14, v78
	v_fma_f32 v78, v158, v78, v174
	v_mul_f32_e32 v79, v79, v210
	v_mul_f32_e32 v79, v15, v79
	v_fma_f32 v79, v159, v79, v175
	v_cvt_pk_bf16_f32 v180, v76, v77
	v_cvt_pk_bf16_f32 v181, v78, v79
	global_store_dwordx2 v196, v[180:181], s[10:11] offset:3584
	s_nop 0
	s_add_u32 s14, s14, 0x2000
	s_addc_u32 s15, s15, 0
	global_load_dwordx4 v[48:51], v194, s[14:15]
	global_load_dwordx4 v[52:55], v194, s[14:15] offset:1024
	global_load_dwordx4 v[56:59], v194, s[14:15] offset:2048
	global_load_dwordx4 v[60:63], v194, s[14:15] offset:3072
	global_load_dwordx4 v[64:67], v195, s[14:15]
	global_load_dwordx4 v[68:71], v195, s[14:15] offset:1024
	global_load_dwordx4 v[72:75], v195, s[14:15] offset:2048
	global_load_dwordx4 v[76:79], v195, s[14:15] offset:3072
	s_waitcnt vmcnt(40)
	v_pk_mul_f32 v[178:179], v[80:81], v[80:81]
	v_pk_fma_f32 v[178:179], v[82:83], v[82:83], v[178:179]
	v_pk_fma_f32 v[178:179], v[84:85], v[84:85], v[178:179]
	v_pk_fma_f32 v[178:179], v[86:87], v[86:87], v[178:179]
	v_pk_fma_f32 v[178:179], v[88:89], v[88:89], v[178:179]
	v_pk_fma_f32 v[178:179], v[90:91], v[90:91], v[178:179]
	v_pk_fma_f32 v[178:179], v[92:93], v[92:93], v[178:179]
	v_pk_fma_f32 v[178:179], v[94:95], v[94:95], v[178:179]
	v_pk_mul_f32 v[180:181], v[96:97], v[96:97]
	v_pk_fma_f32 v[180:181], v[98:99], v[98:99], v[180:181]
	v_pk_fma_f32 v[180:181], v[100:101], v[100:101], v[180:181]
	v_pk_fma_f32 v[180:181], v[102:103], v[102:103], v[180:181]
	v_pk_fma_f32 v[180:181], v[104:105], v[104:105], v[180:181]
	v_pk_fma_f32 v[180:181], v[106:107], v[106:107], v[180:181]
	v_pk_fma_f32 v[180:181], v[108:109], v[108:109], v[180:181]
	v_pk_fma_f32 v[180:181], v[110:111], v[110:111], v[180:181]
	v_add_f32_e32 v176, v178, v179
	v_add_f32_e32 v177, v180, v181
	v_add_f32_dpp v176, v176, v176 quad_perm:[1,0,3,2] row_mask:0xf bank_mask:0xf bound_ctrl:1
	v_add_f32_dpp v177, v177, v177 quad_perm:[1,0,3,2] row_mask:0xf bank_mask:0xf bound_ctrl:1
	s_nop 0
	v_add_f32_dpp v176, v176, v176 quad_perm:[2,3,0,1] row_mask:0xf bank_mask:0xf bound_ctrl:1
	v_add_f32_dpp v177, v177, v177 quad_perm:[2,3,0,1] row_mask:0xf bank_mask:0xf bound_ctrl:1
	s_nop 0
	v_add_f32_dpp v176, v176, v176 row_half_mirror row_mask:0xf bank_mask:0xf bound_ctrl:1
	v_add_f32_dpp v177, v177, v177 row_half_mirror row_mask:0xf bank_mask:0xf bound_ctrl:1
	s_nop 0
	v_add_f32_dpp v176, v176, v176 row_mirror row_mask:0xf bank_mask:0xf bound_ctrl:1
	v_add_f32_dpp v177, v177, v177 row_mirror row_mask:0xf bank_mask:0xf bound_ctrl:1
	s_nop 1
	v_readlane_b32 s20, v176, 0
	v_readlane_b32 s24, v177, 0
	v_readlane_b32 s21, v176, 16
	v_readlane_b32 s25, v177, 16
	v_readlane_b32 s22, v176, 32
	v_readlane_b32 s26, v177, 32
	v_readlane_b32 s23, v176, 48
	v_readlane_b32 s28, v177, 48
	s_nop 1
	v_mov_b32_e32 v176, s21
	v_mov_b32_e32 v178, s23
	v_mov_b32_e32 v177, s25
	v_mov_b32_e32 v179, s28
	v_add_f32_e32 v176, s20, v176
	v_add_f32_e32 v178, s22, v178
	v_add_f32_e32 v177, s24, v177
	v_add_f32_e32 v179, s26, v179
	v_add_f32_e32 v176, v176, v178
	v_add_f32_e32 v177, v177, v179
	v_fmamk_f32 v176, v176, 0x3a800000, v208
	v_mul_f32_e32 v178, 0x4b800000, v176
	v_cmp_gt_f32_e32 vcc, s27, v176
	s_nop 1
	v_cndmask_b32_e32 v176, v176, v178, vcc
	v_rsq_f32_e32 v209, v176
	s_nop 0
	v_mul_f32_e32 v178, 0x45800000, v209
	v_cndmask_b32_e32 v209, v209, v178, vcc
	v_fmamk_f32 v177, v177, 0x3a800000, v208
	v_mul_f32_e32 v178, 0x4b800000, v177
	v_cmp_gt_f32_e32 vcc, s27, v177
	s_nop 1
	v_cndmask_b32_e32 v177, v177, v178, vcc
	v_rsq_f32_e32 v210, v177
	s_nop 0
	v_mul_f32_e32 v178, 0x45800000, v210
	v_cndmask_b32_e32 v210, v210, v178, vcc
	s_add_u32 s10, s10, 0x1000
	s_addc_u32 s11, s11, 0
	v_mul_f32_e32 v80, v80, v209
	v_mul_f32_e32 v80, v0, v80
	v_fma_f32 v80, v144, v80, v160
	v_mul_f32_e32 v81, v81, v209
	v_mul_f32_e32 v81, v1, v81
	v_fma_f32 v81, v145, v81, v161
	v_mul_f32_e32 v82, v82, v209
	v_mul_f32_e32 v82, v2, v82
	v_fma_f32 v82, v146, v82, v162
	v_mul_f32_e32 v83, v83, v209
	v_mul_f32_e32 v83, v3, v83
	v_fma_f32 v83, v147, v83, v163
	v_cvt_pk_bf16_f32 v180, v80, v81
	v_cvt_pk_bf16_f32 v181, v82, v83
	global_store_dwordx2 v196, v[180:181], s[10:11]
	s_nop 0
	v_mul_f32_e32 v84, v84, v209
	v_mul_f32_e32 v84, v4, v84
	v_fma_f32 v84, v148, v84, v164
	v_mul_f32_e32 v85, v85, v209
	v_mul_f32_e32 v85, v5, v85
	v_fma_f32 v85, v149, v85, v165
	v_mul_f32_e32 v86, v86, v209
	v_mul_f32_e32 v86, v6, v86
	v_fma_f32 v86, v150, v86, v166
	v_mul_f32_e32 v87, v87, v209
	v_mul_f32_e32 v87, v7, v87
	v_fma_f32 v87, v151, v87, v167
	v_cvt_pk_bf16_f32 v180, v84, v85
	v_cvt_pk_bf16_f32 v181, v86, v87
	global_store_dwordx2 v196, v[180:181], s[10:11] offset:512
	s_nop 0
	v_mul_f32_e32 v88, v88, v209
	v_mul_f32_e32 v88, v8, v88
	v_fma_f32 v88, v152, v88, v168
	v_mul_f32_e32 v89, v89, v209
	v_mul_f32_e32 v89, v9, v89
	v_fma_f32 v89, v153, v89, v169
	v_mul_f32_e32 v90, v90, v209
	v_mul_f32_e32 v90, v10, v90
	v_fma_f32 v90, v154, v90, v170
	v_mul_f32_e32 v91, v91, v209
	v_mul_f32_e32 v91, v11, v91
	v_fma_f32 v91, v155, v91, v171
	v_cvt_pk_bf16_f32 v180, v88, v89
	v_cvt_pk_bf16_f32 v181, v90, v91
	global_store_dwordx2 v196, v[180:181], s[10:11] offset:1024
	s_nop 0
	v_mul_f32_e32 v92, v92, v209
	v_mul_f32_e32 v92, v12, v92
	v_fma_f32 v92, v156, v92, v172
	v_mul_f32_e32 v93, v93, v209
	v_mul_f32_e32 v93, v13, v93
	v_fma_f32 v93, v157, v93, v173
	v_mul_f32_e32 v94, v94, v209
	v_mul_f32_e32 v94, v14, v94
	v_fma_f32 v94, v158, v94, v174
	v_mul_f32_e32 v95, v95, v209
	v_mul_f32_e32 v95, v15, v95
	v_fma_f32 v95, v159, v95, v175
	v_cvt_pk_bf16_f32 v180, v92, v93
	v_cvt_pk_bf16_f32 v181, v94, v95
	global_store_dwordx2 v196, v[180:181], s[10:11] offset:1536
	s_nop 0
	v_mul_f32_e32 v96, v96, v210
	v_mul_f32_e32 v96, v0, v96
	v_fma_f32 v96, v144, v96, v160
	v_mul_f32_e32 v97, v97, v210
	v_mul_f32_e32 v97, v1, v97
	v_fma_f32 v97, v145, v97, v161
	v_mul_f32_e32 v98, v98, v210
	v_mul_f32_e32 v98, v2, v98
	v_fma_f32 v98, v146, v98, v162
	v_mul_f32_e32 v99, v99, v210
	v_mul_f32_e32 v99, v3, v99
	v_fma_f32 v99, v147, v99, v163
	v_cvt_pk_bf16_f32 v180, v96, v97
	v_cvt_pk_bf16_f32 v181, v98, v99
	global_store_dwordx2 v196, v[180:181], s[10:11] offset:2048
	s_nop 0
	v_mul_f32_e32 v100, v100, v210
	v_mul_f32_e32 v100, v4, v100
	v_fma_f32 v100, v148, v100, v164
	v_mul_f32_e32 v101, v101, v210
	v_mul_f32_e32 v101, v5, v101
	v_fma_f32 v101, v149, v101, v165
	v_mul_f32_e32 v102, v102, v210
	v_mul_f32_e32 v102, v6, v102
	v_fma_f32 v102, v150, v102, v166
	v_mul_f32_e32 v103, v103, v210
	v_mul_f32_e32 v103, v7, v103
	v_fma_f32 v103, v151, v103, v167
	v_cvt_pk_bf16_f32 v180, v100, v101
	v_cvt_pk_bf16_f32 v181, v102, v103
	global_store_dwordx2 v196, v[180:181], s[10:11] offset:2560
	s_nop 0
	v_mul_f32_e32 v104, v104, v210
	v_mul_f32_e32 v104, v8, v104
	v_fma_f32 v104, v152, v104, v168
	v_mul_f32_e32 v105, v105, v210
	v_mul_f32_e32 v105, v9, v105
	v_fma_f32 v105, v153, v105, v169
	v_mul_f32_e32 v106, v106, v210
	v_mul_f32_e32 v106, v10, v106
	v_fma_f32 v106, v154, v106, v170
	v_mul_f32_e32 v107, v107, v210
	v_mul_f32_e32 v107, v11, v107
	v_fma_f32 v107, v155, v107, v171
	v_cvt_pk_bf16_f32 v180, v104, v105
	v_cvt_pk_bf16_f32 v181, v106, v107
	global_store_dwordx2 v196, v[180:181], s[10:11] offset:3072
	s_nop 0
	v_mul_f32_e32 v108, v108, v210
	v_mul_f32_e32 v108, v12, v108
	v_fma_f32 v108, v156, v108, v172
	v_mul_f32_e32 v109, v109, v210
	v_mul_f32_e32 v109, v13, v109
	v_fma_f32 v109, v157, v109, v173
	v_mul_f32_e32 v110, v110, v210
	v_mul_f32_e32 v110, v14, v110
	v_fma_f32 v110, v158, v110, v174
	v_mul_f32_e32 v111, v111, v210
	v_mul_f32_e32 v111, v15, v111
	v_fma_f32 v111, v159, v111, v175
	v_cvt_pk_bf16_f32 v180, v108, v109
	v_cvt_pk_bf16_f32 v181, v110, v111
	global_store_dwordx2 v196, v[180:181], s[10:11] offset:3584
	s_nop 0
	s_add_u32 s14, s14, 0x2000
	s_addc_u32 s15, s15, 0
	global_load_dwordx4 v[80:83], v194, s[14:15]
	global_load_dwordx4 v[84:87], v194, s[14:15] offset:1024
	global_load_dwordx4 v[88:91], v194, s[14:15] offset:2048
	global_load_dwordx4 v[92:95], v194, s[14:15] offset:3072
	global_load_dwordx4 v[96:99], v195, s[14:15]
	global_load_dwordx4 v[100:103], v195, s[14:15] offset:1024
	global_load_dwordx4 v[104:107], v195, s[14:15] offset:2048
	global_load_dwordx4 v[108:111], v195, s[14:15] offset:3072
	s_waitcnt vmcnt(48)
	v_pk_mul_f32 v[178:179], v[112:113], v[112:113]
	v_pk_fma_f32 v[178:179], v[114:115], v[114:115], v[178:179]
	v_pk_fma_f32 v[178:179], v[116:117], v[116:117], v[178:179]
	v_pk_fma_f32 v[178:179], v[118:119], v[118:119], v[178:179]
	v_pk_fma_f32 v[178:179], v[120:121], v[120:121], v[178:179]
	v_pk_fma_f32 v[178:179], v[122:123], v[122:123], v[178:179]
	v_pk_fma_f32 v[178:179], v[124:125], v[124:125], v[178:179]
	v_pk_fma_f32 v[178:179], v[126:127], v[126:127], v[178:179]
	v_pk_mul_f32 v[180:181], v[128:129], v[128:129]
	v_pk_fma_f32 v[180:181], v[130:131], v[130:131], v[180:181]
	v_pk_fma_f32 v[180:181], v[132:133], v[132:133], v[180:181]
	v_pk_fma_f32 v[180:181], v[134:135], v[134:135], v[180:181]
	v_pk_fma_f32 v[180:181], v[136:137], v[136:137], v[180:181]
	v_pk_fma_f32 v[180:181], v[138:139], v[138:139], v[180:181]
	v_pk_fma_f32 v[180:181], v[140:141], v[140:141], v[180:181]
	v_pk_fma_f32 v[180:181], v[142:143], v[142:143], v[180:181]
	v_add_f32_e32 v176, v178, v179
	v_add_f32_e32 v177, v180, v181
	v_add_f32_dpp v176, v176, v176 quad_perm:[1,0,3,2] row_mask:0xf bank_mask:0xf bound_ctrl:1
	v_add_f32_dpp v177, v177, v177 quad_perm:[1,0,3,2] row_mask:0xf bank_mask:0xf bound_ctrl:1
	s_nop 0
	v_add_f32_dpp v176, v176, v176 quad_perm:[2,3,0,1] row_mask:0xf bank_mask:0xf bound_ctrl:1
	v_add_f32_dpp v177, v177, v177 quad_perm:[2,3,0,1] row_mask:0xf bank_mask:0xf bound_ctrl:1
	s_nop 0
	v_add_f32_dpp v176, v176, v176 row_half_mirror row_mask:0xf bank_mask:0xf bound_ctrl:1
	v_add_f32_dpp v177, v177, v177 row_half_mirror row_mask:0xf bank_mask:0xf bound_ctrl:1
	s_nop 0
	v_add_f32_dpp v176, v176, v176 row_mirror row_mask:0xf bank_mask:0xf bound_ctrl:1
	v_add_f32_dpp v177, v177, v177 row_mirror row_mask:0xf bank_mask:0xf bound_ctrl:1
	s_nop 1
	v_readlane_b32 s20, v176, 0
	v_readlane_b32 s24, v177, 0
	v_readlane_b32 s21, v176, 16
	v_readlane_b32 s25, v177, 16
	v_readlane_b32 s22, v176, 32
	v_readlane_b32 s26, v177, 32
	v_readlane_b32 s23, v176, 48
	v_readlane_b32 s28, v177, 48
	s_nop 1
	v_mov_b32_e32 v176, s21
	v_mov_b32_e32 v178, s23
	v_mov_b32_e32 v177, s25
	v_mov_b32_e32 v179, s28
	v_add_f32_e32 v176, s20, v176
	v_add_f32_e32 v178, s22, v178
	v_add_f32_e32 v177, s24, v177
	v_add_f32_e32 v179, s26, v179
	v_add_f32_e32 v176, v176, v178
	v_add_f32_e32 v177, v177, v179
	v_fmamk_f32 v176, v176, 0x3a800000, v208
	v_mul_f32_e32 v178, 0x4b800000, v176
	v_cmp_gt_f32_e32 vcc, s27, v176
	s_nop 1
	v_cndmask_b32_e32 v176, v176, v178, vcc
	v_rsq_f32_e32 v209, v176
	s_nop 0
	v_mul_f32_e32 v178, 0x45800000, v209
	v_cndmask_b32_e32 v209, v209, v178, vcc
	v_fmamk_f32 v177, v177, 0x3a800000, v208
	v_mul_f32_e32 v178, 0x4b800000, v177
	v_cmp_gt_f32_e32 vcc, s27, v177
	s_nop 1
	v_cndmask_b32_e32 v177, v177, v178, vcc
	v_rsq_f32_e32 v210, v177
	s_nop 0
	v_mul_f32_e32 v178, 0x45800000, v210
	v_cndmask_b32_e32 v210, v210, v178, vcc
	s_add_u32 s10, s10, 0x1000
	s_addc_u32 s11, s11, 0
	v_mul_f32_e32 v112, v112, v209
	v_mul_f32_e32 v112, v0, v112
	v_fma_f32 v112, v144, v112, v160
	v_mul_f32_e32 v113, v113, v209
	v_mul_f32_e32 v113, v1, v113
	v_fma_f32 v113, v145, v113, v161
	v_mul_f32_e32 v114, v114, v209
	v_mul_f32_e32 v114, v2, v114
	v_fma_f32 v114, v146, v114, v162
	v_mul_f32_e32 v115, v115, v209
	v_mul_f32_e32 v115, v3, v115
	v_fma_f32 v115, v147, v115, v163
	v_cvt_pk_bf16_f32 v180, v112, v113
	v_cvt_pk_bf16_f32 v181, v114, v115
	global_store_dwordx2 v196, v[180:181], s[10:11]
	s_nop 0
	v_mul_f32_e32 v116, v116, v209
	v_mul_f32_e32 v116, v4, v116
	v_fma_f32 v116, v148, v116, v164
	v_mul_f32_e32 v117, v117, v209
	v_mul_f32_e32 v117, v5, v117
	v_fma_f32 v117, v149, v117, v165
	v_mul_f32_e32 v118, v118, v209
	v_mul_f32_e32 v118, v6, v118
	v_fma_f32 v118, v150, v118, v166
	v_mul_f32_e32 v119, v119, v209
	v_mul_f32_e32 v119, v7, v119
	v_fma_f32 v119, v151, v119, v167
	v_cvt_pk_bf16_f32 v180, v116, v117
	v_cvt_pk_bf16_f32 v181, v118, v119
	global_store_dwordx2 v196, v[180:181], s[10:11] offset:512
	s_nop 0
	v_mul_f32_e32 v120, v120, v209
	v_mul_f32_e32 v120, v8, v120
	v_fma_f32 v120, v152, v120, v168
	v_mul_f32_e32 v121, v121, v209
	v_mul_f32_e32 v121, v9, v121
	v_fma_f32 v121, v153, v121, v169
	v_mul_f32_e32 v122, v122, v209
	v_mul_f32_e32 v122, v10, v122
	v_fma_f32 v122, v154, v122, v170
	v_mul_f32_e32 v123, v123, v209
	v_mul_f32_e32 v123, v11, v123
	v_fma_f32 v123, v155, v123, v171
	v_cvt_pk_bf16_f32 v180, v120, v121
	v_cvt_pk_bf16_f32 v181, v122, v123
	global_store_dwordx2 v196, v[180:181], s[10:11] offset:1024
	s_nop 0
	v_mul_f32_e32 v124, v124, v209
	v_mul_f32_e32 v124, v12, v124
	v_fma_f32 v124, v156, v124, v172
	v_mul_f32_e32 v125, v125, v209
	v_mul_f32_e32 v125, v13, v125
	v_fma_f32 v125, v157, v125, v173
	v_mul_f32_e32 v126, v126, v209
	v_mul_f32_e32 v126, v14, v126
	v_fma_f32 v126, v158, v126, v174
	v_mul_f32_e32 v127, v127, v209
	v_mul_f32_e32 v127, v15, v127
	v_fma_f32 v127, v159, v127, v175
	v_cvt_pk_bf16_f32 v180, v124, v125
	v_cvt_pk_bf16_f32 v181, v126, v127
	global_store_dwordx2 v196, v[180:181], s[10:11] offset:1536
	s_nop 0
	v_mul_f32_e32 v128, v128, v210
	v_mul_f32_e32 v128, v0, v128
	v_fma_f32 v128, v144, v128, v160
	v_mul_f32_e32 v129, v129, v210
	v_mul_f32_e32 v129, v1, v129
	v_fma_f32 v129, v145, v129, v161
	v_mul_f32_e32 v130, v130, v210
	v_mul_f32_e32 v130, v2, v130
	v_fma_f32 v130, v146, v130, v162
	v_mul_f32_e32 v131, v131, v210
	v_mul_f32_e32 v131, v3, v131
	v_fma_f32 v131, v147, v131, v163
	v_cvt_pk_bf16_f32 v180, v128, v129
	v_cvt_pk_bf16_f32 v181, v130, v131
	global_store_dwordx2 v196, v[180:181], s[10:11] offset:2048
	s_nop 0
	v_mul_f32_e32 v132, v132, v210
	v_mul_f32_e32 v132, v4, v132
	v_fma_f32 v132, v148, v132, v164
	v_mul_f32_e32 v133, v133, v210
	v_mul_f32_e32 v133, v5, v133
	v_fma_f32 v133, v149, v133, v165
	v_mul_f32_e32 v134, v134, v210
	v_mul_f32_e32 v134, v6, v134
	v_fma_f32 v134, v150, v134, v166
	v_mul_f32_e32 v135, v135, v210
	v_mul_f32_e32 v135, v7, v135
	v_fma_f32 v135, v151, v135, v167
	v_cvt_pk_bf16_f32 v180, v132, v133
	v_cvt_pk_bf16_f32 v181, v134, v135
	global_store_dwordx2 v196, v[180:181], s[10:11] offset:2560
	s_nop 0
	v_mul_f32_e32 v136, v136, v210
	v_mul_f32_e32 v136, v8, v136
	v_fma_f32 v136, v152, v136, v168
	v_mul_f32_e32 v137, v137, v210
	v_mul_f32_e32 v137, v9, v137
	v_fma_f32 v137, v153, v137, v169
	v_mul_f32_e32 v138, v138, v210
	v_mul_f32_e32 v138, v10, v138
	v_fma_f32 v138, v154, v138, v170
	v_mul_f32_e32 v139, v139, v210
	v_mul_f32_e32 v139, v11, v139
	v_fma_f32 v139, v155, v139, v171
	v_cvt_pk_bf16_f32 v180, v136, v137
	v_cvt_pk_bf16_f32 v181, v138, v139
	global_store_dwordx2 v196, v[180:181], s[10:11] offset:3072
	s_nop 0
	v_mul_f32_e32 v140, v140, v210
	v_mul_f32_e32 v140, v12, v140
	v_fma_f32 v140, v156, v140, v172
	v_mul_f32_e32 v141, v141, v210
	v_mul_f32_e32 v141, v13, v141
	v_fma_f32 v141, v157, v141, v173
	v_mul_f32_e32 v142, v142, v210
	v_mul_f32_e32 v142, v14, v142
	v_fma_f32 v142, v158, v142, v174
	v_mul_f32_e32 v143, v143, v210
	v_mul_f32_e32 v143, v15, v143
	v_fma_f32 v143, v159, v143, v175
	v_cvt_pk_bf16_f32 v180, v140, v141
	v_cvt_pk_bf16_f32 v181, v142, v143
	global_store_dwordx2 v196, v[180:181], s[10:11] offset:3584
	s_nop 0
	s_add_u32 s14, s14, 0x2000
	s_addc_u32 s15, s15, 0
	global_load_dwordx4 v[112:115], v194, s[14:15]
	global_load_dwordx4 v[116:119], v194, s[14:15] offset:1024
	global_load_dwordx4 v[120:123], v194, s[14:15] offset:2048
	global_load_dwordx4 v[124:127], v194, s[14:15] offset:3072
	global_load_dwordx4 v[128:131], v195, s[14:15]
	global_load_dwordx4 v[132:135], v195, s[14:15] offset:1024
	global_load_dwordx4 v[136:139], v195, s[14:15] offset:2048
	global_load_dwordx4 v[140:143], v195, s[14:15] offset:3072
	s_waitcnt vmcnt(48)
	v_pk_mul_f32 v[178:179], v[16:17], v[16:17]
	v_pk_fma_f32 v[178:179], v[18:19], v[18:19], v[178:179]
	v_pk_fma_f32 v[178:179], v[20:21], v[20:21], v[178:179]
	v_pk_fma_f32 v[178:179], v[22:23], v[22:23], v[178:179]
	v_pk_fma_f32 v[178:179], v[24:25], v[24:25], v[178:179]
	v_pk_fma_f32 v[178:179], v[26:27], v[26:27], v[178:179]
	v_pk_fma_f32 v[178:179], v[28:29], v[28:29], v[178:179]
	v_pk_fma_f32 v[178:179], v[30:31], v[30:31], v[178:179]
	v_pk_mul_f32 v[180:181], v[32:33], v[32:33]
	v_pk_fma_f32 v[180:181], v[34:35], v[34:35], v[180:181]
	v_pk_fma_f32 v[180:181], v[36:37], v[36:37], v[180:181]
	v_pk_fma_f32 v[180:181], v[38:39], v[38:39], v[180:181]
	v_pk_fma_f32 v[180:181], v[40:41], v[40:41], v[180:181]
	v_pk_fma_f32 v[180:181], v[42:43], v[42:43], v[180:181]
	v_pk_fma_f32 v[180:181], v[44:45], v[44:45], v[180:181]
	v_pk_fma_f32 v[180:181], v[46:47], v[46:47], v[180:181]
	v_add_f32_e32 v176, v178, v179
	v_add_f32_e32 v177, v180, v181
	v_add_f32_dpp v176, v176, v176 quad_perm:[1,0,3,2] row_mask:0xf bank_mask:0xf bound_ctrl:1
	v_add_f32_dpp v177, v177, v177 quad_perm:[1,0,3,2] row_mask:0xf bank_mask:0xf bound_ctrl:1
	s_nop 0
	v_add_f32_dpp v176, v176, v176 quad_perm:[2,3,0,1] row_mask:0xf bank_mask:0xf bound_ctrl:1
	v_add_f32_dpp v177, v177, v177 quad_perm:[2,3,0,1] row_mask:0xf bank_mask:0xf bound_ctrl:1
	s_nop 0
	v_add_f32_dpp v176, v176, v176 row_half_mirror row_mask:0xf bank_mask:0xf bound_ctrl:1
	v_add_f32_dpp v177, v177, v177 row_half_mirror row_mask:0xf bank_mask:0xf bound_ctrl:1
	s_nop 0
	v_add_f32_dpp v176, v176, v176 row_mirror row_mask:0xf bank_mask:0xf bound_ctrl:1
	v_add_f32_dpp v177, v177, v177 row_mirror row_mask:0xf bank_mask:0xf bound_ctrl:1
	s_nop 1
	v_readlane_b32 s20, v176, 0
	v_readlane_b32 s24, v177, 0
	v_readlane_b32 s21, v176, 16
	v_readlane_b32 s25, v177, 16
	v_readlane_b32 s22, v176, 32
	v_readlane_b32 s26, v177, 32
	v_readlane_b32 s23, v176, 48
	v_readlane_b32 s28, v177, 48
	s_nop 1
	v_mov_b32_e32 v176, s21
	v_mov_b32_e32 v178, s23
	v_mov_b32_e32 v177, s25
	v_mov_b32_e32 v179, s28
	v_add_f32_e32 v176, s20, v176
	v_add_f32_e32 v178, s22, v178
	v_add_f32_e32 v177, s24, v177
	v_add_f32_e32 v179, s26, v179
	v_add_f32_e32 v176, v176, v178
	v_add_f32_e32 v177, v177, v179
	v_fmamk_f32 v176, v176, 0x3a800000, v208
	v_mul_f32_e32 v178, 0x4b800000, v176
	v_cmp_gt_f32_e32 vcc, s27, v176
	s_nop 1
	v_cndmask_b32_e32 v176, v176, v178, vcc
	v_rsq_f32_e32 v209, v176
	s_nop 0
	v_mul_f32_e32 v178, 0x45800000, v209
	v_cndmask_b32_e32 v209, v209, v178, vcc
	v_fmamk_f32 v177, v177, 0x3a800000, v208
	v_mul_f32_e32 v178, 0x4b800000, v177
	v_cmp_gt_f32_e32 vcc, s27, v177
	s_nop 1
	v_cndmask_b32_e32 v177, v177, v178, vcc
	v_rsq_f32_e32 v210, v177
	s_nop 0
	v_mul_f32_e32 v178, 0x45800000, v210
	v_cndmask_b32_e32 v210, v210, v178, vcc
	s_add_u32 s10, s10, 0x1000
	s_addc_u32 s11, s11, 0
	v_mul_f32_e32 v16, v16, v209
	v_mul_f32_e32 v16, v0, v16
	v_fma_f32 v16, v144, v16, v160
	v_mul_f32_e32 v17, v17, v209
	v_mul_f32_e32 v17, v1, v17
	v_fma_f32 v17, v145, v17, v161
	v_mul_f32_e32 v18, v18, v209
	v_mul_f32_e32 v18, v2, v18
	v_fma_f32 v18, v146, v18, v162
	v_mul_f32_e32 v19, v19, v209
	v_mul_f32_e32 v19, v3, v19
	v_fma_f32 v19, v147, v19, v163
	v_cvt_pk_bf16_f32 v180, v16, v17
	v_cvt_pk_bf16_f32 v181, v18, v19
	global_store_dwordx2 v196, v[180:181], s[10:11]
	s_nop 0
	v_mul_f32_e32 v20, v20, v209
	v_mul_f32_e32 v20, v4, v20
	v_fma_f32 v20, v148, v20, v164
	v_mul_f32_e32 v21, v21, v209
	v_mul_f32_e32 v21, v5, v21
	v_fma_f32 v21, v149, v21, v165
	v_mul_f32_e32 v22, v22, v209
	v_mul_f32_e32 v22, v6, v22
	v_fma_f32 v22, v150, v22, v166
	v_mul_f32_e32 v23, v23, v209
	v_mul_f32_e32 v23, v7, v23
	v_fma_f32 v23, v151, v23, v167
	v_cvt_pk_bf16_f32 v180, v20, v21
	v_cvt_pk_bf16_f32 v181, v22, v23
	global_store_dwordx2 v196, v[180:181], s[10:11] offset:512
	s_nop 0
	v_mul_f32_e32 v24, v24, v209
	v_mul_f32_e32 v24, v8, v24
	v_fma_f32 v24, v152, v24, v168
	v_mul_f32_e32 v25, v25, v209
	v_mul_f32_e32 v25, v9, v25
	v_fma_f32 v25, v153, v25, v169
	v_mul_f32_e32 v26, v26, v209
	v_mul_f32_e32 v26, v10, v26
	v_fma_f32 v26, v154, v26, v170
	v_mul_f32_e32 v27, v27, v209
	v_mul_f32_e32 v27, v11, v27
	v_fma_f32 v27, v155, v27, v171
	v_cvt_pk_bf16_f32 v180, v24, v25
	v_cvt_pk_bf16_f32 v181, v26, v27
	global_store_dwordx2 v196, v[180:181], s[10:11] offset:1024
	s_nop 0
	v_mul_f32_e32 v28, v28, v209
	v_mul_f32_e32 v28, v12, v28
	v_fma_f32 v28, v156, v28, v172
	v_mul_f32_e32 v29, v29, v209
	v_mul_f32_e32 v29, v13, v29
	v_fma_f32 v29, v157, v29, v173
	v_mul_f32_e32 v30, v30, v209
	v_mul_f32_e32 v30, v14, v30
	v_fma_f32 v30, v158, v30, v174
	v_mul_f32_e32 v31, v31, v209
	v_mul_f32_e32 v31, v15, v31
	v_fma_f32 v31, v159, v31, v175
	v_cvt_pk_bf16_f32 v180, v28, v29
	v_cvt_pk_bf16_f32 v181, v30, v31
	global_store_dwordx2 v196, v[180:181], s[10:11] offset:1536
	s_nop 0
	v_mul_f32_e32 v32, v32, v210
	v_mul_f32_e32 v32, v0, v32
	v_fma_f32 v32, v144, v32, v160
	v_mul_f32_e32 v33, v33, v210
	v_mul_f32_e32 v33, v1, v33
	v_fma_f32 v33, v145, v33, v161
	v_mul_f32_e32 v34, v34, v210
	v_mul_f32_e32 v34, v2, v34
	v_fma_f32 v34, v146, v34, v162
	v_mul_f32_e32 v35, v35, v210
	v_mul_f32_e32 v35, v3, v35
	v_fma_f32 v35, v147, v35, v163
	v_cvt_pk_bf16_f32 v180, v32, v33
	v_cvt_pk_bf16_f32 v181, v34, v35
	global_store_dwordx2 v196, v[180:181], s[10:11] offset:2048
	s_nop 0
	v_mul_f32_e32 v36, v36, v210
	v_mul_f32_e32 v36, v4, v36
	v_fma_f32 v36, v148, v36, v164
	v_mul_f32_e32 v37, v37, v210
	v_mul_f32_e32 v37, v5, v37
	v_fma_f32 v37, v149, v37, v165
	v_mul_f32_e32 v38, v38, v210
	v_mul_f32_e32 v38, v6, v38
	v_fma_f32 v38, v150, v38, v166
	v_mul_f32_e32 v39, v39, v210
	v_mul_f32_e32 v39, v7, v39
	v_fma_f32 v39, v151, v39, v167
	v_cvt_pk_bf16_f32 v180, v36, v37
	v_cvt_pk_bf16_f32 v181, v38, v39
	global_store_dwordx2 v196, v[180:181], s[10:11] offset:2560
	s_nop 0
	v_mul_f32_e32 v40, v40, v210
	v_mul_f32_e32 v40, v8, v40
	v_fma_f32 v40, v152, v40, v168
	v_mul_f32_e32 v41, v41, v210
	v_mul_f32_e32 v41, v9, v41
	v_fma_f32 v41, v153, v41, v169
	v_mul_f32_e32 v42, v42, v210
	v_mul_f32_e32 v42, v10, v42
	v_fma_f32 v42, v154, v42, v170
	v_mul_f32_e32 v43, v43, v210
	v_mul_f32_e32 v43, v11, v43
	v_fma_f32 v43, v155, v43, v171
	v_cvt_pk_bf16_f32 v180, v40, v41
	v_cvt_pk_bf16_f32 v181, v42, v43
	global_store_dwordx2 v196, v[180:181], s[10:11] offset:3072
	s_nop 0
	v_mul_f32_e32 v44, v44, v210
	v_mul_f32_e32 v44, v12, v44
	v_fma_f32 v44, v156, v44, v172
	v_mul_f32_e32 v45, v45, v210
	v_mul_f32_e32 v45, v13, v45
	v_fma_f32 v45, v157, v45, v173
	v_mul_f32_e32 v46, v46, v210
	v_mul_f32_e32 v46, v14, v46
	v_fma_f32 v46, v158, v46, v174
	v_mul_f32_e32 v47, v47, v210
	v_mul_f32_e32 v47, v15, v47
	v_fma_f32 v47, v159, v47, v175
	v_cvt_pk_bf16_f32 v180, v44, v45
	v_cvt_pk_bf16_f32 v181, v46, v47
	global_store_dwordx2 v196, v[180:181], s[10:11] offset:3584
	s_nop 0
	s_add_u32 s14, s14, 0x2000
	s_addc_u32 s15, s15, 0
	global_load_dwordx4 v[16:19], v194, s[14:15]
	global_load_dwordx4 v[20:23], v194, s[14:15] offset:1024
	global_load_dwordx4 v[24:27], v194, s[14:15] offset:2048
	global_load_dwordx4 v[28:31], v194, s[14:15] offset:3072
	global_load_dwordx4 v[32:35], v195, s[14:15]
	global_load_dwordx4 v[36:39], v195, s[14:15] offset:1024
	global_load_dwordx4 v[40:43], v195, s[14:15] offset:2048
	global_load_dwordx4 v[44:47], v195, s[14:15] offset:3072
	s_waitcnt vmcnt(48)
	v_pk_mul_f32 v[178:179], v[48:49], v[48:49]
	v_pk_fma_f32 v[178:179], v[50:51], v[50:51], v[178:179]
	v_pk_fma_f32 v[178:179], v[52:53], v[52:53], v[178:179]
	v_pk_fma_f32 v[178:179], v[54:55], v[54:55], v[178:179]
	v_pk_fma_f32 v[178:179], v[56:57], v[56:57], v[178:179]
	v_pk_fma_f32 v[178:179], v[58:59], v[58:59], v[178:179]
	v_pk_fma_f32 v[178:179], v[60:61], v[60:61], v[178:179]
	v_pk_fma_f32 v[178:179], v[62:63], v[62:63], v[178:179]
	v_pk_mul_f32 v[180:181], v[64:65], v[64:65]
	v_pk_fma_f32 v[180:181], v[66:67], v[66:67], v[180:181]
	v_pk_fma_f32 v[180:181], v[68:69], v[68:69], v[180:181]
	v_pk_fma_f32 v[180:181], v[70:71], v[70:71], v[180:181]
	v_pk_fma_f32 v[180:181], v[72:73], v[72:73], v[180:181]
	v_pk_fma_f32 v[180:181], v[74:75], v[74:75], v[180:181]
	v_pk_fma_f32 v[180:181], v[76:77], v[76:77], v[180:181]
	v_pk_fma_f32 v[180:181], v[78:79], v[78:79], v[180:181]
	v_add_f32_e32 v176, v178, v179
	v_add_f32_e32 v177, v180, v181
	v_add_f32_dpp v176, v176, v176 quad_perm:[1,0,3,2] row_mask:0xf bank_mask:0xf bound_ctrl:1
	v_add_f32_dpp v177, v177, v177 quad_perm:[1,0,3,2] row_mask:0xf bank_mask:0xf bound_ctrl:1
	s_nop 0
	v_add_f32_dpp v176, v176, v176 quad_perm:[2,3,0,1] row_mask:0xf bank_mask:0xf bound_ctrl:1
	v_add_f32_dpp v177, v177, v177 quad_perm:[2,3,0,1] row_mask:0xf bank_mask:0xf bound_ctrl:1
	s_nop 0
	v_add_f32_dpp v176, v176, v176 row_half_mirror row_mask:0xf bank_mask:0xf bound_ctrl:1
	v_add_f32_dpp v177, v177, v177 row_half_mirror row_mask:0xf bank_mask:0xf bound_ctrl:1
	s_nop 0
	v_add_f32_dpp v176, v176, v176 row_mirror row_mask:0xf bank_mask:0xf bound_ctrl:1
	v_add_f32_dpp v177, v177, v177 row_mirror row_mask:0xf bank_mask:0xf bound_ctrl:1
	s_nop 1
	v_readlane_b32 s20, v176, 0
	v_readlane_b32 s24, v177, 0
	v_readlane_b32 s21, v176, 16
	v_readlane_b32 s25, v177, 16
	v_readlane_b32 s22, v176, 32
	v_readlane_b32 s26, v177, 32
	v_readlane_b32 s23, v176, 48
	v_readlane_b32 s28, v177, 48
	s_nop 1
	v_mov_b32_e32 v176, s21
	v_mov_b32_e32 v178, s23
	v_mov_b32_e32 v177, s25
	v_mov_b32_e32 v179, s28
	v_add_f32_e32 v176, s20, v176
	v_add_f32_e32 v178, s22, v178
	v_add_f32_e32 v177, s24, v177
	v_add_f32_e32 v179, s26, v179
	v_add_f32_e32 v176, v176, v178
	v_add_f32_e32 v177, v177, v179
	v_fmamk_f32 v176, v176, 0x3a800000, v208
	v_mul_f32_e32 v178, 0x4b800000, v176
	v_cmp_gt_f32_e32 vcc, s27, v176
	s_nop 1
	v_cndmask_b32_e32 v176, v176, v178, vcc
	v_rsq_f32_e32 v209, v176
	s_nop 0
	v_mul_f32_e32 v178, 0x45800000, v209
	v_cndmask_b32_e32 v209, v209, v178, vcc
	v_fmamk_f32 v177, v177, 0x3a800000, v208
	v_mul_f32_e32 v178, 0x4b800000, v177
	v_cmp_gt_f32_e32 vcc, s27, v177
	s_nop 1
	v_cndmask_b32_e32 v177, v177, v178, vcc
	v_rsq_f32_e32 v210, v177
	s_nop 0
	v_mul_f32_e32 v178, 0x45800000, v210
	v_cndmask_b32_e32 v210, v210, v178, vcc
	s_add_u32 s10, s10, 0x1000
	s_addc_u32 s11, s11, 0
	v_mul_f32_e32 v48, v48, v209
	v_mul_f32_e32 v48, v0, v48
	v_fma_f32 v48, v144, v48, v160
	v_mul_f32_e32 v49, v49, v209
	v_mul_f32_e32 v49, v1, v49
	v_fma_f32 v49, v145, v49, v161
	v_mul_f32_e32 v50, v50, v209
	v_mul_f32_e32 v50, v2, v50
	v_fma_f32 v50, v146, v50, v162
	v_mul_f32_e32 v51, v51, v209
	v_mul_f32_e32 v51, v3, v51
	v_fma_f32 v51, v147, v51, v163
	v_cvt_pk_bf16_f32 v180, v48, v49
	v_cvt_pk_bf16_f32 v181, v50, v51
	global_store_dwordx2 v196, v[180:181], s[10:11]
	s_nop 0
	v_mul_f32_e32 v52, v52, v209
	v_mul_f32_e32 v52, v4, v52
	v_fma_f32 v52, v148, v52, v164
	v_mul_f32_e32 v53, v53, v209
	v_mul_f32_e32 v53, v5, v53
	v_fma_f32 v53, v149, v53, v165
	v_mul_f32_e32 v54, v54, v209
	v_mul_f32_e32 v54, v6, v54
	v_fma_f32 v54, v150, v54, v166
	v_mul_f32_e32 v55, v55, v209
	v_mul_f32_e32 v55, v7, v55
	v_fma_f32 v55, v151, v55, v167
	v_cvt_pk_bf16_f32 v180, v52, v53
	v_cvt_pk_bf16_f32 v181, v54, v55
	global_store_dwordx2 v196, v[180:181], s[10:11] offset:512
	s_nop 0
	v_mul_f32_e32 v56, v56, v209
	v_mul_f32_e32 v56, v8, v56
	v_fma_f32 v56, v152, v56, v168
	v_mul_f32_e32 v57, v57, v209
	v_mul_f32_e32 v57, v9, v57
	v_fma_f32 v57, v153, v57, v169
	v_mul_f32_e32 v58, v58, v209
	v_mul_f32_e32 v58, v10, v58
	v_fma_f32 v58, v154, v58, v170
	v_mul_f32_e32 v59, v59, v209
	v_mul_f32_e32 v59, v11, v59
	v_fma_f32 v59, v155, v59, v171
	v_cvt_pk_bf16_f32 v180, v56, v57
	v_cvt_pk_bf16_f32 v181, v58, v59
	global_store_dwordx2 v196, v[180:181], s[10:11] offset:1024
	s_nop 0
	v_mul_f32_e32 v60, v60, v209
	v_mul_f32_e32 v60, v12, v60
	v_fma_f32 v60, v156, v60, v172
	v_mul_f32_e32 v61, v61, v209
	v_mul_f32_e32 v61, v13, v61
	v_fma_f32 v61, v157, v61, v173
	v_mul_f32_e32 v62, v62, v209
	v_mul_f32_e32 v62, v14, v62
	v_fma_f32 v62, v158, v62, v174
	v_mul_f32_e32 v63, v63, v209
	v_mul_f32_e32 v63, v15, v63
	v_fma_f32 v63, v159, v63, v175
	v_cvt_pk_bf16_f32 v180, v60, v61
	v_cvt_pk_bf16_f32 v181, v62, v63
	global_store_dwordx2 v196, v[180:181], s[10:11] offset:1536
	s_nop 0
	v_mul_f32_e32 v64, v64, v210
	v_mul_f32_e32 v64, v0, v64
	v_fma_f32 v64, v144, v64, v160
	v_mul_f32_e32 v65, v65, v210
	v_mul_f32_e32 v65, v1, v65
	v_fma_f32 v65, v145, v65, v161
	v_mul_f32_e32 v66, v66, v210
	v_mul_f32_e32 v66, v2, v66
	v_fma_f32 v66, v146, v66, v162
	v_mul_f32_e32 v67, v67, v210
	v_mul_f32_e32 v67, v3, v67
	v_fma_f32 v67, v147, v67, v163
	v_cvt_pk_bf16_f32 v180, v64, v65
	v_cvt_pk_bf16_f32 v181, v66, v67
	global_store_dwordx2 v196, v[180:181], s[10:11] offset:2048
	s_nop 0
	v_mul_f32_e32 v68, v68, v210
	v_mul_f32_e32 v68, v4, v68
	v_fma_f32 v68, v148, v68, v164
	v_mul_f32_e32 v69, v69, v210
	v_mul_f32_e32 v69, v5, v69
	v_fma_f32 v69, v149, v69, v165
	v_mul_f32_e32 v70, v70, v210
	v_mul_f32_e32 v70, v6, v70
	v_fma_f32 v70, v150, v70, v166
	v_mul_f32_e32 v71, v71, v210
	v_mul_f32_e32 v71, v7, v71
	v_fma_f32 v71, v151, v71, v167
	v_cvt_pk_bf16_f32 v180, v68, v69
	v_cvt_pk_bf16_f32 v181, v70, v71
	global_store_dwordx2 v196, v[180:181], s[10:11] offset:2560
	s_nop 0
	v_mul_f32_e32 v72, v72, v210
	v_mul_f32_e32 v72, v8, v72
	v_fma_f32 v72, v152, v72, v168
	v_mul_f32_e32 v73, v73, v210
	v_mul_f32_e32 v73, v9, v73
	v_fma_f32 v73, v153, v73, v169
	v_mul_f32_e32 v74, v74, v210
	v_mul_f32_e32 v74, v10, v74
	v_fma_f32 v74, v154, v74, v170
	v_mul_f32_e32 v75, v75, v210
	v_mul_f32_e32 v75, v11, v75
	v_fma_f32 v75, v155, v75, v171
	v_cvt_pk_bf16_f32 v180, v72, v73
	v_cvt_pk_bf16_f32 v181, v74, v75
	global_store_dwordx2 v196, v[180:181], s[10:11] offset:3072
	s_nop 0
	v_mul_f32_e32 v76, v76, v210
	v_mul_f32_e32 v76, v12, v76
	v_fma_f32 v76, v156, v76, v172
	v_mul_f32_e32 v77, v77, v210
	v_mul_f32_e32 v77, v13, v77
	v_fma_f32 v77, v157, v77, v173
	v_mul_f32_e32 v78, v78, v210
	v_mul_f32_e32 v78, v14, v78
	v_fma_f32 v78, v158, v78, v174
	v_mul_f32_e32 v79, v79, v210
	v_mul_f32_e32 v79, v15, v79
	v_fma_f32 v79, v159, v79, v175
	v_cvt_pk_bf16_f32 v180, v76, v77
	v_cvt_pk_bf16_f32 v181, v78, v79
	global_store_dwordx2 v196, v[180:181], s[10:11] offset:3584
	s_nop 0
	s_add_u32 s14, s14, 0x2000
	s_addc_u32 s15, s15, 0
	global_load_dwordx4 v[48:51], v194, s[14:15]
	global_load_dwordx4 v[52:55], v194, s[14:15] offset:1024
	global_load_dwordx4 v[56:59], v194, s[14:15] offset:2048
	global_load_dwordx4 v[60:63], v194, s[14:15] offset:3072
	global_load_dwordx4 v[64:67], v195, s[14:15]
	global_load_dwordx4 v[68:71], v195, s[14:15] offset:1024
	global_load_dwordx4 v[72:75], v195, s[14:15] offset:2048
	global_load_dwordx4 v[76:79], v195, s[14:15] offset:3072
	s_waitcnt vmcnt(48)
	v_pk_mul_f32 v[178:179], v[80:81], v[80:81]
	v_pk_fma_f32 v[178:179], v[82:83], v[82:83], v[178:179]
	v_pk_fma_f32 v[178:179], v[84:85], v[84:85], v[178:179]
	v_pk_fma_f32 v[178:179], v[86:87], v[86:87], v[178:179]
	v_pk_fma_f32 v[178:179], v[88:89], v[88:89], v[178:179]
	v_pk_fma_f32 v[178:179], v[90:91], v[90:91], v[178:179]
	v_pk_fma_f32 v[178:179], v[92:93], v[92:93], v[178:179]
	v_pk_fma_f32 v[178:179], v[94:95], v[94:95], v[178:179]
	v_pk_mul_f32 v[180:181], v[96:97], v[96:97]
	v_pk_fma_f32 v[180:181], v[98:99], v[98:99], v[180:181]
	v_pk_fma_f32 v[180:181], v[100:101], v[100:101], v[180:181]
	v_pk_fma_f32 v[180:181], v[102:103], v[102:103], v[180:181]
	v_pk_fma_f32 v[180:181], v[104:105], v[104:105], v[180:181]
	v_pk_fma_f32 v[180:181], v[106:107], v[106:107], v[180:181]
	v_pk_fma_f32 v[180:181], v[108:109], v[108:109], v[180:181]
	v_pk_fma_f32 v[180:181], v[110:111], v[110:111], v[180:181]
	v_add_f32_e32 v176, v178, v179
	v_add_f32_e32 v177, v180, v181
	v_add_f32_dpp v176, v176, v176 quad_perm:[1,0,3,2] row_mask:0xf bank_mask:0xf bound_ctrl:1
	v_add_f32_dpp v177, v177, v177 quad_perm:[1,0,3,2] row_mask:0xf bank_mask:0xf bound_ctrl:1
	s_nop 0
	v_add_f32_dpp v176, v176, v176 quad_perm:[2,3,0,1] row_mask:0xf bank_mask:0xf bound_ctrl:1
	v_add_f32_dpp v177, v177, v177 quad_perm:[2,3,0,1] row_mask:0xf bank_mask:0xf bound_ctrl:1
	s_nop 0
	v_add_f32_dpp v176, v176, v176 row_half_mirror row_mask:0xf bank_mask:0xf bound_ctrl:1
	v_add_f32_dpp v177, v177, v177 row_half_mirror row_mask:0xf bank_mask:0xf bound_ctrl:1
	s_nop 0
	v_add_f32_dpp v176, v176, v176 row_mirror row_mask:0xf bank_mask:0xf bound_ctrl:1
	v_add_f32_dpp v177, v177, v177 row_mirror row_mask:0xf bank_mask:0xf bound_ctrl:1
	s_nop 1
	v_readlane_b32 s20, v176, 0
	v_readlane_b32 s24, v177, 0
	v_readlane_b32 s21, v176, 16
	v_readlane_b32 s25, v177, 16
	v_readlane_b32 s22, v176, 32
	v_readlane_b32 s26, v177, 32
	v_readlane_b32 s23, v176, 48
	v_readlane_b32 s28, v177, 48
	s_nop 1
	v_mov_b32_e32 v176, s21
	v_mov_b32_e32 v178, s23
	v_mov_b32_e32 v177, s25
	v_mov_b32_e32 v179, s28
	v_add_f32_e32 v176, s20, v176
	v_add_f32_e32 v178, s22, v178
	v_add_f32_e32 v177, s24, v177
	v_add_f32_e32 v179, s26, v179
	v_add_f32_e32 v176, v176, v178
	v_add_f32_e32 v177, v177, v179
	v_fmamk_f32 v176, v176, 0x3a800000, v208
	v_mul_f32_e32 v178, 0x4b800000, v176
	v_cmp_gt_f32_e32 vcc, s27, v176
	s_nop 1
	v_cndmask_b32_e32 v176, v176, v178, vcc
	v_rsq_f32_e32 v209, v176
	s_nop 0
	v_mul_f32_e32 v178, 0x45800000, v209
	v_cndmask_b32_e32 v209, v209, v178, vcc
	v_fmamk_f32 v177, v177, 0x3a800000, v208
	v_mul_f32_e32 v178, 0x4b800000, v177
	v_cmp_gt_f32_e32 vcc, s27, v177
	s_nop 1
	v_cndmask_b32_e32 v177, v177, v178, vcc
	v_rsq_f32_e32 v210, v177
	s_nop 0
	v_mul_f32_e32 v178, 0x45800000, v210
	v_cndmask_b32_e32 v210, v210, v178, vcc
	s_add_u32 s10, s10, 0x1000
	s_addc_u32 s11, s11, 0
	v_mul_f32_e32 v80, v80, v209
	v_mul_f32_e32 v80, v0, v80
	v_fma_f32 v80, v144, v80, v160
	v_mul_f32_e32 v81, v81, v209
	v_mul_f32_e32 v81, v1, v81
	v_fma_f32 v81, v145, v81, v161
	v_mul_f32_e32 v82, v82, v209
	v_mul_f32_e32 v82, v2, v82
	v_fma_f32 v82, v146, v82, v162
	v_mul_f32_e32 v83, v83, v209
	v_mul_f32_e32 v83, v3, v83
	v_fma_f32 v83, v147, v83, v163
	v_cvt_pk_bf16_f32 v180, v80, v81
	v_cvt_pk_bf16_f32 v181, v82, v83
	global_store_dwordx2 v196, v[180:181], s[10:11]
	s_nop 0
	v_mul_f32_e32 v84, v84, v209
	v_mul_f32_e32 v84, v4, v84
	v_fma_f32 v84, v148, v84, v164
	v_mul_f32_e32 v85, v85, v209
	v_mul_f32_e32 v85, v5, v85
	v_fma_f32 v85, v149, v85, v165
	v_mul_f32_e32 v86, v86, v209
	v_mul_f32_e32 v86, v6, v86
	v_fma_f32 v86, v150, v86, v166
	v_mul_f32_e32 v87, v87, v209
	v_mul_f32_e32 v87, v7, v87
	v_fma_f32 v87, v151, v87, v167
	v_cvt_pk_bf16_f32 v180, v84, v85
	v_cvt_pk_bf16_f32 v181, v86, v87
	global_store_dwordx2 v196, v[180:181], s[10:11] offset:512
	s_nop 0
	v_mul_f32_e32 v88, v88, v209
	v_mul_f32_e32 v88, v8, v88
	v_fma_f32 v88, v152, v88, v168
	v_mul_f32_e32 v89, v89, v209
	v_mul_f32_e32 v89, v9, v89
	v_fma_f32 v89, v153, v89, v169
	v_mul_f32_e32 v90, v90, v209
	v_mul_f32_e32 v90, v10, v90
	v_fma_f32 v90, v154, v90, v170
	v_mul_f32_e32 v91, v91, v209
	v_mul_f32_e32 v91, v11, v91
	v_fma_f32 v91, v155, v91, v171
	v_cvt_pk_bf16_f32 v180, v88, v89
	v_cvt_pk_bf16_f32 v181, v90, v91
	global_store_dwordx2 v196, v[180:181], s[10:11] offset:1024
	s_nop 0
	v_mul_f32_e32 v92, v92, v209
	v_mul_f32_e32 v92, v12, v92
	v_fma_f32 v92, v156, v92, v172
	v_mul_f32_e32 v93, v93, v209
	v_mul_f32_e32 v93, v13, v93
	v_fma_f32 v93, v157, v93, v173
	v_mul_f32_e32 v94, v94, v209
	v_mul_f32_e32 v94, v14, v94
	v_fma_f32 v94, v158, v94, v174
	v_mul_f32_e32 v95, v95, v209
	v_mul_f32_e32 v95, v15, v95
	v_fma_f32 v95, v159, v95, v175
	v_cvt_pk_bf16_f32 v180, v92, v93
	v_cvt_pk_bf16_f32 v181, v94, v95
	global_store_dwordx2 v196, v[180:181], s[10:11] offset:1536
	s_nop 0
	v_mul_f32_e32 v96, v96, v210
	v_mul_f32_e32 v96, v0, v96
	v_fma_f32 v96, v144, v96, v160
	v_mul_f32_e32 v97, v97, v210
	v_mul_f32_e32 v97, v1, v97
	v_fma_f32 v97, v145, v97, v161
	v_mul_f32_e32 v98, v98, v210
	v_mul_f32_e32 v98, v2, v98
	v_fma_f32 v98, v146, v98, v162
	v_mul_f32_e32 v99, v99, v210
	v_mul_f32_e32 v99, v3, v99
	v_fma_f32 v99, v147, v99, v163
	v_cvt_pk_bf16_f32 v180, v96, v97
	v_cvt_pk_bf16_f32 v181, v98, v99
	global_store_dwordx2 v196, v[180:181], s[10:11] offset:2048
	s_nop 0
	v_mul_f32_e32 v100, v100, v210
	v_mul_f32_e32 v100, v4, v100
	v_fma_f32 v100, v148, v100, v164
	v_mul_f32_e32 v101, v101, v210
	v_mul_f32_e32 v101, v5, v101
	v_fma_f32 v101, v149, v101, v165
	v_mul_f32_e32 v102, v102, v210
	v_mul_f32_e32 v102, v6, v102
	v_fma_f32 v102, v150, v102, v166
	v_mul_f32_e32 v103, v103, v210
	v_mul_f32_e32 v103, v7, v103
	v_fma_f32 v103, v151, v103, v167
	v_cvt_pk_bf16_f32 v180, v100, v101
	v_cvt_pk_bf16_f32 v181, v102, v103
	global_store_dwordx2 v196, v[180:181], s[10:11] offset:2560
	s_nop 0
	v_mul_f32_e32 v104, v104, v210
	v_mul_f32_e32 v104, v8, v104
	v_fma_f32 v104, v152, v104, v168
	v_mul_f32_e32 v105, v105, v210
	v_mul_f32_e32 v105, v9, v105
	v_fma_f32 v105, v153, v105, v169
	v_mul_f32_e32 v106, v106, v210
	v_mul_f32_e32 v106, v10, v106
	v_fma_f32 v106, v154, v106, v170
	v_mul_f32_e32 v107, v107, v210
	v_mul_f32_e32 v107, v11, v107
	v_fma_f32 v107, v155, v107, v171
	v_cvt_pk_bf16_f32 v180, v104, v105
	v_cvt_pk_bf16_f32 v181, v106, v107
	global_store_dwordx2 v196, v[180:181], s[10:11] offset:3072
	s_nop 0
	v_mul_f32_e32 v108, v108, v210
	v_mul_f32_e32 v108, v12, v108
	v_fma_f32 v108, v156, v108, v172
	v_mul_f32_e32 v109, v109, v210
	v_mul_f32_e32 v109, v13, v109
	v_fma_f32 v109, v157, v109, v173
	v_mul_f32_e32 v110, v110, v210
	v_mul_f32_e32 v110, v14, v110
	v_fma_f32 v110, v158, v110, v174
	v_mul_f32_e32 v111, v111, v210
	v_mul_f32_e32 v111, v15, v111
	v_fma_f32 v111, v159, v111, v175
	v_cvt_pk_bf16_f32 v180, v108, v109
	v_cvt_pk_bf16_f32 v181, v110, v111
	global_store_dwordx2 v196, v[180:181], s[10:11] offset:3584
	s_nop 0
	s_add_u32 s14, s14, 0x2000
	s_addc_u32 s15, s15, 0
	global_load_dwordx4 v[80:83], v194, s[14:15]
	global_load_dwordx4 v[84:87], v194, s[14:15] offset:1024
	global_load_dwordx4 v[88:91], v194, s[14:15] offset:2048
	global_load_dwordx4 v[92:95], v194, s[14:15] offset:3072
	global_load_dwordx4 v[96:99], v195, s[14:15]
	global_load_dwordx4 v[100:103], v195, s[14:15] offset:1024
	global_load_dwordx4 v[104:107], v195, s[14:15] offset:2048
	global_load_dwordx4 v[108:111], v195, s[14:15] offset:3072
	s_waitcnt vmcnt(48)
	v_pk_mul_f32 v[178:179], v[112:113], v[112:113]
	v_pk_fma_f32 v[178:179], v[114:115], v[114:115], v[178:179]
	v_pk_fma_f32 v[178:179], v[116:117], v[116:117], v[178:179]
	v_pk_fma_f32 v[178:179], v[118:119], v[118:119], v[178:179]
	v_pk_fma_f32 v[178:179], v[120:121], v[120:121], v[178:179]
	v_pk_fma_f32 v[178:179], v[122:123], v[122:123], v[178:179]
	v_pk_fma_f32 v[178:179], v[124:125], v[124:125], v[178:179]
	v_pk_fma_f32 v[178:179], v[126:127], v[126:127], v[178:179]
	v_pk_mul_f32 v[180:181], v[128:129], v[128:129]
	v_pk_fma_f32 v[180:181], v[130:131], v[130:131], v[180:181]
	v_pk_fma_f32 v[180:181], v[132:133], v[132:133], v[180:181]
	v_pk_fma_f32 v[180:181], v[134:135], v[134:135], v[180:181]
	v_pk_fma_f32 v[180:181], v[136:137], v[136:137], v[180:181]
	v_pk_fma_f32 v[180:181], v[138:139], v[138:139], v[180:181]
	v_pk_fma_f32 v[180:181], v[140:141], v[140:141], v[180:181]
	v_pk_fma_f32 v[180:181], v[142:143], v[142:143], v[180:181]
	v_add_f32_e32 v176, v178, v179
	v_add_f32_e32 v177, v180, v181
	v_add_f32_dpp v176, v176, v176 quad_perm:[1,0,3,2] row_mask:0xf bank_mask:0xf bound_ctrl:1
	v_add_f32_dpp v177, v177, v177 quad_perm:[1,0,3,2] row_mask:0xf bank_mask:0xf bound_ctrl:1
	s_nop 0
	v_add_f32_dpp v176, v176, v176 quad_perm:[2,3,0,1] row_mask:0xf bank_mask:0xf bound_ctrl:1
	v_add_f32_dpp v177, v177, v177 quad_perm:[2,3,0,1] row_mask:0xf bank_mask:0xf bound_ctrl:1
	s_nop 0
	v_add_f32_dpp v176, v176, v176 row_half_mirror row_mask:0xf bank_mask:0xf bound_ctrl:1
	v_add_f32_dpp v177, v177, v177 row_half_mirror row_mask:0xf bank_mask:0xf bound_ctrl:1
	s_nop 0
	v_add_f32_dpp v176, v176, v176 row_mirror row_mask:0xf bank_mask:0xf bound_ctrl:1
	v_add_f32_dpp v177, v177, v177 row_mirror row_mask:0xf bank_mask:0xf bound_ctrl:1
	s_nop 1
	v_readlane_b32 s20, v176, 0
	v_readlane_b32 s24, v177, 0
	v_readlane_b32 s21, v176, 16
	v_readlane_b32 s25, v177, 16
	v_readlane_b32 s22, v176, 32
	v_readlane_b32 s26, v177, 32
	v_readlane_b32 s23, v176, 48
	v_readlane_b32 s28, v177, 48
	s_nop 1
	v_mov_b32_e32 v176, s21
	v_mov_b32_e32 v178, s23
	v_mov_b32_e32 v177, s25
	v_mov_b32_e32 v179, s28
	v_add_f32_e32 v176, s20, v176
	v_add_f32_e32 v178, s22, v178
	v_add_f32_e32 v177, s24, v177
	v_add_f32_e32 v179, s26, v179
	v_add_f32_e32 v176, v176, v178
	v_add_f32_e32 v177, v177, v179
	v_fmamk_f32 v176, v176, 0x3a800000, v208
	v_mul_f32_e32 v178, 0x4b800000, v176
	v_cmp_gt_f32_e32 vcc, s27, v176
	s_nop 1
	v_cndmask_b32_e32 v176, v176, v178, vcc
	v_rsq_f32_e32 v209, v176
	s_nop 0
	v_mul_f32_e32 v178, 0x45800000, v209
	v_cndmask_b32_e32 v209, v209, v178, vcc
	v_fmamk_f32 v177, v177, 0x3a800000, v208
	v_mul_f32_e32 v178, 0x4b800000, v177
	v_cmp_gt_f32_e32 vcc, s27, v177
	s_nop 1
	v_cndmask_b32_e32 v177, v177, v178, vcc
	v_rsq_f32_e32 v210, v177
	s_nop 0
	v_mul_f32_e32 v178, 0x45800000, v210
	v_cndmask_b32_e32 v210, v210, v178, vcc
	s_add_u32 s10, s10, 0x1000
	s_addc_u32 s11, s11, 0
	v_mul_f32_e32 v112, v112, v209
	v_mul_f32_e32 v112, v0, v112
	v_fma_f32 v112, v144, v112, v160
	v_mul_f32_e32 v113, v113, v209
	v_mul_f32_e32 v113, v1, v113
	v_fma_f32 v113, v145, v113, v161
	v_mul_f32_e32 v114, v114, v209
	v_mul_f32_e32 v114, v2, v114
	v_fma_f32 v114, v146, v114, v162
	v_mul_f32_e32 v115, v115, v209
	v_mul_f32_e32 v115, v3, v115
	v_fma_f32 v115, v147, v115, v163
	v_cvt_pk_bf16_f32 v180, v112, v113
	v_cvt_pk_bf16_f32 v181, v114, v115
	global_store_dwordx2 v196, v[180:181], s[10:11]
	s_nop 0
	v_mul_f32_e32 v116, v116, v209
	v_mul_f32_e32 v116, v4, v116
	v_fma_f32 v116, v148, v116, v164
	v_mul_f32_e32 v117, v117, v209
	v_mul_f32_e32 v117, v5, v117
	v_fma_f32 v117, v149, v117, v165
	v_mul_f32_e32 v118, v118, v209
	v_mul_f32_e32 v118, v6, v118
	v_fma_f32 v118, v150, v118, v166
	v_mul_f32_e32 v119, v119, v209
	v_mul_f32_e32 v119, v7, v119
	v_fma_f32 v119, v151, v119, v167
	v_cvt_pk_bf16_f32 v180, v116, v117
	v_cvt_pk_bf16_f32 v181, v118, v119
	global_store_dwordx2 v196, v[180:181], s[10:11] offset:512
	s_nop 0
	v_mul_f32_e32 v120, v120, v209
	v_mul_f32_e32 v120, v8, v120
	v_fma_f32 v120, v152, v120, v168
	v_mul_f32_e32 v121, v121, v209
	v_mul_f32_e32 v121, v9, v121
	v_fma_f32 v121, v153, v121, v169
	v_mul_f32_e32 v122, v122, v209
	v_mul_f32_e32 v122, v10, v122
	v_fma_f32 v122, v154, v122, v170
	v_mul_f32_e32 v123, v123, v209
	v_mul_f32_e32 v123, v11, v123
	v_fma_f32 v123, v155, v123, v171
	v_cvt_pk_bf16_f32 v180, v120, v121
	v_cvt_pk_bf16_f32 v181, v122, v123
	global_store_dwordx2 v196, v[180:181], s[10:11] offset:1024
	s_nop 0
	v_mul_f32_e32 v124, v124, v209
	v_mul_f32_e32 v124, v12, v124
	v_fma_f32 v124, v156, v124, v172
	v_mul_f32_e32 v125, v125, v209
	v_mul_f32_e32 v125, v13, v125
	v_fma_f32 v125, v157, v125, v173
	v_mul_f32_e32 v126, v126, v209
	v_mul_f32_e32 v126, v14, v126
	v_fma_f32 v126, v158, v126, v174
	v_mul_f32_e32 v127, v127, v209
	v_mul_f32_e32 v127, v15, v127
	v_fma_f32 v127, v159, v127, v175
	v_cvt_pk_bf16_f32 v180, v124, v125
	v_cvt_pk_bf16_f32 v181, v126, v127
	global_store_dwordx2 v196, v[180:181], s[10:11] offset:1536
	s_nop 0
	v_mul_f32_e32 v128, v128, v210
	v_mul_f32_e32 v128, v0, v128
	v_fma_f32 v128, v144, v128, v160
	v_mul_f32_e32 v129, v129, v210
	v_mul_f32_e32 v129, v1, v129
	v_fma_f32 v129, v145, v129, v161
	v_mul_f32_e32 v130, v130, v210
	v_mul_f32_e32 v130, v2, v130
	v_fma_f32 v130, v146, v130, v162
	v_mul_f32_e32 v131, v131, v210
	v_mul_f32_e32 v131, v3, v131
	v_fma_f32 v131, v147, v131, v163
	v_cvt_pk_bf16_f32 v180, v128, v129
	v_cvt_pk_bf16_f32 v181, v130, v131
	global_store_dwordx2 v196, v[180:181], s[10:11] offset:2048
	s_nop 0
	v_mul_f32_e32 v132, v132, v210
	v_mul_f32_e32 v132, v4, v132
	v_fma_f32 v132, v148, v132, v164
	v_mul_f32_e32 v133, v133, v210
	v_mul_f32_e32 v133, v5, v133
	v_fma_f32 v133, v149, v133, v165
	v_mul_f32_e32 v134, v134, v210
	v_mul_f32_e32 v134, v6, v134
	v_fma_f32 v134, v150, v134, v166
	v_mul_f32_e32 v135, v135, v210
	v_mul_f32_e32 v135, v7, v135
	v_fma_f32 v135, v151, v135, v167
	v_cvt_pk_bf16_f32 v180, v132, v133
	v_cvt_pk_bf16_f32 v181, v134, v135
	global_store_dwordx2 v196, v[180:181], s[10:11] offset:2560
	s_nop 0
	v_mul_f32_e32 v136, v136, v210
	v_mul_f32_e32 v136, v8, v136
	v_fma_f32 v136, v152, v136, v168
	v_mul_f32_e32 v137, v137, v210
	v_mul_f32_e32 v137, v9, v137
	v_fma_f32 v137, v153, v137, v169
	v_mul_f32_e32 v138, v138, v210
	v_mul_f32_e32 v138, v10, v138
	v_fma_f32 v138, v154, v138, v170
	v_mul_f32_e32 v139, v139, v210
	v_mul_f32_e32 v139, v11, v139
	v_fma_f32 v139, v155, v139, v171
	v_cvt_pk_bf16_f32 v180, v136, v137
	v_cvt_pk_bf16_f32 v181, v138, v139
	global_store_dwordx2 v196, v[180:181], s[10:11] offset:3072
	s_nop 0
	v_mul_f32_e32 v140, v140, v210
	v_mul_f32_e32 v140, v12, v140
	v_fma_f32 v140, v156, v140, v172
	v_mul_f32_e32 v141, v141, v210
	v_mul_f32_e32 v141, v13, v141
	v_fma_f32 v141, v157, v141, v173
	v_mul_f32_e32 v142, v142, v210
	v_mul_f32_e32 v142, v14, v142
	v_fma_f32 v142, v158, v142, v174
	v_mul_f32_e32 v143, v143, v210
	v_mul_f32_e32 v143, v15, v143
	v_fma_f32 v143, v159, v143, v175
	v_cvt_pk_bf16_f32 v180, v140, v141
	v_cvt_pk_bf16_f32 v181, v142, v143
	global_store_dwordx2 v196, v[180:181], s[10:11] offset:3584
	s_nop 0
	s_add_u32 s14, s14, 0x2000
	s_addc_u32 s15, s15, 0
	global_load_dwordx4 v[112:115], v194, s[14:15]
	global_load_dwordx4 v[116:119], v194, s[14:15] offset:1024
	global_load_dwordx4 v[120:123], v194, s[14:15] offset:2048
	global_load_dwordx4 v[124:127], v194, s[14:15] offset:3072
	global_load_dwordx4 v[128:131], v195, s[14:15]
	global_load_dwordx4 v[132:135], v195, s[14:15] offset:1024
	global_load_dwordx4 v[136:139], v195, s[14:15] offset:2048
	global_load_dwordx4 v[140:143], v195, s[14:15] offset:3072
	s_waitcnt vmcnt(48)
	v_pk_mul_f32 v[178:179], v[16:17], v[16:17]
	v_pk_fma_f32 v[178:179], v[18:19], v[18:19], v[178:179]
	v_pk_fma_f32 v[178:179], v[20:21], v[20:21], v[178:179]
	v_pk_fma_f32 v[178:179], v[22:23], v[22:23], v[178:179]
	v_pk_fma_f32 v[178:179], v[24:25], v[24:25], v[178:179]
	v_pk_fma_f32 v[178:179], v[26:27], v[26:27], v[178:179]
	v_pk_fma_f32 v[178:179], v[28:29], v[28:29], v[178:179]
	v_pk_fma_f32 v[178:179], v[30:31], v[30:31], v[178:179]
	v_pk_mul_f32 v[180:181], v[32:33], v[32:33]
	v_pk_fma_f32 v[180:181], v[34:35], v[34:35], v[180:181]
	v_pk_fma_f32 v[180:181], v[36:37], v[36:37], v[180:181]
	v_pk_fma_f32 v[180:181], v[38:39], v[38:39], v[180:181]
	v_pk_fma_f32 v[180:181], v[40:41], v[40:41], v[180:181]
	v_pk_fma_f32 v[180:181], v[42:43], v[42:43], v[180:181]
	v_pk_fma_f32 v[180:181], v[44:45], v[44:45], v[180:181]
	v_pk_fma_f32 v[180:181], v[46:47], v[46:47], v[180:181]
	v_add_f32_e32 v176, v178, v179
	v_add_f32_e32 v177, v180, v181
	v_add_f32_dpp v176, v176, v176 quad_perm:[1,0,3,2] row_mask:0xf bank_mask:0xf bound_ctrl:1
	v_add_f32_dpp v177, v177, v177 quad_perm:[1,0,3,2] row_mask:0xf bank_mask:0xf bound_ctrl:1
	s_nop 0
	v_add_f32_dpp v176, v176, v176 quad_perm:[2,3,0,1] row_mask:0xf bank_mask:0xf bound_ctrl:1
	v_add_f32_dpp v177, v177, v177 quad_perm:[2,3,0,1] row_mask:0xf bank_mask:0xf bound_ctrl:1
	s_nop 0
	v_add_f32_dpp v176, v176, v176 row_half_mirror row_mask:0xf bank_mask:0xf bound_ctrl:1
	v_add_f32_dpp v177, v177, v177 row_half_mirror row_mask:0xf bank_mask:0xf bound_ctrl:1
	s_nop 0
	v_add_f32_dpp v176, v176, v176 row_mirror row_mask:0xf bank_mask:0xf bound_ctrl:1
	v_add_f32_dpp v177, v177, v177 row_mirror row_mask:0xf bank_mask:0xf bound_ctrl:1
	s_nop 1
	v_readlane_b32 s20, v176, 0
	v_readlane_b32 s24, v177, 0
	v_readlane_b32 s21, v176, 16
	v_readlane_b32 s25, v177, 16
	v_readlane_b32 s22, v176, 32
	v_readlane_b32 s26, v177, 32
	v_readlane_b32 s23, v176, 48
	v_readlane_b32 s28, v177, 48
	s_nop 1
	v_mov_b32_e32 v176, s21
	v_mov_b32_e32 v178, s23
	v_mov_b32_e32 v177, s25
	v_mov_b32_e32 v179, s28
	v_add_f32_e32 v176, s20, v176
	v_add_f32_e32 v178, s22, v178
	v_add_f32_e32 v177, s24, v177
	v_add_f32_e32 v179, s26, v179
	v_add_f32_e32 v176, v176, v178
	v_add_f32_e32 v177, v177, v179
	v_fmamk_f32 v176, v176, 0x3a800000, v208
	v_mul_f32_e32 v178, 0x4b800000, v176
	v_cmp_gt_f32_e32 vcc, s27, v176
	s_nop 1
	v_cndmask_b32_e32 v176, v176, v178, vcc
	v_rsq_f32_e32 v209, v176
	s_nop 0
	v_mul_f32_e32 v178, 0x45800000, v209
	v_cndmask_b32_e32 v209, v209, v178, vcc
	v_fmamk_f32 v177, v177, 0x3a800000, v208
	v_mul_f32_e32 v178, 0x4b800000, v177
	v_cmp_gt_f32_e32 vcc, s27, v177
	s_nop 1
	v_cndmask_b32_e32 v177, v177, v178, vcc
	v_rsq_f32_e32 v210, v177
	s_nop 0
	v_mul_f32_e32 v178, 0x45800000, v210
	v_cndmask_b32_e32 v210, v210, v178, vcc
	s_add_u32 s10, s10, 0x1000
	s_addc_u32 s11, s11, 0
	v_mul_f32_e32 v16, v16, v209
	v_mul_f32_e32 v16, v0, v16
	v_fma_f32 v16, v144, v16, v160
	v_mul_f32_e32 v17, v17, v209
	v_mul_f32_e32 v17, v1, v17
	v_fma_f32 v17, v145, v17, v161
	v_mul_f32_e32 v18, v18, v209
	v_mul_f32_e32 v18, v2, v18
	v_fma_f32 v18, v146, v18, v162
	v_mul_f32_e32 v19, v19, v209
	v_mul_f32_e32 v19, v3, v19
	v_fma_f32 v19, v147, v19, v163
	v_cvt_pk_bf16_f32 v180, v16, v17
	v_cvt_pk_bf16_f32 v181, v18, v19
	global_store_dwordx2 v196, v[180:181], s[10:11]
	s_nop 0
	v_mul_f32_e32 v20, v20, v209
	v_mul_f32_e32 v20, v4, v20
	v_fma_f32 v20, v148, v20, v164
	v_mul_f32_e32 v21, v21, v209
	v_mul_f32_e32 v21, v5, v21
	v_fma_f32 v21, v149, v21, v165
	v_mul_f32_e32 v22, v22, v209
	v_mul_f32_e32 v22, v6, v22
	v_fma_f32 v22, v150, v22, v166
	v_mul_f32_e32 v23, v23, v209
	v_mul_f32_e32 v23, v7, v23
	v_fma_f32 v23, v151, v23, v167
	v_cvt_pk_bf16_f32 v180, v20, v21
	v_cvt_pk_bf16_f32 v181, v22, v23
	global_store_dwordx2 v196, v[180:181], s[10:11] offset:512
	s_nop 0
	v_mul_f32_e32 v24, v24, v209
	v_mul_f32_e32 v24, v8, v24
	v_fma_f32 v24, v152, v24, v168
	v_mul_f32_e32 v25, v25, v209
	v_mul_f32_e32 v25, v9, v25
	v_fma_f32 v25, v153, v25, v169
	v_mul_f32_e32 v26, v26, v209
	v_mul_f32_e32 v26, v10, v26
	v_fma_f32 v26, v154, v26, v170
	v_mul_f32_e32 v27, v27, v209
	v_mul_f32_e32 v27, v11, v27
	v_fma_f32 v27, v155, v27, v171
	v_cvt_pk_bf16_f32 v180, v24, v25
	v_cvt_pk_bf16_f32 v181, v26, v27
	global_store_dwordx2 v196, v[180:181], s[10:11] offset:1024
	s_nop 0
	v_mul_f32_e32 v28, v28, v209
	v_mul_f32_e32 v28, v12, v28
	v_fma_f32 v28, v156, v28, v172
	v_mul_f32_e32 v29, v29, v209
	v_mul_f32_e32 v29, v13, v29
	v_fma_f32 v29, v157, v29, v173
	v_mul_f32_e32 v30, v30, v209
	v_mul_f32_e32 v30, v14, v30
	v_fma_f32 v30, v158, v30, v174
	v_mul_f32_e32 v31, v31, v209
	v_mul_f32_e32 v31, v15, v31
	v_fma_f32 v31, v159, v31, v175
	v_cvt_pk_bf16_f32 v180, v28, v29
	v_cvt_pk_bf16_f32 v181, v30, v31
	global_store_dwordx2 v196, v[180:181], s[10:11] offset:1536
	s_nop 0
	v_mul_f32_e32 v32, v32, v210
	v_mul_f32_e32 v32, v0, v32
	v_fma_f32 v32, v144, v32, v160
	v_mul_f32_e32 v33, v33, v210
	v_mul_f32_e32 v33, v1, v33
	v_fma_f32 v33, v145, v33, v161
	v_mul_f32_e32 v34, v34, v210
	v_mul_f32_e32 v34, v2, v34
	v_fma_f32 v34, v146, v34, v162
	v_mul_f32_e32 v35, v35, v210
	v_mul_f32_e32 v35, v3, v35
	v_fma_f32 v35, v147, v35, v163
	v_cvt_pk_bf16_f32 v180, v32, v33
	v_cvt_pk_bf16_f32 v181, v34, v35
	global_store_dwordx2 v196, v[180:181], s[10:11] offset:2048
	s_nop 0
	v_mul_f32_e32 v36, v36, v210
	v_mul_f32_e32 v36, v4, v36
	v_fma_f32 v36, v148, v36, v164
	v_mul_f32_e32 v37, v37, v210
	v_mul_f32_e32 v37, v5, v37
	v_fma_f32 v37, v149, v37, v165
	v_mul_f32_e32 v38, v38, v210
	v_mul_f32_e32 v38, v6, v38
	v_fma_f32 v38, v150, v38, v166
	v_mul_f32_e32 v39, v39, v210
	v_mul_f32_e32 v39, v7, v39
	v_fma_f32 v39, v151, v39, v167
	v_cvt_pk_bf16_f32 v180, v36, v37
	v_cvt_pk_bf16_f32 v181, v38, v39
	global_store_dwordx2 v196, v[180:181], s[10:11] offset:2560
	s_nop 0
	v_mul_f32_e32 v40, v40, v210
	v_mul_f32_e32 v40, v8, v40
	v_fma_f32 v40, v152, v40, v168
	v_mul_f32_e32 v41, v41, v210
	v_mul_f32_e32 v41, v9, v41
	v_fma_f32 v41, v153, v41, v169
	v_mul_f32_e32 v42, v42, v210
	v_mul_f32_e32 v42, v10, v42
	v_fma_f32 v42, v154, v42, v170
	v_mul_f32_e32 v43, v43, v210
	v_mul_f32_e32 v43, v11, v43
	v_fma_f32 v43, v155, v43, v171
	v_cvt_pk_bf16_f32 v180, v40, v41
	v_cvt_pk_bf16_f32 v181, v42, v43
	global_store_dwordx2 v196, v[180:181], s[10:11] offset:3072
	s_nop 0
	v_mul_f32_e32 v44, v44, v210
	v_mul_f32_e32 v44, v12, v44
	v_fma_f32 v44, v156, v44, v172
	v_mul_f32_e32 v45, v45, v210
	v_mul_f32_e32 v45, v13, v45
	v_fma_f32 v45, v157, v45, v173
	v_mul_f32_e32 v46, v46, v210
	v_mul_f32_e32 v46, v14, v46
	v_fma_f32 v46, v158, v46, v174
	v_mul_f32_e32 v47, v47, v210
	v_mul_f32_e32 v47, v15, v47
	v_fma_f32 v47, v159, v47, v175
	v_cvt_pk_bf16_f32 v180, v44, v45
	v_cvt_pk_bf16_f32 v181, v46, v47
	global_store_dwordx2 v196, v[180:181], s[10:11] offset:3584
	s_nop 0
	s_add_u32 s14, s14, 0x2000
	s_addc_u32 s15, s15, 0
	global_load_dwordx4 v[16:19], v194, s[14:15]
	global_load_dwordx4 v[20:23], v194, s[14:15] offset:1024
	global_load_dwordx4 v[24:27], v194, s[14:15] offset:2048
	global_load_dwordx4 v[28:31], v194, s[14:15] offset:3072
	global_load_dwordx4 v[32:35], v195, s[14:15]
	global_load_dwordx4 v[36:39], v195, s[14:15] offset:1024
	global_load_dwordx4 v[40:43], v195, s[14:15] offset:2048
	global_load_dwordx4 v[44:47], v195, s[14:15] offset:3072
	s_waitcnt vmcnt(48)
	v_pk_mul_f32 v[178:179], v[48:49], v[48:49]
	v_pk_fma_f32 v[178:179], v[50:51], v[50:51], v[178:179]
	v_pk_fma_f32 v[178:179], v[52:53], v[52:53], v[178:179]
	v_pk_fma_f32 v[178:179], v[54:55], v[54:55], v[178:179]
	v_pk_fma_f32 v[178:179], v[56:57], v[56:57], v[178:179]
	v_pk_fma_f32 v[178:179], v[58:59], v[58:59], v[178:179]
	v_pk_fma_f32 v[178:179], v[60:61], v[60:61], v[178:179]
	v_pk_fma_f32 v[178:179], v[62:63], v[62:63], v[178:179]
	v_pk_mul_f32 v[180:181], v[64:65], v[64:65]
	v_pk_fma_f32 v[180:181], v[66:67], v[66:67], v[180:181]
	v_pk_fma_f32 v[180:181], v[68:69], v[68:69], v[180:181]
	v_pk_fma_f32 v[180:181], v[70:71], v[70:71], v[180:181]
	v_pk_fma_f32 v[180:181], v[72:73], v[72:73], v[180:181]
	v_pk_fma_f32 v[180:181], v[74:75], v[74:75], v[180:181]
	v_pk_fma_f32 v[180:181], v[76:77], v[76:77], v[180:181]
	v_pk_fma_f32 v[180:181], v[78:79], v[78:79], v[180:181]
	v_add_f32_e32 v176, v178, v179
	v_add_f32_e32 v177, v180, v181
	v_add_f32_dpp v176, v176, v176 quad_perm:[1,0,3,2] row_mask:0xf bank_mask:0xf bound_ctrl:1
	v_add_f32_dpp v177, v177, v177 quad_perm:[1,0,3,2] row_mask:0xf bank_mask:0xf bound_ctrl:1
	s_nop 0
	v_add_f32_dpp v176, v176, v176 quad_perm:[2,3,0,1] row_mask:0xf bank_mask:0xf bound_ctrl:1
	v_add_f32_dpp v177, v177, v177 quad_perm:[2,3,0,1] row_mask:0xf bank_mask:0xf bound_ctrl:1
	s_nop 0
	v_add_f32_dpp v176, v176, v176 row_half_mirror row_mask:0xf bank_mask:0xf bound_ctrl:1
	v_add_f32_dpp v177, v177, v177 row_half_mirror row_mask:0xf bank_mask:0xf bound_ctrl:1
	s_nop 0
	v_add_f32_dpp v176, v176, v176 row_mirror row_mask:0xf bank_mask:0xf bound_ctrl:1
	v_add_f32_dpp v177, v177, v177 row_mirror row_mask:0xf bank_mask:0xf bound_ctrl:1
	s_nop 1
	v_readlane_b32 s20, v176, 0
	v_readlane_b32 s24, v177, 0
	v_readlane_b32 s21, v176, 16
	v_readlane_b32 s25, v177, 16
	v_readlane_b32 s22, v176, 32
	v_readlane_b32 s26, v177, 32
	v_readlane_b32 s23, v176, 48
	v_readlane_b32 s28, v177, 48
	s_nop 1
	v_mov_b32_e32 v176, s21
	v_mov_b32_e32 v178, s23
	v_mov_b32_e32 v177, s25
	v_mov_b32_e32 v179, s28
	v_add_f32_e32 v176, s20, v176
	v_add_f32_e32 v178, s22, v178
	v_add_f32_e32 v177, s24, v177
	v_add_f32_e32 v179, s26, v179
	v_add_f32_e32 v176, v176, v178
	v_add_f32_e32 v177, v177, v179
	v_fmamk_f32 v176, v176, 0x3a800000, v208
	v_mul_f32_e32 v178, 0x4b800000, v176
	v_cmp_gt_f32_e32 vcc, s27, v176
	s_nop 1
	v_cndmask_b32_e32 v176, v176, v178, vcc
	v_rsq_f32_e32 v209, v176
	s_nop 0
	v_mul_f32_e32 v178, 0x45800000, v209
	v_cndmask_b32_e32 v209, v209, v178, vcc
	v_fmamk_f32 v177, v177, 0x3a800000, v208
	v_mul_f32_e32 v178, 0x4b800000, v177
	v_cmp_gt_f32_e32 vcc, s27, v177
	s_nop 1
	v_cndmask_b32_e32 v177, v177, v178, vcc
	v_rsq_f32_e32 v210, v177
	s_nop 0
	v_mul_f32_e32 v178, 0x45800000, v210
	v_cndmask_b32_e32 v210, v210, v178, vcc
	s_add_u32 s10, s10, 0x1000
	s_addc_u32 s11, s11, 0
	v_mul_f32_e32 v48, v48, v209
	v_mul_f32_e32 v48, v0, v48
	v_fma_f32 v48, v144, v48, v160
	v_mul_f32_e32 v49, v49, v209
	v_mul_f32_e32 v49, v1, v49
	v_fma_f32 v49, v145, v49, v161
	v_mul_f32_e32 v50, v50, v209
	v_mul_f32_e32 v50, v2, v50
	v_fma_f32 v50, v146, v50, v162
	v_mul_f32_e32 v51, v51, v209
	v_mul_f32_e32 v51, v3, v51
	v_fma_f32 v51, v147, v51, v163
	v_cvt_pk_bf16_f32 v180, v48, v49
	v_cvt_pk_bf16_f32 v181, v50, v51
	global_store_dwordx2 v196, v[180:181], s[10:11]
	s_nop 0
	v_mul_f32_e32 v52, v52, v209
	v_mul_f32_e32 v52, v4, v52
	v_fma_f32 v52, v148, v52, v164
	v_mul_f32_e32 v53, v53, v209
	v_mul_f32_e32 v53, v5, v53
	v_fma_f32 v53, v149, v53, v165
	v_mul_f32_e32 v54, v54, v209
	v_mul_f32_e32 v54, v6, v54
	v_fma_f32 v54, v150, v54, v166
	v_mul_f32_e32 v55, v55, v209
	v_mul_f32_e32 v55, v7, v55
	v_fma_f32 v55, v151, v55, v167
	v_cvt_pk_bf16_f32 v180, v52, v53
	v_cvt_pk_bf16_f32 v181, v54, v55
	global_store_dwordx2 v196, v[180:181], s[10:11] offset:512
	s_nop 0
	v_mul_f32_e32 v56, v56, v209
	v_mul_f32_e32 v56, v8, v56
	v_fma_f32 v56, v152, v56, v168
	v_mul_f32_e32 v57, v57, v209
	v_mul_f32_e32 v57, v9, v57
	v_fma_f32 v57, v153, v57, v169
	v_mul_f32_e32 v58, v58, v209
	v_mul_f32_e32 v58, v10, v58
	v_fma_f32 v58, v154, v58, v170
	v_mul_f32_e32 v59, v59, v209
	v_mul_f32_e32 v59, v11, v59
	v_fma_f32 v59, v155, v59, v171
	v_cvt_pk_bf16_f32 v180, v56, v57
	v_cvt_pk_bf16_f32 v181, v58, v59
	global_store_dwordx2 v196, v[180:181], s[10:11] offset:1024
	s_nop 0
	v_mul_f32_e32 v60, v60, v209
	v_mul_f32_e32 v60, v12, v60
	v_fma_f32 v60, v156, v60, v172
	v_mul_f32_e32 v61, v61, v209
	v_mul_f32_e32 v61, v13, v61
	v_fma_f32 v61, v157, v61, v173
	v_mul_f32_e32 v62, v62, v209
	v_mul_f32_e32 v62, v14, v62
	v_fma_f32 v62, v158, v62, v174
	v_mul_f32_e32 v63, v63, v209
	v_mul_f32_e32 v63, v15, v63
	v_fma_f32 v63, v159, v63, v175
	v_cvt_pk_bf16_f32 v180, v60, v61
	v_cvt_pk_bf16_f32 v181, v62, v63
	global_store_dwordx2 v196, v[180:181], s[10:11] offset:1536
	s_nop 0
	v_mul_f32_e32 v64, v64, v210
	v_mul_f32_e32 v64, v0, v64
	v_fma_f32 v64, v144, v64, v160
	v_mul_f32_e32 v65, v65, v210
	v_mul_f32_e32 v65, v1, v65
	v_fma_f32 v65, v145, v65, v161
	v_mul_f32_e32 v66, v66, v210
	v_mul_f32_e32 v66, v2, v66
	v_fma_f32 v66, v146, v66, v162
	v_mul_f32_e32 v67, v67, v210
	v_mul_f32_e32 v67, v3, v67
	v_fma_f32 v67, v147, v67, v163
	v_cvt_pk_bf16_f32 v180, v64, v65
	v_cvt_pk_bf16_f32 v181, v66, v67
	global_store_dwordx2 v196, v[180:181], s[10:11] offset:2048
	s_nop 0
	v_mul_f32_e32 v68, v68, v210
	v_mul_f32_e32 v68, v4, v68
	v_fma_f32 v68, v148, v68, v164
	v_mul_f32_e32 v69, v69, v210
	v_mul_f32_e32 v69, v5, v69
	v_fma_f32 v69, v149, v69, v165
	v_mul_f32_e32 v70, v70, v210
	v_mul_f32_e32 v70, v6, v70
	v_fma_f32 v70, v150, v70, v166
	v_mul_f32_e32 v71, v71, v210
	v_mul_f32_e32 v71, v7, v71
	v_fma_f32 v71, v151, v71, v167
	v_cvt_pk_bf16_f32 v180, v68, v69
	v_cvt_pk_bf16_f32 v181, v70, v71
	global_store_dwordx2 v196, v[180:181], s[10:11] offset:2560
	s_nop 0
	v_mul_f32_e32 v72, v72, v210
	v_mul_f32_e32 v72, v8, v72
	v_fma_f32 v72, v152, v72, v168
	v_mul_f32_e32 v73, v73, v210
	v_mul_f32_e32 v73, v9, v73
	v_fma_f32 v73, v153, v73, v169
	v_mul_f32_e32 v74, v74, v210
	v_mul_f32_e32 v74, v10, v74
	v_fma_f32 v74, v154, v74, v170
	v_mul_f32_e32 v75, v75, v210
	v_mul_f32_e32 v75, v11, v75
	v_fma_f32 v75, v155, v75, v171
	v_cvt_pk_bf16_f32 v180, v72, v73
	v_cvt_pk_bf16_f32 v181, v74, v75
	global_store_dwordx2 v196, v[180:181], s[10:11] offset:3072
	s_nop 0
	v_mul_f32_e32 v76, v76, v210
	v_mul_f32_e32 v76, v12, v76
	v_fma_f32 v76, v156, v76, v172
	v_mul_f32_e32 v77, v77, v210
	v_mul_f32_e32 v77, v13, v77
	v_fma_f32 v77, v157, v77, v173
	v_mul_f32_e32 v78, v78, v210
	v_mul_f32_e32 v78, v14, v78
	v_fma_f32 v78, v158, v78, v174
	v_mul_f32_e32 v79, v79, v210
	v_mul_f32_e32 v79, v15, v79
	v_fma_f32 v79, v159, v79, v175
	v_cvt_pk_bf16_f32 v180, v76, v77
	v_cvt_pk_bf16_f32 v181, v78, v79
	global_store_dwordx2 v196, v[180:181], s[10:11] offset:3584
	s_nop 0
	s_add_u32 s14, s14, 0x2000
	s_addc_u32 s15, s15, 0
	global_load_dwordx4 v[48:51], v194, s[14:15]
	global_load_dwordx4 v[52:55], v194, s[14:15] offset:1024
	global_load_dwordx4 v[56:59], v194, s[14:15] offset:2048
	global_load_dwordx4 v[60:63], v194, s[14:15] offset:3072
	global_load_dwordx4 v[64:67], v195, s[14:15]
	global_load_dwordx4 v[68:71], v195, s[14:15] offset:1024
	global_load_dwordx4 v[72:75], v195, s[14:15] offset:2048
	global_load_dwordx4 v[76:79], v195, s[14:15] offset:3072
	s_waitcnt vmcnt(48)
	v_pk_mul_f32 v[178:179], v[80:81], v[80:81]
	v_pk_fma_f32 v[178:179], v[82:83], v[82:83], v[178:179]
	v_pk_fma_f32 v[178:179], v[84:85], v[84:85], v[178:179]
	v_pk_fma_f32 v[178:179], v[86:87], v[86:87], v[178:179]
	v_pk_fma_f32 v[178:179], v[88:89], v[88:89], v[178:179]
	v_pk_fma_f32 v[178:179], v[90:91], v[90:91], v[178:179]
	v_pk_fma_f32 v[178:179], v[92:93], v[92:93], v[178:179]
	v_pk_fma_f32 v[178:179], v[94:95], v[94:95], v[178:179]
	v_pk_mul_f32 v[180:181], v[96:97], v[96:97]
	v_pk_fma_f32 v[180:181], v[98:99], v[98:99], v[180:181]
	v_pk_fma_f32 v[180:181], v[100:101], v[100:101], v[180:181]
	v_pk_fma_f32 v[180:181], v[102:103], v[102:103], v[180:181]
	v_pk_fma_f32 v[180:181], v[104:105], v[104:105], v[180:181]
	v_pk_fma_f32 v[180:181], v[106:107], v[106:107], v[180:181]
	v_pk_fma_f32 v[180:181], v[108:109], v[108:109], v[180:181]
	v_pk_fma_f32 v[180:181], v[110:111], v[110:111], v[180:181]
	v_add_f32_e32 v176, v178, v179
	v_add_f32_e32 v177, v180, v181
	v_add_f32_dpp v176, v176, v176 quad_perm:[1,0,3,2] row_mask:0xf bank_mask:0xf bound_ctrl:1
	v_add_f32_dpp v177, v177, v177 quad_perm:[1,0,3,2] row_mask:0xf bank_mask:0xf bound_ctrl:1
	s_nop 0
	v_add_f32_dpp v176, v176, v176 quad_perm:[2,3,0,1] row_mask:0xf bank_mask:0xf bound_ctrl:1
	v_add_f32_dpp v177, v177, v177 quad_perm:[2,3,0,1] row_mask:0xf bank_mask:0xf bound_ctrl:1
	s_nop 0
	v_add_f32_dpp v176, v176, v176 row_half_mirror row_mask:0xf bank_mask:0xf bound_ctrl:1
	v_add_f32_dpp v177, v177, v177 row_half_mirror row_mask:0xf bank_mask:0xf bound_ctrl:1
	s_nop 0
	v_add_f32_dpp v176, v176, v176 row_mirror row_mask:0xf bank_mask:0xf bound_ctrl:1
	v_add_f32_dpp v177, v177, v177 row_mirror row_mask:0xf bank_mask:0xf bound_ctrl:1
	s_nop 1
	v_readlane_b32 s20, v176, 0
	v_readlane_b32 s24, v177, 0
	v_readlane_b32 s21, v176, 16
	v_readlane_b32 s25, v177, 16
	v_readlane_b32 s22, v176, 32
	v_readlane_b32 s26, v177, 32
	v_readlane_b32 s23, v176, 48
	v_readlane_b32 s28, v177, 48
	s_nop 1
	v_mov_b32_e32 v176, s21
	v_mov_b32_e32 v178, s23
	v_mov_b32_e32 v177, s25
	v_mov_b32_e32 v179, s28
	v_add_f32_e32 v176, s20, v176
	v_add_f32_e32 v178, s22, v178
	v_add_f32_e32 v177, s24, v177
	v_add_f32_e32 v179, s26, v179
	v_add_f32_e32 v176, v176, v178
	v_add_f32_e32 v177, v177, v179
	v_fmamk_f32 v176, v176, 0x3a800000, v208
	v_mul_f32_e32 v178, 0x4b800000, v176
	v_cmp_gt_f32_e32 vcc, s27, v176
	s_nop 1
	v_cndmask_b32_e32 v176, v176, v178, vcc
	v_rsq_f32_e32 v209, v176
	s_nop 0
	v_mul_f32_e32 v178, 0x45800000, v209
	v_cndmask_b32_e32 v209, v209, v178, vcc
	v_fmamk_f32 v177, v177, 0x3a800000, v208
	v_mul_f32_e32 v178, 0x4b800000, v177
	v_cmp_gt_f32_e32 vcc, s27, v177
	s_nop 1
	v_cndmask_b32_e32 v177, v177, v178, vcc
	v_rsq_f32_e32 v210, v177
	s_nop 0
	v_mul_f32_e32 v178, 0x45800000, v210
	v_cndmask_b32_e32 v210, v210, v178, vcc
	s_add_u32 s10, s10, 0x1000
	s_addc_u32 s11, s11, 0
	v_mul_f32_e32 v80, v80, v209
	v_mul_f32_e32 v80, v0, v80
	v_fma_f32 v80, v144, v80, v160
	v_mul_f32_e32 v81, v81, v209
	v_mul_f32_e32 v81, v1, v81
	v_fma_f32 v81, v145, v81, v161
	v_mul_f32_e32 v82, v82, v209
	v_mul_f32_e32 v82, v2, v82
	v_fma_f32 v82, v146, v82, v162
	v_mul_f32_e32 v83, v83, v209
	v_mul_f32_e32 v83, v3, v83
	v_fma_f32 v83, v147, v83, v163
	v_cvt_pk_bf16_f32 v180, v80, v81
	v_cvt_pk_bf16_f32 v181, v82, v83
	global_store_dwordx2 v196, v[180:181], s[10:11]
	s_nop 0
	v_mul_f32_e32 v84, v84, v209
	v_mul_f32_e32 v84, v4, v84
	v_fma_f32 v84, v148, v84, v164
	v_mul_f32_e32 v85, v85, v209
	v_mul_f32_e32 v85, v5, v85
	v_fma_f32 v85, v149, v85, v165
	v_mul_f32_e32 v86, v86, v209
	v_mul_f32_e32 v86, v6, v86
	v_fma_f32 v86, v150, v86, v166
	v_mul_f32_e32 v87, v87, v209
	v_mul_f32_e32 v87, v7, v87
	v_fma_f32 v87, v151, v87, v167
	v_cvt_pk_bf16_f32 v180, v84, v85
	v_cvt_pk_bf16_f32 v181, v86, v87
	global_store_dwordx2 v196, v[180:181], s[10:11] offset:512
	s_nop 0
	v_mul_f32_e32 v88, v88, v209
	v_mul_f32_e32 v88, v8, v88
	v_fma_f32 v88, v152, v88, v168
	v_mul_f32_e32 v89, v89, v209
	v_mul_f32_e32 v89, v9, v89
	v_fma_f32 v89, v153, v89, v169
	v_mul_f32_e32 v90, v90, v209
	v_mul_f32_e32 v90, v10, v90
	v_fma_f32 v90, v154, v90, v170
	v_mul_f32_e32 v91, v91, v209
	v_mul_f32_e32 v91, v11, v91
	v_fma_f32 v91, v155, v91, v171
	v_cvt_pk_bf16_f32 v180, v88, v89
	v_cvt_pk_bf16_f32 v181, v90, v91
	global_store_dwordx2 v196, v[180:181], s[10:11] offset:1024
	s_nop 0
	v_mul_f32_e32 v92, v92, v209
	v_mul_f32_e32 v92, v12, v92
	v_fma_f32 v92, v156, v92, v172
	v_mul_f32_e32 v93, v93, v209
	v_mul_f32_e32 v93, v13, v93
	v_fma_f32 v93, v157, v93, v173
	v_mul_f32_e32 v94, v94, v209
	v_mul_f32_e32 v94, v14, v94
	v_fma_f32 v94, v158, v94, v174
	v_mul_f32_e32 v95, v95, v209
	v_mul_f32_e32 v95, v15, v95
	v_fma_f32 v95, v159, v95, v175
	v_cvt_pk_bf16_f32 v180, v92, v93
	v_cvt_pk_bf16_f32 v181, v94, v95
	global_store_dwordx2 v196, v[180:181], s[10:11] offset:1536
	s_nop 0
	v_mul_f32_e32 v96, v96, v210
	v_mul_f32_e32 v96, v0, v96
	v_fma_f32 v96, v144, v96, v160
	v_mul_f32_e32 v97, v97, v210
	v_mul_f32_e32 v97, v1, v97
	v_fma_f32 v97, v145, v97, v161
	v_mul_f32_e32 v98, v98, v210
	v_mul_f32_e32 v98, v2, v98
	v_fma_f32 v98, v146, v98, v162
	v_mul_f32_e32 v99, v99, v210
	v_mul_f32_e32 v99, v3, v99
	v_fma_f32 v99, v147, v99, v163
	v_cvt_pk_bf16_f32 v180, v96, v97
	v_cvt_pk_bf16_f32 v181, v98, v99
	global_store_dwordx2 v196, v[180:181], s[10:11] offset:2048
	s_nop 0
	v_mul_f32_e32 v100, v100, v210
	v_mul_f32_e32 v100, v4, v100
	v_fma_f32 v100, v148, v100, v164
	v_mul_f32_e32 v101, v101, v210
	v_mul_f32_e32 v101, v5, v101
	v_fma_f32 v101, v149, v101, v165
	v_mul_f32_e32 v102, v102, v210
	v_mul_f32_e32 v102, v6, v102
	v_fma_f32 v102, v150, v102, v166
	v_mul_f32_e32 v103, v103, v210
	v_mul_f32_e32 v103, v7, v103
	v_fma_f32 v103, v151, v103, v167
	v_cvt_pk_bf16_f32 v180, v100, v101
	v_cvt_pk_bf16_f32 v181, v102, v103
	global_store_dwordx2 v196, v[180:181], s[10:11] offset:2560
	s_nop 0
	v_mul_f32_e32 v104, v104, v210
	v_mul_f32_e32 v104, v8, v104
	v_fma_f32 v104, v152, v104, v168
	v_mul_f32_e32 v105, v105, v210
	v_mul_f32_e32 v105, v9, v105
	v_fma_f32 v105, v153, v105, v169
	v_mul_f32_e32 v106, v106, v210
	v_mul_f32_e32 v106, v10, v106
	v_fma_f32 v106, v154, v106, v170
	v_mul_f32_e32 v107, v107, v210
	v_mul_f32_e32 v107, v11, v107
	v_fma_f32 v107, v155, v107, v171
	v_cvt_pk_bf16_f32 v180, v104, v105
	v_cvt_pk_bf16_f32 v181, v106, v107
	global_store_dwordx2 v196, v[180:181], s[10:11] offset:3072
	s_nop 0
	v_mul_f32_e32 v108, v108, v210
	v_mul_f32_e32 v108, v12, v108
	v_fma_f32 v108, v156, v108, v172
	v_mul_f32_e32 v109, v109, v210
	v_mul_f32_e32 v109, v13, v109
	v_fma_f32 v109, v157, v109, v173
	v_mul_f32_e32 v110, v110, v210
	v_mul_f32_e32 v110, v14, v110
	v_fma_f32 v110, v158, v110, v174
	v_mul_f32_e32 v111, v111, v210
	v_mul_f32_e32 v111, v15, v111
	v_fma_f32 v111, v159, v111, v175
	v_cvt_pk_bf16_f32 v180, v108, v109
	v_cvt_pk_bf16_f32 v181, v110, v111
	global_store_dwordx2 v196, v[180:181], s[10:11] offset:3584
	s_nop 0
	s_add_u32 s14, s14, 0x2000
	s_addc_u32 s15, s15, 0
	global_load_dwordx4 v[80:83], v194, s[14:15]
	global_load_dwordx4 v[84:87], v194, s[14:15] offset:1024
	global_load_dwordx4 v[88:91], v194, s[14:15] offset:2048
	global_load_dwordx4 v[92:95], v194, s[14:15] offset:3072
	global_load_dwordx4 v[96:99], v195, s[14:15]
	global_load_dwordx4 v[100:103], v195, s[14:15] offset:1024
	global_load_dwordx4 v[104:107], v195, s[14:15] offset:2048
	global_load_dwordx4 v[108:111], v195, s[14:15] offset:3072
	s_waitcnt vmcnt(48)
	v_pk_mul_f32 v[178:179], v[112:113], v[112:113]
	v_pk_fma_f32 v[178:179], v[114:115], v[114:115], v[178:179]
	v_pk_fma_f32 v[178:179], v[116:117], v[116:117], v[178:179]
	v_pk_fma_f32 v[178:179], v[118:119], v[118:119], v[178:179]
	v_pk_fma_f32 v[178:179], v[120:121], v[120:121], v[178:179]
	v_pk_fma_f32 v[178:179], v[122:123], v[122:123], v[178:179]
	v_pk_fma_f32 v[178:179], v[124:125], v[124:125], v[178:179]
	v_pk_fma_f32 v[178:179], v[126:127], v[126:127], v[178:179]
	v_pk_mul_f32 v[180:181], v[128:129], v[128:129]
	v_pk_fma_f32 v[180:181], v[130:131], v[130:131], v[180:181]
	v_pk_fma_f32 v[180:181], v[132:133], v[132:133], v[180:181]
	v_pk_fma_f32 v[180:181], v[134:135], v[134:135], v[180:181]
	v_pk_fma_f32 v[180:181], v[136:137], v[136:137], v[180:181]
	v_pk_fma_f32 v[180:181], v[138:139], v[138:139], v[180:181]
	v_pk_fma_f32 v[180:181], v[140:141], v[140:141], v[180:181]
	v_pk_fma_f32 v[180:181], v[142:143], v[142:143], v[180:181]
	v_add_f32_e32 v176, v178, v179
	v_add_f32_e32 v177, v180, v181
	v_add_f32_dpp v176, v176, v176 quad_perm:[1,0,3,2] row_mask:0xf bank_mask:0xf bound_ctrl:1
	v_add_f32_dpp v177, v177, v177 quad_perm:[1,0,3,2] row_mask:0xf bank_mask:0xf bound_ctrl:1
	s_nop 0
	v_add_f32_dpp v176, v176, v176 quad_perm:[2,3,0,1] row_mask:0xf bank_mask:0xf bound_ctrl:1
	v_add_f32_dpp v177, v177, v177 quad_perm:[2,3,0,1] row_mask:0xf bank_mask:0xf bound_ctrl:1
	s_nop 0
	v_add_f32_dpp v176, v176, v176 row_half_mirror row_mask:0xf bank_mask:0xf bound_ctrl:1
	v_add_f32_dpp v177, v177, v177 row_half_mirror row_mask:0xf bank_mask:0xf bound_ctrl:1
	s_nop 0
	v_add_f32_dpp v176, v176, v176 row_mirror row_mask:0xf bank_mask:0xf bound_ctrl:1
	v_add_f32_dpp v177, v177, v177 row_mirror row_mask:0xf bank_mask:0xf bound_ctrl:1
	s_nop 1
	v_readlane_b32 s20, v176, 0
	v_readlane_b32 s24, v177, 0
	v_readlane_b32 s21, v176, 16
	v_readlane_b32 s25, v177, 16
	v_readlane_b32 s22, v176, 32
	v_readlane_b32 s26, v177, 32
	v_readlane_b32 s23, v176, 48
	v_readlane_b32 s28, v177, 48
	s_nop 1
	v_mov_b32_e32 v176, s21
	v_mov_b32_e32 v178, s23
	v_mov_b32_e32 v177, s25
	v_mov_b32_e32 v179, s28
	v_add_f32_e32 v176, s20, v176
	v_add_f32_e32 v178, s22, v178
	v_add_f32_e32 v177, s24, v177
	v_add_f32_e32 v179, s26, v179
	v_add_f32_e32 v176, v176, v178
	v_add_f32_e32 v177, v177, v179
	v_fmamk_f32 v176, v176, 0x3a800000, v208
	v_mul_f32_e32 v178, 0x4b800000, v176
	v_cmp_gt_f32_e32 vcc, s27, v176
	s_nop 1
	v_cndmask_b32_e32 v176, v176, v178, vcc
	v_rsq_f32_e32 v209, v176
	s_nop 0
	v_mul_f32_e32 v178, 0x45800000, v209
	v_cndmask_b32_e32 v209, v209, v178, vcc
	v_fmamk_f32 v177, v177, 0x3a800000, v208
	v_mul_f32_e32 v178, 0x4b800000, v177
	v_cmp_gt_f32_e32 vcc, s27, v177
	s_nop 1
	v_cndmask_b32_e32 v177, v177, v178, vcc
	v_rsq_f32_e32 v210, v177
	s_nop 0
	v_mul_f32_e32 v178, 0x45800000, v210
	v_cndmask_b32_e32 v210, v210, v178, vcc
	s_add_u32 s10, s10, 0x1000
	s_addc_u32 s11, s11, 0
	v_mul_f32_e32 v112, v112, v209
	v_mul_f32_e32 v112, v0, v112
	v_fma_f32 v112, v144, v112, v160
	v_mul_f32_e32 v113, v113, v209
	v_mul_f32_e32 v113, v1, v113
	v_fma_f32 v113, v145, v113, v161
	v_mul_f32_e32 v114, v114, v209
	v_mul_f32_e32 v114, v2, v114
	v_fma_f32 v114, v146, v114, v162
	v_mul_f32_e32 v115, v115, v209
	v_mul_f32_e32 v115, v3, v115
	v_fma_f32 v115, v147, v115, v163
	v_cvt_pk_bf16_f32 v180, v112, v113
	v_cvt_pk_bf16_f32 v181, v114, v115
	global_store_dwordx2 v196, v[180:181], s[10:11]
	s_nop 0
	v_mul_f32_e32 v116, v116, v209
	v_mul_f32_e32 v116, v4, v116
	v_fma_f32 v116, v148, v116, v164
	v_mul_f32_e32 v117, v117, v209
	v_mul_f32_e32 v117, v5, v117
	v_fma_f32 v117, v149, v117, v165
	v_mul_f32_e32 v118, v118, v209
	v_mul_f32_e32 v118, v6, v118
	v_fma_f32 v118, v150, v118, v166
	v_mul_f32_e32 v119, v119, v209
	v_mul_f32_e32 v119, v7, v119
	v_fma_f32 v119, v151, v119, v167
	v_cvt_pk_bf16_f32 v180, v116, v117
	v_cvt_pk_bf16_f32 v181, v118, v119
	global_store_dwordx2 v196, v[180:181], s[10:11] offset:512
	s_nop 0
	v_mul_f32_e32 v120, v120, v209
	v_mul_f32_e32 v120, v8, v120
	v_fma_f32 v120, v152, v120, v168
	v_mul_f32_e32 v121, v121, v209
	v_mul_f32_e32 v121, v9, v121
	v_fma_f32 v121, v153, v121, v169
	v_mul_f32_e32 v122, v122, v209
	v_mul_f32_e32 v122, v10, v122
	v_fma_f32 v122, v154, v122, v170
	v_mul_f32_e32 v123, v123, v209
	v_mul_f32_e32 v123, v11, v123
	v_fma_f32 v123, v155, v123, v171
	v_cvt_pk_bf16_f32 v180, v120, v121
	v_cvt_pk_bf16_f32 v181, v122, v123
	global_store_dwordx2 v196, v[180:181], s[10:11] offset:1024
	s_nop 0
	v_mul_f32_e32 v124, v124, v209
	v_mul_f32_e32 v124, v12, v124
	v_fma_f32 v124, v156, v124, v172
	v_mul_f32_e32 v125, v125, v209
	v_mul_f32_e32 v125, v13, v125
	v_fma_f32 v125, v157, v125, v173
	v_mul_f32_e32 v126, v126, v209
	v_mul_f32_e32 v126, v14, v126
	v_fma_f32 v126, v158, v126, v174
	v_mul_f32_e32 v127, v127, v209
	v_mul_f32_e32 v127, v15, v127
	v_fma_f32 v127, v159, v127, v175
	v_cvt_pk_bf16_f32 v180, v124, v125
	v_cvt_pk_bf16_f32 v181, v126, v127
	global_store_dwordx2 v196, v[180:181], s[10:11] offset:1536
	s_nop 0
	v_mul_f32_e32 v128, v128, v210
	v_mul_f32_e32 v128, v0, v128
	v_fma_f32 v128, v144, v128, v160
	v_mul_f32_e32 v129, v129, v210
	v_mul_f32_e32 v129, v1, v129
	v_fma_f32 v129, v145, v129, v161
	v_mul_f32_e32 v130, v130, v210
	v_mul_f32_e32 v130, v2, v130
	v_fma_f32 v130, v146, v130, v162
	v_mul_f32_e32 v131, v131, v210
	v_mul_f32_e32 v131, v3, v131
	v_fma_f32 v131, v147, v131, v163
	v_cvt_pk_bf16_f32 v180, v128, v129
	v_cvt_pk_bf16_f32 v181, v130, v131
	global_store_dwordx2 v196, v[180:181], s[10:11] offset:2048
	s_nop 0
	v_mul_f32_e32 v132, v132, v210
	v_mul_f32_e32 v132, v4, v132
	v_fma_f32 v132, v148, v132, v164
	v_mul_f32_e32 v133, v133, v210
	v_mul_f32_e32 v133, v5, v133
	v_fma_f32 v133, v149, v133, v165
	v_mul_f32_e32 v134, v134, v210
	v_mul_f32_e32 v134, v6, v134
	v_fma_f32 v134, v150, v134, v166
	v_mul_f32_e32 v135, v135, v210
	v_mul_f32_e32 v135, v7, v135
	v_fma_f32 v135, v151, v135, v167
	v_cvt_pk_bf16_f32 v180, v132, v133
	v_cvt_pk_bf16_f32 v181, v134, v135
	global_store_dwordx2 v196, v[180:181], s[10:11] offset:2560
	s_nop 0
	v_mul_f32_e32 v136, v136, v210
	v_mul_f32_e32 v136, v8, v136
	v_fma_f32 v136, v152, v136, v168
	v_mul_f32_e32 v137, v137, v210
	v_mul_f32_e32 v137, v9, v137
	v_fma_f32 v137, v153, v137, v169
	v_mul_f32_e32 v138, v138, v210
	v_mul_f32_e32 v138, v10, v138
	v_fma_f32 v138, v154, v138, v170
	v_mul_f32_e32 v139, v139, v210
	v_mul_f32_e32 v139, v11, v139
	v_fma_f32 v139, v155, v139, v171
	v_cvt_pk_bf16_f32 v180, v136, v137
	v_cvt_pk_bf16_f32 v181, v138, v139
	global_store_dwordx2 v196, v[180:181], s[10:11] offset:3072
	s_nop 0
	v_mul_f32_e32 v140, v140, v210
	v_mul_f32_e32 v140, v12, v140
	v_fma_f32 v140, v156, v140, v172
	v_mul_f32_e32 v141, v141, v210
	v_mul_f32_e32 v141, v13, v141
	v_fma_f32 v141, v157, v141, v173
	v_mul_f32_e32 v142, v142, v210
	v_mul_f32_e32 v142, v14, v142
	v_fma_f32 v142, v158, v142, v174
	v_mul_f32_e32 v143, v143, v210
	v_mul_f32_e32 v143, v15, v143
	v_fma_f32 v143, v159, v143, v175
	v_cvt_pk_bf16_f32 v180, v140, v141
	v_cvt_pk_bf16_f32 v181, v142, v143
	global_store_dwordx2 v196, v[180:181], s[10:11] offset:3584
	s_nop 0
	s_add_u32 s14, s14, 0x2000
	s_addc_u32 s15, s15, 0
	global_load_dwordx4 v[112:115], v194, s[14:15]
	global_load_dwordx4 v[116:119], v194, s[14:15] offset:1024
	global_load_dwordx4 v[120:123], v194, s[14:15] offset:2048
	global_load_dwordx4 v[124:127], v194, s[14:15] offset:3072
	global_load_dwordx4 v[128:131], v195, s[14:15]
	global_load_dwordx4 v[132:135], v195, s[14:15] offset:1024
	global_load_dwordx4 v[136:139], v195, s[14:15] offset:2048
	global_load_dwordx4 v[140:143], v195, s[14:15] offset:3072
	s_waitcnt vmcnt(48)
	v_pk_mul_f32 v[178:179], v[16:17], v[16:17]
	v_pk_fma_f32 v[178:179], v[18:19], v[18:19], v[178:179]
	v_pk_fma_f32 v[178:179], v[20:21], v[20:21], v[178:179]
	v_pk_fma_f32 v[178:179], v[22:23], v[22:23], v[178:179]
	v_pk_fma_f32 v[178:179], v[24:25], v[24:25], v[178:179]
	v_pk_fma_f32 v[178:179], v[26:27], v[26:27], v[178:179]
	v_pk_fma_f32 v[178:179], v[28:29], v[28:29], v[178:179]
	v_pk_fma_f32 v[178:179], v[30:31], v[30:31], v[178:179]
	v_pk_mul_f32 v[180:181], v[32:33], v[32:33]
	v_pk_fma_f32 v[180:181], v[34:35], v[34:35], v[180:181]
	v_pk_fma_f32 v[180:181], v[36:37], v[36:37], v[180:181]
	v_pk_fma_f32 v[180:181], v[38:39], v[38:39], v[180:181]
	v_pk_fma_f32 v[180:181], v[40:41], v[40:41], v[180:181]
	v_pk_fma_f32 v[180:181], v[42:43], v[42:43], v[180:181]
	v_pk_fma_f32 v[180:181], v[44:45], v[44:45], v[180:181]
	v_pk_fma_f32 v[180:181], v[46:47], v[46:47], v[180:181]
	v_add_f32_e32 v176, v178, v179
	v_add_f32_e32 v177, v180, v181
	v_add_f32_dpp v176, v176, v176 quad_perm:[1,0,3,2] row_mask:0xf bank_mask:0xf bound_ctrl:1
	v_add_f32_dpp v177, v177, v177 quad_perm:[1,0,3,2] row_mask:0xf bank_mask:0xf bound_ctrl:1
	s_nop 0
	v_add_f32_dpp v176, v176, v176 quad_perm:[2,3,0,1] row_mask:0xf bank_mask:0xf bound_ctrl:1
	v_add_f32_dpp v177, v177, v177 quad_perm:[2,3,0,1] row_mask:0xf bank_mask:0xf bound_ctrl:1
	s_nop 0
	v_add_f32_dpp v176, v176, v176 row_half_mirror row_mask:0xf bank_mask:0xf bound_ctrl:1
	v_add_f32_dpp v177, v177, v177 row_half_mirror row_mask:0xf bank_mask:0xf bound_ctrl:1
	s_nop 0
	v_add_f32_dpp v176, v176, v176 row_mirror row_mask:0xf bank_mask:0xf bound_ctrl:1
	v_add_f32_dpp v177, v177, v177 row_mirror row_mask:0xf bank_mask:0xf bound_ctrl:1
	s_nop 1
	v_readlane_b32 s20, v176, 0
	v_readlane_b32 s24, v177, 0
	v_readlane_b32 s21, v176, 16
	v_readlane_b32 s25, v177, 16
	v_readlane_b32 s22, v176, 32
	v_readlane_b32 s26, v177, 32
	v_readlane_b32 s23, v176, 48
	v_readlane_b32 s28, v177, 48
	s_nop 1
	v_mov_b32_e32 v176, s21
	v_mov_b32_e32 v178, s23
	v_mov_b32_e32 v177, s25
	v_mov_b32_e32 v179, s28
	v_add_f32_e32 v176, s20, v176
	v_add_f32_e32 v178, s22, v178
	v_add_f32_e32 v177, s24, v177
	v_add_f32_e32 v179, s26, v179
	v_add_f32_e32 v176, v176, v178
	v_add_f32_e32 v177, v177, v179
	v_fmamk_f32 v176, v176, 0x3a800000, v208
	v_mul_f32_e32 v178, 0x4b800000, v176
	v_cmp_gt_f32_e32 vcc, s27, v176
	s_nop 1
	v_cndmask_b32_e32 v176, v176, v178, vcc
	v_rsq_f32_e32 v209, v176
	s_nop 0
	v_mul_f32_e32 v178, 0x45800000, v209
	v_cndmask_b32_e32 v209, v209, v178, vcc
	v_fmamk_f32 v177, v177, 0x3a800000, v208
	v_mul_f32_e32 v178, 0x4b800000, v177
	v_cmp_gt_f32_e32 vcc, s27, v177
	s_nop 1
	v_cndmask_b32_e32 v177, v177, v178, vcc
	v_rsq_f32_e32 v210, v177
	s_nop 0
	v_mul_f32_e32 v178, 0x45800000, v210
	v_cndmask_b32_e32 v210, v210, v178, vcc
	s_add_u32 s10, s10, 0x1000
	s_addc_u32 s11, s11, 0
	v_mul_f32_e32 v16, v16, v209
	v_mul_f32_e32 v16, v0, v16
	v_fma_f32 v16, v144, v16, v160
	v_mul_f32_e32 v17, v17, v209
	v_mul_f32_e32 v17, v1, v17
	v_fma_f32 v17, v145, v17, v161
	v_mul_f32_e32 v18, v18, v209
	v_mul_f32_e32 v18, v2, v18
	v_fma_f32 v18, v146, v18, v162
	v_mul_f32_e32 v19, v19, v209
	v_mul_f32_e32 v19, v3, v19
	v_fma_f32 v19, v147, v19, v163
	v_cvt_pk_bf16_f32 v180, v16, v17
	v_cvt_pk_bf16_f32 v181, v18, v19
	global_store_dwordx2 v196, v[180:181], s[10:11]
	s_nop 0
	v_mul_f32_e32 v20, v20, v209
	v_mul_f32_e32 v20, v4, v20
	v_fma_f32 v20, v148, v20, v164
	v_mul_f32_e32 v21, v21, v209
	v_mul_f32_e32 v21, v5, v21
	v_fma_f32 v21, v149, v21, v165
	v_mul_f32_e32 v22, v22, v209
	v_mul_f32_e32 v22, v6, v22
	v_fma_f32 v22, v150, v22, v166
	v_mul_f32_e32 v23, v23, v209
	v_mul_f32_e32 v23, v7, v23
	v_fma_f32 v23, v151, v23, v167
	v_cvt_pk_bf16_f32 v180, v20, v21
	v_cvt_pk_bf16_f32 v181, v22, v23
	global_store_dwordx2 v196, v[180:181], s[10:11] offset:512
	s_nop 0
	v_mul_f32_e32 v24, v24, v209
	v_mul_f32_e32 v24, v8, v24
	v_fma_f32 v24, v152, v24, v168
	v_mul_f32_e32 v25, v25, v209
	v_mul_f32_e32 v25, v9, v25
	v_fma_f32 v25, v153, v25, v169
	v_mul_f32_e32 v26, v26, v209
	v_mul_f32_e32 v26, v10, v26
	v_fma_f32 v26, v154, v26, v170
	v_mul_f32_e32 v27, v27, v209
	v_mul_f32_e32 v27, v11, v27
	v_fma_f32 v27, v155, v27, v171
	v_cvt_pk_bf16_f32 v180, v24, v25
	v_cvt_pk_bf16_f32 v181, v26, v27
	global_store_dwordx2 v196, v[180:181], s[10:11] offset:1024
	s_nop 0
	v_mul_f32_e32 v28, v28, v209
	v_mul_f32_e32 v28, v12, v28
	v_fma_f32 v28, v156, v28, v172
	v_mul_f32_e32 v29, v29, v209
	v_mul_f32_e32 v29, v13, v29
	v_fma_f32 v29, v157, v29, v173
	v_mul_f32_e32 v30, v30, v209
	v_mul_f32_e32 v30, v14, v30
	v_fma_f32 v30, v158, v30, v174
	v_mul_f32_e32 v31, v31, v209
	v_mul_f32_e32 v31, v15, v31
	v_fma_f32 v31, v159, v31, v175
	v_cvt_pk_bf16_f32 v180, v28, v29
	v_cvt_pk_bf16_f32 v181, v30, v31
	global_store_dwordx2 v196, v[180:181], s[10:11] offset:1536
	s_nop 0
	v_mul_f32_e32 v32, v32, v210
	v_mul_f32_e32 v32, v0, v32
	v_fma_f32 v32, v144, v32, v160
	v_mul_f32_e32 v33, v33, v210
	v_mul_f32_e32 v33, v1, v33
	v_fma_f32 v33, v145, v33, v161
	v_mul_f32_e32 v34, v34, v210
	v_mul_f32_e32 v34, v2, v34
	v_fma_f32 v34, v146, v34, v162
	v_mul_f32_e32 v35, v35, v210
	v_mul_f32_e32 v35, v3, v35
	v_fma_f32 v35, v147, v35, v163
	v_cvt_pk_bf16_f32 v180, v32, v33
	v_cvt_pk_bf16_f32 v181, v34, v35
	global_store_dwordx2 v196, v[180:181], s[10:11] offset:2048
	s_nop 0
	v_mul_f32_e32 v36, v36, v210
	v_mul_f32_e32 v36, v4, v36
	v_fma_f32 v36, v148, v36, v164
	v_mul_f32_e32 v37, v37, v210
	v_mul_f32_e32 v37, v5, v37
	v_fma_f32 v37, v149, v37, v165
	v_mul_f32_e32 v38, v38, v210
	v_mul_f32_e32 v38, v6, v38
	v_fma_f32 v38, v150, v38, v166
	v_mul_f32_e32 v39, v39, v210
	v_mul_f32_e32 v39, v7, v39
	v_fma_f32 v39, v151, v39, v167
	v_cvt_pk_bf16_f32 v180, v36, v37
	v_cvt_pk_bf16_f32 v181, v38, v39
	global_store_dwordx2 v196, v[180:181], s[10:11] offset:2560
	s_nop 0
	v_mul_f32_e32 v40, v40, v210
	v_mul_f32_e32 v40, v8, v40
	v_fma_f32 v40, v152, v40, v168
	v_mul_f32_e32 v41, v41, v210
	v_mul_f32_e32 v41, v9, v41
	v_fma_f32 v41, v153, v41, v169
	v_mul_f32_e32 v42, v42, v210
	v_mul_f32_e32 v42, v10, v42
	v_fma_f32 v42, v154, v42, v170
	v_mul_f32_e32 v43, v43, v210
	v_mul_f32_e32 v43, v11, v43
	v_fma_f32 v43, v155, v43, v171
	v_cvt_pk_bf16_f32 v180, v40, v41
	v_cvt_pk_bf16_f32 v181, v42, v43
	global_store_dwordx2 v196, v[180:181], s[10:11] offset:3072
	s_nop 0
	v_mul_f32_e32 v44, v44, v210
	v_mul_f32_e32 v44, v12, v44
	v_fma_f32 v44, v156, v44, v172
	v_mul_f32_e32 v45, v45, v210
	v_mul_f32_e32 v45, v13, v45
	v_fma_f32 v45, v157, v45, v173
	v_mul_f32_e32 v46, v46, v210
	v_mul_f32_e32 v46, v14, v46
	v_fma_f32 v46, v158, v46, v174
	v_mul_f32_e32 v47, v47, v210
	v_mul_f32_e32 v47, v15, v47
	v_fma_f32 v47, v159, v47, v175
	v_cvt_pk_bf16_f32 v180, v44, v45
	v_cvt_pk_bf16_f32 v181, v46, v47
	global_store_dwordx2 v196, v[180:181], s[10:11] offset:3584
	s_nop 0
	s_waitcnt vmcnt(40)
	v_pk_mul_f32 v[178:179], v[48:49], v[48:49]
	v_pk_fma_f32 v[178:179], v[50:51], v[50:51], v[178:179]
	v_pk_fma_f32 v[178:179], v[52:53], v[52:53], v[178:179]
	v_pk_fma_f32 v[178:179], v[54:55], v[54:55], v[178:179]
	v_pk_fma_f32 v[178:179], v[56:57], v[56:57], v[178:179]
	v_pk_fma_f32 v[178:179], v[58:59], v[58:59], v[178:179]
	v_pk_fma_f32 v[178:179], v[60:61], v[60:61], v[178:179]
	v_pk_fma_f32 v[178:179], v[62:63], v[62:63], v[178:179]
	v_pk_mul_f32 v[180:181], v[64:65], v[64:65]
	v_pk_fma_f32 v[180:181], v[66:67], v[66:67], v[180:181]
	v_pk_fma_f32 v[180:181], v[68:69], v[68:69], v[180:181]
	v_pk_fma_f32 v[180:181], v[70:71], v[70:71], v[180:181]
	v_pk_fma_f32 v[180:181], v[72:73], v[72:73], v[180:181]
	v_pk_fma_f32 v[180:181], v[74:75], v[74:75], v[180:181]
	v_pk_fma_f32 v[180:181], v[76:77], v[76:77], v[180:181]
	v_pk_fma_f32 v[180:181], v[78:79], v[78:79], v[180:181]
	v_add_f32_e32 v176, v178, v179
	v_add_f32_e32 v177, v180, v181
	v_add_f32_dpp v176, v176, v176 quad_perm:[1,0,3,2] row_mask:0xf bank_mask:0xf bound_ctrl:1
	v_add_f32_dpp v177, v177, v177 quad_perm:[1,0,3,2] row_mask:0xf bank_mask:0xf bound_ctrl:1
	s_nop 0
	v_add_f32_dpp v176, v176, v176 quad_perm:[2,3,0,1] row_mask:0xf bank_mask:0xf bound_ctrl:1
	v_add_f32_dpp v177, v177, v177 quad_perm:[2,3,0,1] row_mask:0xf bank_mask:0xf bound_ctrl:1
	s_nop 0
	v_add_f32_dpp v176, v176, v176 row_half_mirror row_mask:0xf bank_mask:0xf bound_ctrl:1
	v_add_f32_dpp v177, v177, v177 row_half_mirror row_mask:0xf bank_mask:0xf bound_ctrl:1
	s_nop 0
	v_add_f32_dpp v176, v176, v176 row_mirror row_mask:0xf bank_mask:0xf bound_ctrl:1
	v_add_f32_dpp v177, v177, v177 row_mirror row_mask:0xf bank_mask:0xf bound_ctrl:1
	s_nop 1
	v_readlane_b32 s20, v176, 0
	v_readlane_b32 s24, v177, 0
	v_readlane_b32 s21, v176, 16
	v_readlane_b32 s25, v177, 16
	v_readlane_b32 s22, v176, 32
	v_readlane_b32 s26, v177, 32
	v_readlane_b32 s23, v176, 48
	v_readlane_b32 s28, v177, 48
	s_nop 1
	v_mov_b32_e32 v176, s21
	v_mov_b32_e32 v178, s23
	v_mov_b32_e32 v177, s25
	v_mov_b32_e32 v179, s28
	v_add_f32_e32 v176, s20, v176
	v_add_f32_e32 v178, s22, v178
	v_add_f32_e32 v177, s24, v177
	v_add_f32_e32 v179, s26, v179
	v_add_f32_e32 v176, v176, v178
	v_add_f32_e32 v177, v177, v179
	v_fmamk_f32 v176, v176, 0x3a800000, v208
	v_mul_f32_e32 v178, 0x4b800000, v176
	v_cmp_gt_f32_e32 vcc, s27, v176
	s_nop 1
	v_cndmask_b32_e32 v176, v176, v178, vcc
	v_rsq_f32_e32 v209, v176
	s_nop 0
	v_mul_f32_e32 v178, 0x45800000, v209
	v_cndmask_b32_e32 v209, v209, v178, vcc
	v_fmamk_f32 v177, v177, 0x3a800000, v208
	v_mul_f32_e32 v178, 0x4b800000, v177
	v_cmp_gt_f32_e32 vcc, s27, v177
	s_nop 1
	v_cndmask_b32_e32 v177, v177, v178, vcc
	v_rsq_f32_e32 v210, v177
	s_nop 0
	v_mul_f32_e32 v178, 0x45800000, v210
	v_cndmask_b32_e32 v210, v210, v178, vcc
	s_add_u32 s10, s10, 0x1000
	s_addc_u32 s11, s11, 0
	v_mul_f32_e32 v48, v48, v209
	v_mul_f32_e32 v48, v0, v48
	v_fma_f32 v48, v144, v48, v160
	v_mul_f32_e32 v49, v49, v209
	v_mul_f32_e32 v49, v1, v49
	v_fma_f32 v49, v145, v49, v161
	v_mul_f32_e32 v50, v50, v209
	v_mul_f32_e32 v50, v2, v50
	v_fma_f32 v50, v146, v50, v162
	v_mul_f32_e32 v51, v51, v209
	v_mul_f32_e32 v51, v3, v51
	v_fma_f32 v51, v147, v51, v163
	v_cvt_pk_bf16_f32 v180, v48, v49
	v_cvt_pk_bf16_f32 v181, v50, v51
	global_store_dwordx2 v196, v[180:181], s[10:11]
	s_nop 0
	v_mul_f32_e32 v52, v52, v209
	v_mul_f32_e32 v52, v4, v52
	v_fma_f32 v52, v148, v52, v164
	v_mul_f32_e32 v53, v53, v209
	v_mul_f32_e32 v53, v5, v53
	v_fma_f32 v53, v149, v53, v165
	v_mul_f32_e32 v54, v54, v209
	v_mul_f32_e32 v54, v6, v54
	v_fma_f32 v54, v150, v54, v166
	v_mul_f32_e32 v55, v55, v209
	v_mul_f32_e32 v55, v7, v55
	v_fma_f32 v55, v151, v55, v167
	v_cvt_pk_bf16_f32 v180, v52, v53
	v_cvt_pk_bf16_f32 v181, v54, v55
	global_store_dwordx2 v196, v[180:181], s[10:11] offset:512
	s_nop 0
	v_mul_f32_e32 v56, v56, v209
	v_mul_f32_e32 v56, v8, v56
	v_fma_f32 v56, v152, v56, v168
	v_mul_f32_e32 v57, v57, v209
	v_mul_f32_e32 v57, v9, v57
	v_fma_f32 v57, v153, v57, v169
	v_mul_f32_e32 v58, v58, v209
	v_mul_f32_e32 v58, v10, v58
	v_fma_f32 v58, v154, v58, v170
	v_mul_f32_e32 v59, v59, v209
	v_mul_f32_e32 v59, v11, v59
	v_fma_f32 v59, v155, v59, v171
	v_cvt_pk_bf16_f32 v180, v56, v57
	v_cvt_pk_bf16_f32 v181, v58, v59
	global_store_dwordx2 v196, v[180:181], s[10:11] offset:1024
	s_nop 0
	v_mul_f32_e32 v60, v60, v209
	v_mul_f32_e32 v60, v12, v60
	v_fma_f32 v60, v156, v60, v172
	v_mul_f32_e32 v61, v61, v209
	v_mul_f32_e32 v61, v13, v61
	v_fma_f32 v61, v157, v61, v173
	v_mul_f32_e32 v62, v62, v209
	v_mul_f32_e32 v62, v14, v62
	v_fma_f32 v62, v158, v62, v174
	v_mul_f32_e32 v63, v63, v209
	v_mul_f32_e32 v63, v15, v63
	v_fma_f32 v63, v159, v63, v175
	v_cvt_pk_bf16_f32 v180, v60, v61
	v_cvt_pk_bf16_f32 v181, v62, v63
	global_store_dwordx2 v196, v[180:181], s[10:11] offset:1536
	s_nop 0
	v_mul_f32_e32 v64, v64, v210
	v_mul_f32_e32 v64, v0, v64
	v_fma_f32 v64, v144, v64, v160
	v_mul_f32_e32 v65, v65, v210
	v_mul_f32_e32 v65, v1, v65
	v_fma_f32 v65, v145, v65, v161
	v_mul_f32_e32 v66, v66, v210
	v_mul_f32_e32 v66, v2, v66
	v_fma_f32 v66, v146, v66, v162
	v_mul_f32_e32 v67, v67, v210
	v_mul_f32_e32 v67, v3, v67
	v_fma_f32 v67, v147, v67, v163
	v_cvt_pk_bf16_f32 v180, v64, v65
	v_cvt_pk_bf16_f32 v181, v66, v67
	global_store_dwordx2 v196, v[180:181], s[10:11] offset:2048
	s_nop 0
	v_mul_f32_e32 v68, v68, v210
	v_mul_f32_e32 v68, v4, v68
	v_fma_f32 v68, v148, v68, v164
	v_mul_f32_e32 v69, v69, v210
	v_mul_f32_e32 v69, v5, v69
	v_fma_f32 v69, v149, v69, v165
	v_mul_f32_e32 v70, v70, v210
	v_mul_f32_e32 v70, v6, v70
	v_fma_f32 v70, v150, v70, v166
	v_mul_f32_e32 v71, v71, v210
	v_mul_f32_e32 v71, v7, v71
	v_fma_f32 v71, v151, v71, v167
	v_cvt_pk_bf16_f32 v180, v68, v69
	v_cvt_pk_bf16_f32 v181, v70, v71
	global_store_dwordx2 v196, v[180:181], s[10:11] offset:2560
	s_nop 0
	v_mul_f32_e32 v72, v72, v210
	v_mul_f32_e32 v72, v8, v72
	v_fma_f32 v72, v152, v72, v168
	v_mul_f32_e32 v73, v73, v210
	v_mul_f32_e32 v73, v9, v73
	v_fma_f32 v73, v153, v73, v169
	v_mul_f32_e32 v74, v74, v210
	v_mul_f32_e32 v74, v10, v74
	v_fma_f32 v74, v154, v74, v170
	v_mul_f32_e32 v75, v75, v210
	v_mul_f32_e32 v75, v11, v75
	v_fma_f32 v75, v155, v75, v171
	v_cvt_pk_bf16_f32 v180, v72, v73
	v_cvt_pk_bf16_f32 v181, v74, v75
	global_store_dwordx2 v196, v[180:181], s[10:11] offset:3072
	s_nop 0
	v_mul_f32_e32 v76, v76, v210
	v_mul_f32_e32 v76, v12, v76
	v_fma_f32 v76, v156, v76, v172
	v_mul_f32_e32 v77, v77, v210
	v_mul_f32_e32 v77, v13, v77
	v_fma_f32 v77, v157, v77, v173
	v_mul_f32_e32 v78, v78, v210
	v_mul_f32_e32 v78, v14, v78
	v_fma_f32 v78, v158, v78, v174
	v_mul_f32_e32 v79, v79, v210
	v_mul_f32_e32 v79, v15, v79
	v_fma_f32 v79, v159, v79, v175
	v_cvt_pk_bf16_f32 v180, v76, v77
	v_cvt_pk_bf16_f32 v181, v78, v79
	global_store_dwordx2 v196, v[180:181], s[10:11] offset:3584
	s_nop 0
	s_waitcnt vmcnt(32)
	v_pk_mul_f32 v[178:179], v[80:81], v[80:81]
	v_pk_fma_f32 v[178:179], v[82:83], v[82:83], v[178:179]
	v_pk_fma_f32 v[178:179], v[84:85], v[84:85], v[178:179]
	v_pk_fma_f32 v[178:179], v[86:87], v[86:87], v[178:179]
	v_pk_fma_f32 v[178:179], v[88:89], v[88:89], v[178:179]
	v_pk_fma_f32 v[178:179], v[90:91], v[90:91], v[178:179]
	v_pk_fma_f32 v[178:179], v[92:93], v[92:93], v[178:179]
	v_pk_fma_f32 v[178:179], v[94:95], v[94:95], v[178:179]
	v_pk_mul_f32 v[180:181], v[96:97], v[96:97]
	v_pk_fma_f32 v[180:181], v[98:99], v[98:99], v[180:181]
	v_pk_fma_f32 v[180:181], v[100:101], v[100:101], v[180:181]
	v_pk_fma_f32 v[180:181], v[102:103], v[102:103], v[180:181]
	v_pk_fma_f32 v[180:181], v[104:105], v[104:105], v[180:181]
	v_pk_fma_f32 v[180:181], v[106:107], v[106:107], v[180:181]
	v_pk_fma_f32 v[180:181], v[108:109], v[108:109], v[180:181]
	v_pk_fma_f32 v[180:181], v[110:111], v[110:111], v[180:181]
	v_add_f32_e32 v176, v178, v179
	v_add_f32_e32 v177, v180, v181
	v_add_f32_dpp v176, v176, v176 quad_perm:[1,0,3,2] row_mask:0xf bank_mask:0xf bound_ctrl:1
	v_add_f32_dpp v177, v177, v177 quad_perm:[1,0,3,2] row_mask:0xf bank_mask:0xf bound_ctrl:1
	s_nop 0
	v_add_f32_dpp v176, v176, v176 quad_perm:[2,3,0,1] row_mask:0xf bank_mask:0xf bound_ctrl:1
	v_add_f32_dpp v177, v177, v177 quad_perm:[2,3,0,1] row_mask:0xf bank_mask:0xf bound_ctrl:1
	s_nop 0
	v_add_f32_dpp v176, v176, v176 row_half_mirror row_mask:0xf bank_mask:0xf bound_ctrl:1
	v_add_f32_dpp v177, v177, v177 row_half_mirror row_mask:0xf bank_mask:0xf bound_ctrl:1
	s_nop 0
	v_add_f32_dpp v176, v176, v176 row_mirror row_mask:0xf bank_mask:0xf bound_ctrl:1
	v_add_f32_dpp v177, v177, v177 row_mirror row_mask:0xf bank_mask:0xf bound_ctrl:1
	s_nop 1
	v_readlane_b32 s20, v176, 0
	v_readlane_b32 s24, v177, 0
	v_readlane_b32 s21, v176, 16
	v_readlane_b32 s25, v177, 16
	v_readlane_b32 s22, v176, 32
	v_readlane_b32 s26, v177, 32
	v_readlane_b32 s23, v176, 48
	v_readlane_b32 s28, v177, 48
	s_nop 1
	v_mov_b32_e32 v176, s21
	v_mov_b32_e32 v178, s23
	v_mov_b32_e32 v177, s25
	v_mov_b32_e32 v179, s28
	v_add_f32_e32 v176, s20, v176
	v_add_f32_e32 v178, s22, v178
	v_add_f32_e32 v177, s24, v177
	v_add_f32_e32 v179, s26, v179
	v_add_f32_e32 v176, v176, v178
	v_add_f32_e32 v177, v177, v179
	v_fmamk_f32 v176, v176, 0x3a800000, v208
	v_mul_f32_e32 v178, 0x4b800000, v176
	v_cmp_gt_f32_e32 vcc, s27, v176
	s_nop 1
	v_cndmask_b32_e32 v176, v176, v178, vcc
	v_rsq_f32_e32 v209, v176
	s_nop 0
	v_mul_f32_e32 v178, 0x45800000, v209
	v_cndmask_b32_e32 v209, v209, v178, vcc
	v_fmamk_f32 v177, v177, 0x3a800000, v208
	v_mul_f32_e32 v178, 0x4b800000, v177
	v_cmp_gt_f32_e32 vcc, s27, v177
	s_nop 1
	v_cndmask_b32_e32 v177, v177, v178, vcc
	v_rsq_f32_e32 v210, v177
	s_nop 0
	v_mul_f32_e32 v178, 0x45800000, v210
	v_cndmask_b32_e32 v210, v210, v178, vcc
	s_add_u32 s10, s10, 0x1000
	s_addc_u32 s11, s11, 0
	v_mul_f32_e32 v80, v80, v209
	v_mul_f32_e32 v80, v0, v80
	v_fma_f32 v80, v144, v80, v160
	v_mul_f32_e32 v81, v81, v209
	v_mul_f32_e32 v81, v1, v81
	v_fma_f32 v81, v145, v81, v161
	v_mul_f32_e32 v82, v82, v209
	v_mul_f32_e32 v82, v2, v82
	v_fma_f32 v82, v146, v82, v162
	v_mul_f32_e32 v83, v83, v209
	v_mul_f32_e32 v83, v3, v83
	v_fma_f32 v83, v147, v83, v163
	v_cvt_pk_bf16_f32 v180, v80, v81
	v_cvt_pk_bf16_f32 v181, v82, v83
	global_store_dwordx2 v196, v[180:181], s[10:11]
	s_nop 0
	v_mul_f32_e32 v84, v84, v209
	v_mul_f32_e32 v84, v4, v84
	v_fma_f32 v84, v148, v84, v164
	v_mul_f32_e32 v85, v85, v209
	v_mul_f32_e32 v85, v5, v85
	v_fma_f32 v85, v149, v85, v165
	v_mul_f32_e32 v86, v86, v209
	v_mul_f32_e32 v86, v6, v86
	v_fma_f32 v86, v150, v86, v166
	v_mul_f32_e32 v87, v87, v209
	v_mul_f32_e32 v87, v7, v87
	v_fma_f32 v87, v151, v87, v167
	v_cvt_pk_bf16_f32 v180, v84, v85
	v_cvt_pk_bf16_f32 v181, v86, v87
	global_store_dwordx2 v196, v[180:181], s[10:11] offset:512
	s_nop 0
	v_mul_f32_e32 v88, v88, v209
	v_mul_f32_e32 v88, v8, v88
	v_fma_f32 v88, v152, v88, v168
	v_mul_f32_e32 v89, v89, v209
	v_mul_f32_e32 v89, v9, v89
	v_fma_f32 v89, v153, v89, v169
	v_mul_f32_e32 v90, v90, v209
	v_mul_f32_e32 v90, v10, v90
	v_fma_f32 v90, v154, v90, v170
	v_mul_f32_e32 v91, v91, v209
	v_mul_f32_e32 v91, v11, v91
	v_fma_f32 v91, v155, v91, v171
	v_cvt_pk_bf16_f32 v180, v88, v89
	v_cvt_pk_bf16_f32 v181, v90, v91
	global_store_dwordx2 v196, v[180:181], s[10:11] offset:1024
	s_nop 0
	v_mul_f32_e32 v92, v92, v209
	v_mul_f32_e32 v92, v12, v92
	v_fma_f32 v92, v156, v92, v172
	v_mul_f32_e32 v93, v93, v209
	v_mul_f32_e32 v93, v13, v93
	v_fma_f32 v93, v157, v93, v173
	v_mul_f32_e32 v94, v94, v209
	v_mul_f32_e32 v94, v14, v94
	v_fma_f32 v94, v158, v94, v174
	v_mul_f32_e32 v95, v95, v209
	v_mul_f32_e32 v95, v15, v95
	v_fma_f32 v95, v159, v95, v175
	v_cvt_pk_bf16_f32 v180, v92, v93
	v_cvt_pk_bf16_f32 v181, v94, v95
	global_store_dwordx2 v196, v[180:181], s[10:11] offset:1536
	s_nop 0
	v_mul_f32_e32 v96, v96, v210
	v_mul_f32_e32 v96, v0, v96
	v_fma_f32 v96, v144, v96, v160
	v_mul_f32_e32 v97, v97, v210
	v_mul_f32_e32 v97, v1, v97
	v_fma_f32 v97, v145, v97, v161
	v_mul_f32_e32 v98, v98, v210
	v_mul_f32_e32 v98, v2, v98
	v_fma_f32 v98, v146, v98, v162
	v_mul_f32_e32 v99, v99, v210
	v_mul_f32_e32 v99, v3, v99
	v_fma_f32 v99, v147, v99, v163
	v_cvt_pk_bf16_f32 v180, v96, v97
	v_cvt_pk_bf16_f32 v181, v98, v99
	global_store_dwordx2 v196, v[180:181], s[10:11] offset:2048
	s_nop 0
	v_mul_f32_e32 v100, v100, v210
	v_mul_f32_e32 v100, v4, v100
	v_fma_f32 v100, v148, v100, v164
	v_mul_f32_e32 v101, v101, v210
	v_mul_f32_e32 v101, v5, v101
	v_fma_f32 v101, v149, v101, v165
	v_mul_f32_e32 v102, v102, v210
	v_mul_f32_e32 v102, v6, v102
	v_fma_f32 v102, v150, v102, v166
	v_mul_f32_e32 v103, v103, v210
	v_mul_f32_e32 v103, v7, v103
	v_fma_f32 v103, v151, v103, v167
	v_cvt_pk_bf16_f32 v180, v100, v101
	v_cvt_pk_bf16_f32 v181, v102, v103
	global_store_dwordx2 v196, v[180:181], s[10:11] offset:2560
	s_nop 0
	v_mul_f32_e32 v104, v104, v210
	v_mul_f32_e32 v104, v8, v104
	v_fma_f32 v104, v152, v104, v168
	v_mul_f32_e32 v105, v105, v210
	v_mul_f32_e32 v105, v9, v105
	v_fma_f32 v105, v153, v105, v169
	v_mul_f32_e32 v106, v106, v210
	v_mul_f32_e32 v106, v10, v106
	v_fma_f32 v106, v154, v106, v170
	v_mul_f32_e32 v107, v107, v210
	v_mul_f32_e32 v107, v11, v107
	v_fma_f32 v107, v155, v107, v171
	v_cvt_pk_bf16_f32 v180, v104, v105
	v_cvt_pk_bf16_f32 v181, v106, v107
	global_store_dwordx2 v196, v[180:181], s[10:11] offset:3072
	s_nop 0
	v_mul_f32_e32 v108, v108, v210
	v_mul_f32_e32 v108, v12, v108
	v_fma_f32 v108, v156, v108, v172
	v_mul_f32_e32 v109, v109, v210
	v_mul_f32_e32 v109, v13, v109
	v_fma_f32 v109, v157, v109, v173
	v_mul_f32_e32 v110, v110, v210
	v_mul_f32_e32 v110, v14, v110
	v_fma_f32 v110, v158, v110, v174
	v_mul_f32_e32 v111, v111, v210
	v_mul_f32_e32 v111, v15, v111
	v_fma_f32 v111, v159, v111, v175
	v_cvt_pk_bf16_f32 v180, v108, v109
	v_cvt_pk_bf16_f32 v181, v110, v111
	global_store_dwordx2 v196, v[180:181], s[10:11] offset:3584
	s_nop 0
	s_waitcnt vmcnt(24)
	v_pk_mul_f32 v[178:179], v[112:113], v[112:113]
	v_pk_fma_f32 v[178:179], v[114:115], v[114:115], v[178:179]
	v_pk_fma_f32 v[178:179], v[116:117], v[116:117], v[178:179]
	v_pk_fma_f32 v[178:179], v[118:119], v[118:119], v[178:179]
	v_pk_fma_f32 v[178:179], v[120:121], v[120:121], v[178:179]
	v_pk_fma_f32 v[178:179], v[122:123], v[122:123], v[178:179]
	v_pk_fma_f32 v[178:179], v[124:125], v[124:125], v[178:179]
	v_pk_fma_f32 v[178:179], v[126:127], v[126:127], v[178:179]
	v_pk_mul_f32 v[180:181], v[128:129], v[128:129]
	v_pk_fma_f32 v[180:181], v[130:131], v[130:131], v[180:181]
	v_pk_fma_f32 v[180:181], v[132:133], v[132:133], v[180:181]
	v_pk_fma_f32 v[180:181], v[134:135], v[134:135], v[180:181]
	v_pk_fma_f32 v[180:181], v[136:137], v[136:137], v[180:181]
	v_pk_fma_f32 v[180:181], v[138:139], v[138:139], v[180:181]
	v_pk_fma_f32 v[180:181], v[140:141], v[140:141], v[180:181]
	v_pk_fma_f32 v[180:181], v[142:143], v[142:143], v[180:181]
	v_add_f32_e32 v176, v178, v179
	v_add_f32_e32 v177, v180, v181
	v_add_f32_dpp v176, v176, v176 quad_perm:[1,0,3,2] row_mask:0xf bank_mask:0xf bound_ctrl:1
	v_add_f32_dpp v177, v177, v177 quad_perm:[1,0,3,2] row_mask:0xf bank_mask:0xf bound_ctrl:1
	s_nop 0
	v_add_f32_dpp v176, v176, v176 quad_perm:[2,3,0,1] row_mask:0xf bank_mask:0xf bound_ctrl:1
	v_add_f32_dpp v177, v177, v177 quad_perm:[2,3,0,1] row_mask:0xf bank_mask:0xf bound_ctrl:1
	s_nop 0
	v_add_f32_dpp v176, v176, v176 row_half_mirror row_mask:0xf bank_mask:0xf bound_ctrl:1
	v_add_f32_dpp v177, v177, v177 row_half_mirror row_mask:0xf bank_mask:0xf bound_ctrl:1
	s_nop 0
	v_add_f32_dpp v176, v176, v176 row_mirror row_mask:0xf bank_mask:0xf bound_ctrl:1
	v_add_f32_dpp v177, v177, v177 row_mirror row_mask:0xf bank_mask:0xf bound_ctrl:1
	s_nop 1
	v_readlane_b32 s20, v176, 0
	v_readlane_b32 s24, v177, 0
	v_readlane_b32 s21, v176, 16
	v_readlane_b32 s25, v177, 16
	v_readlane_b32 s22, v176, 32
	v_readlane_b32 s26, v177, 32
	v_readlane_b32 s23, v176, 48
	v_readlane_b32 s28, v177, 48
	s_nop 1
	v_mov_b32_e32 v176, s21
	v_mov_b32_e32 v178, s23
	v_mov_b32_e32 v177, s25
	v_mov_b32_e32 v179, s28
	v_add_f32_e32 v176, s20, v176
	v_add_f32_e32 v178, s22, v178
	v_add_f32_e32 v177, s24, v177
	v_add_f32_e32 v179, s26, v179
	v_add_f32_e32 v176, v176, v178
	v_add_f32_e32 v177, v177, v179
	v_fmamk_f32 v176, v176, 0x3a800000, v208
	v_mul_f32_e32 v178, 0x4b800000, v176
	v_cmp_gt_f32_e32 vcc, s27, v176
	s_nop 1
	v_cndmask_b32_e32 v176, v176, v178, vcc
	v_rsq_f32_e32 v209, v176
	s_nop 0
	v_mul_f32_e32 v178, 0x45800000, v209
	v_cndmask_b32_e32 v209, v209, v178, vcc
	v_fmamk_f32 v177, v177, 0x3a800000, v208
	v_mul_f32_e32 v178, 0x4b800000, v177
	v_cmp_gt_f32_e32 vcc, s27, v177
	s_nop 1
	v_cndmask_b32_e32 v177, v177, v178, vcc
	v_rsq_f32_e32 v210, v177
	s_nop 0
	v_mul_f32_e32 v178, 0x45800000, v210
	v_cndmask_b32_e32 v210, v210, v178, vcc
	s_add_u32 s10, s10, 0x1000
	s_addc_u32 s11, s11, 0
	v_mul_f32_e32 v112, v112, v209
	v_mul_f32_e32 v112, v0, v112
	v_fma_f32 v112, v144, v112, v160
	v_mul_f32_e32 v113, v113, v209
	v_mul_f32_e32 v113, v1, v113
	v_fma_f32 v113, v145, v113, v161
	v_mul_f32_e32 v114, v114, v209
	v_mul_f32_e32 v114, v2, v114
	v_fma_f32 v114, v146, v114, v162
	v_mul_f32_e32 v115, v115, v209
	v_mul_f32_e32 v115, v3, v115
	v_fma_f32 v115, v147, v115, v163
	v_cvt_pk_bf16_f32 v180, v112, v113
	v_cvt_pk_bf16_f32 v181, v114, v115
	global_store_dwordx2 v196, v[180:181], s[10:11]
	s_nop 0
	v_mul_f32_e32 v116, v116, v209
	v_mul_f32_e32 v116, v4, v116
	v_fma_f32 v116, v148, v116, v164
	v_mul_f32_e32 v117, v117, v209
	v_mul_f32_e32 v117, v5, v117
	v_fma_f32 v117, v149, v117, v165
	v_mul_f32_e32 v118, v118, v209
	v_mul_f32_e32 v118, v6, v118
	v_fma_f32 v118, v150, v118, v166
	v_mul_f32_e32 v119, v119, v209
	v_mul_f32_e32 v119, v7, v119
	v_fma_f32 v119, v151, v119, v167
	v_cvt_pk_bf16_f32 v180, v116, v117
	v_cvt_pk_bf16_f32 v181, v118, v119
	global_store_dwordx2 v196, v[180:181], s[10:11] offset:512
	s_nop 0
	v_mul_f32_e32 v120, v120, v209
	v_mul_f32_e32 v120, v8, v120
	v_fma_f32 v120, v152, v120, v168
	v_mul_f32_e32 v121, v121, v209
	v_mul_f32_e32 v121, v9, v121
	v_fma_f32 v121, v153, v121, v169
	v_mul_f32_e32 v122, v122, v209
	v_mul_f32_e32 v122, v10, v122
	v_fma_f32 v122, v154, v122, v170
	v_mul_f32_e32 v123, v123, v209
	v_mul_f32_e32 v123, v11, v123
	v_fma_f32 v123, v155, v123, v171
	v_cvt_pk_bf16_f32 v180, v120, v121
	v_cvt_pk_bf16_f32 v181, v122, v123
	global_store_dwordx2 v196, v[180:181], s[10:11] offset:1024
	s_nop 0
	v_mul_f32_e32 v124, v124, v209
	v_mul_f32_e32 v124, v12, v124
	v_fma_f32 v124, v156, v124, v172
	v_mul_f32_e32 v125, v125, v209
	v_mul_f32_e32 v125, v13, v125
	v_fma_f32 v125, v157, v125, v173
	v_mul_f32_e32 v126, v126, v209
	v_mul_f32_e32 v126, v14, v126
	v_fma_f32 v126, v158, v126, v174
	v_mul_f32_e32 v127, v127, v209
	v_mul_f32_e32 v127, v15, v127
	v_fma_f32 v127, v159, v127, v175
	v_cvt_pk_bf16_f32 v180, v124, v125
	v_cvt_pk_bf16_f32 v181, v126, v127
	global_store_dwordx2 v196, v[180:181], s[10:11] offset:1536
	s_nop 0
	v_mul_f32_e32 v128, v128, v210
	v_mul_f32_e32 v128, v0, v128
	v_fma_f32 v128, v144, v128, v160
	v_mul_f32_e32 v129, v129, v210
	v_mul_f32_e32 v129, v1, v129
	v_fma_f32 v129, v145, v129, v161
	v_mul_f32_e32 v130, v130, v210
	v_mul_f32_e32 v130, v2, v130
	v_fma_f32 v130, v146, v130, v162
	v_mul_f32_e32 v131, v131, v210
	v_mul_f32_e32 v131, v3, v131
	v_fma_f32 v131, v147, v131, v163
	v_cvt_pk_bf16_f32 v180, v128, v129
	v_cvt_pk_bf16_f32 v181, v130, v131
	global_store_dwordx2 v196, v[180:181], s[10:11] offset:2048
	s_nop 0
	v_mul_f32_e32 v132, v132, v210
	v_mul_f32_e32 v132, v4, v132
	v_fma_f32 v132, v148, v132, v164
	v_mul_f32_e32 v133, v133, v210
	v_mul_f32_e32 v133, v5, v133
	v_fma_f32 v133, v149, v133, v165
	v_mul_f32_e32 v134, v134, v210
	v_mul_f32_e32 v134, v6, v134
	v_fma_f32 v134, v150, v134, v166
	v_mul_f32_e32 v135, v135, v210
	v_mul_f32_e32 v135, v7, v135
	v_fma_f32 v135, v151, v135, v167
	v_cvt_pk_bf16_f32 v180, v132, v133
	v_cvt_pk_bf16_f32 v181, v134, v135
	global_store_dwordx2 v196, v[180:181], s[10:11] offset:2560
	s_nop 0
	v_mul_f32_e32 v136, v136, v210
	v_mul_f32_e32 v136, v8, v136
	v_fma_f32 v136, v152, v136, v168
	v_mul_f32_e32 v137, v137, v210
	v_mul_f32_e32 v137, v9, v137
	v_fma_f32 v137, v153, v137, v169
	v_mul_f32_e32 v138, v138, v210
	v_mul_f32_e32 v138, v10, v138
	v_fma_f32 v138, v154, v138, v170
	v_mul_f32_e32 v139, v139, v210
	v_mul_f32_e32 v139, v11, v139
	v_fma_f32 v139, v155, v139, v171
	v_cvt_pk_bf16_f32 v180, v136, v137
	v_cvt_pk_bf16_f32 v181, v138, v139
	global_store_dwordx2 v196, v[180:181], s[10:11] offset:3072
	s_nop 0
	v_mul_f32_e32 v140, v140, v210
	v_mul_f32_e32 v140, v12, v140
	v_fma_f32 v140, v156, v140, v172
	v_mul_f32_e32 v141, v141, v210
	v_mul_f32_e32 v141, v13, v141
	v_fma_f32 v141, v157, v141, v173
	v_mul_f32_e32 v142, v142, v210
	v_mul_f32_e32 v142, v14, v142
	v_fma_f32 v142, v158, v142, v174
	v_mul_f32_e32 v143, v143, v210
	v_mul_f32_e32 v143, v15, v143
	v_fma_f32 v143, v159, v143, v175
	v_cvt_pk_bf16_f32 v180, v140, v141
	v_cvt_pk_bf16_f32 v181, v142, v143
	global_store_dwordx2 v196, v[180:181], s[10:11] offset:3584
	s_nop 0

.Lp1x_top0:
	s_lshr_b32 s4, s2, 8
	s_mul_i32 s4, s4, 0x3000
	s_add_u32 s16, s18, s4
	s_addc_u32 s17, s19, 0
	global_load_dwordx4 v[96:99], v128, s[16:17]
	global_load_dwordx4 v[100:103], v128, s[16:17] offset:1024
	global_load_dwordx4 v[104:107], v128, s[16:17] offset:2048
	global_load_dwordx4 v[108:111], v128, s[16:17] offset:3072
	global_load_dwordx4 v[80:83], v129, s[16:17]
	global_load_dwordx4 v[84:87], v129, s[16:17] offset:1024
	global_load_dwordx4 v[88:91], v129, s[16:17] offset:2048
	global_load_dwordx4 v[92:95], v129, s[16:17] offset:3072
	s_lshl_b32 s4, s2, 4
	s_add_u32 s4, s4, s3
	s_lshl_b32 s4, s4, 11
	s_add_u32 s10, s94, s4
	s_addc_u32 s11, s95, 0
	s_add_u32 s12, s2, 0xe0
	s_cmp_lt_u32 s12, 0x800
	s_cbranch_scc0 .Lp1x_last0
	s_lshl_b32 s4, s12, 4
	s_add_u32 s4, s4, s3
	s_lshl_b32 s5, s4, 12
	s_add_u32 s14, s52, s5
	s_addc_u32 s15, s53, 0
	global_load_dwordx4 v[48:51], v128, s[14:15]
	global_load_dwordx4 v[52:55], v128, s[14:15] offset:1024
	global_load_dwordx4 v[56:59], v128, s[14:15] offset:2048
	global_load_dwordx4 v[60:63], v128, s[14:15] offset:3072
	global_load_dwordx4 v[64:67], v129, s[14:15]
	global_load_dwordx4 v[68:71], v129, s[14:15] offset:1024
	global_load_dwordx4 v[72:75], v129, s[14:15] offset:2048
	global_load_dwordx4 v[76:79], v129, s[14:15] offset:3072
	s_waitcnt vmcnt(8)
	v_pk_mul_f32 v[114:115], v[16:17], v[16:17]
	v_pk_fma_f32 v[114:115], v[18:19], v[18:19], v[114:115]
	v_pk_fma_f32 v[114:115], v[20:21], v[20:21], v[114:115]
	v_pk_fma_f32 v[114:115], v[22:23], v[22:23], v[114:115]
	v_pk_fma_f32 v[114:115], v[24:25], v[24:25], v[114:115]
	v_pk_fma_f32 v[114:115], v[26:27], v[26:27], v[114:115]
	v_pk_fma_f32 v[114:115], v[28:29], v[28:29], v[114:115]
	v_pk_fma_f32 v[114:115], v[30:31], v[30:31], v[114:115]
	v_pk_mul_f32 v[116:117], v[32:33], v[32:33]
	v_pk_fma_f32 v[116:117], v[34:35], v[34:35], v[116:117]
	v_pk_fma_f32 v[116:117], v[36:37], v[36:37], v[116:117]
	v_pk_fma_f32 v[116:117], v[38:39], v[38:39], v[116:117]
	v_pk_fma_f32 v[116:117], v[40:41], v[40:41], v[116:117]
	v_pk_fma_f32 v[116:117], v[42:43], v[42:43], v[116:117]
	v_pk_fma_f32 v[116:117], v[44:45], v[44:45], v[116:117]
	v_pk_fma_f32 v[116:117], v[46:47], v[46:47], v[116:117]
	v_add_f32_e32 v112, v114, v115
	v_add_f32_e32 v113, v116, v117
	v_add_f32_dpp v112, v112, v112 quad_perm:[1,0,3,2] row_mask:0xf bank_mask:0xf bound_ctrl:1
	v_add_f32_dpp v113, v113, v113 quad_perm:[1,0,3,2] row_mask:0xf bank_mask:0xf bound_ctrl:1
	s_nop 0
	v_add_f32_dpp v112, v112, v112 quad_perm:[2,3,0,1] row_mask:0xf bank_mask:0xf bound_ctrl:1
	v_add_f32_dpp v113, v113, v113 quad_perm:[2,3,0,1] row_mask:0xf bank_mask:0xf bound_ctrl:1
	s_nop 0
	v_add_f32_dpp v112, v112, v112 row_half_mirror row_mask:0xf bank_mask:0xf bound_ctrl:1
	v_add_f32_dpp v113, v113, v113 row_half_mirror row_mask:0xf bank_mask:0xf bound_ctrl:1
	s_nop 0
	v_add_f32_dpp v112, v112, v112 row_mirror row_mask:0xf bank_mask:0xf bound_ctrl:1
	v_add_f32_dpp v113, v113, v113 row_mirror row_mask:0xf bank_mask:0xf bound_ctrl:1
	s_nop 1
	v_readlane_b32 s20, v112, 0
	v_readlane_b32 s24, v113, 0
	v_readlane_b32 s21, v112, 16
	v_readlane_b32 s25, v113, 16
	v_readlane_b32 s22, v112, 32
	v_readlane_b32 s26, v113, 32
	v_readlane_b32 s23, v112, 48
	v_readlane_b32 s28, v113, 48
	s_nop 1
	v_mov_b32_e32 v112, s21
	v_mov_b32_e32 v114, s23
	v_mov_b32_e32 v113, s25
	v_mov_b32_e32 v115, s28
	v_add_f32_e32 v112, s20, v112
	v_add_f32_e32 v114, s22, v114
	v_add_f32_e32 v113, s24, v113
	v_add_f32_e32 v115, s26, v115
	v_add_f32_e32 v112, v112, v114
	v_add_f32_e32 v113, v113, v115
	v_fmamk_f32 v112, v112, 0x3a800000, v138
	v_mul_f32_e32 v114, 0x4b800000, v112
	v_cmp_gt_f32_e32 vcc, s29, v112
	s_nop 1
	v_cndmask_b32_e32 v112, v112, v114, vcc
	v_rsq_f32_e32 v139, v112
	s_nop 0
	v_mul_f32_e32 v114, 0x45800000, v139
	v_cndmask_b32_e32 v139, v139, v114, vcc
	v_fmamk_f32 v113, v113, 0x3a800000, v138
	v_mul_f32_e32 v114, 0x4b800000, v113
	v_cmp_gt_f32_e32 vcc, s29, v113
	s_nop 1
	v_cndmask_b32_e32 v113, v113, v114, vcc
	v_rsq_f32_e32 v140, v113
	s_nop 0
	v_mul_f32_e32 v114, 0x45800000, v140
	v_cndmask_b32_e32 v140, v140, v114, vcc
	v_add_f32_e32 v80, 1.0, v80
	v_add_f32_e32 v81, 1.0, v81
	v_add_f32_e32 v82, 1.0, v82
	v_add_f32_e32 v83, 1.0, v83
	v_add_f32_e32 v84, 1.0, v84
	v_add_f32_e32 v85, 1.0, v85
	v_add_f32_e32 v86, 1.0, v86
	v_add_f32_e32 v87, 1.0, v87
	v_add_f32_e32 v88, 1.0, v88
	v_add_f32_e32 v89, 1.0, v89
	v_add_f32_e32 v90, 1.0, v90
	v_add_f32_e32 v91, 1.0, v91
	v_add_f32_e32 v92, 1.0, v92
	v_add_f32_e32 v93, 1.0, v93
	v_add_f32_e32 v94, 1.0, v94
	v_add_f32_e32 v95, 1.0, v95
	v_mul_f32_e32 v16, v16, v139
	v_mul_f32_e32 v16, v0, v16
	v_fma_f32 v16, v80, v16, v96
	v_mul_f32_e32 v17, v17, v139
	v_mul_f32_e32 v17, v1, v17
	v_fma_f32 v17, v81, v17, v97
	v_mul_f32_e32 v18, v18, v139
	v_mul_f32_e32 v18, v2, v18
	v_fma_f32 v18, v82, v18, v98
	v_mul_f32_e32 v19, v19, v139
	v_mul_f32_e32 v19, v3, v19
	v_fma_f32 v19, v83, v19, v99
	v_cvt_pk_bf16_f32 v116, v16, v17
	v_cvt_pk_bf16_f32 v117, v18, v19
	global_store_dwordx2 v130, v[116:117], s[10:11]
	s_nop 0
	v_mul_f32_e32 v20, v20, v139
	v_mul_f32_e32 v20, v4, v20
	v_fma_f32 v20, v84, v20, v100
	v_mul_f32_e32 v21, v21, v139
	v_mul_f32_e32 v21, v5, v21
	v_fma_f32 v21, v85, v21, v101
	v_mul_f32_e32 v22, v22, v139
	v_mul_f32_e32 v22, v6, v22
	v_fma_f32 v22, v86, v22, v102
	v_mul_f32_e32 v23, v23, v139
	v_mul_f32_e32 v23, v7, v23
	v_fma_f32 v23, v87, v23, v103
	v_cvt_pk_bf16_f32 v116, v20, v21
	v_cvt_pk_bf16_f32 v117, v22, v23
	global_store_dwordx2 v130, v[116:117], s[10:11] offset:512
	s_nop 0
	v_mul_f32_e32 v24, v24, v139
	v_mul_f32_e32 v24, v8, v24
	v_fma_f32 v24, v88, v24, v104
	v_mul_f32_e32 v25, v25, v139
	v_mul_f32_e32 v25, v9, v25
	v_fma_f32 v25, v89, v25, v105
	v_mul_f32_e32 v26, v26, v139
	v_mul_f32_e32 v26, v10, v26
	v_fma_f32 v26, v90, v26, v106
	v_mul_f32_e32 v27, v27, v139
	v_mul_f32_e32 v27, v11, v27
	v_fma_f32 v27, v91, v27, v107
	v_cvt_pk_bf16_f32 v116, v24, v25
	v_cvt_pk_bf16_f32 v117, v26, v27
	global_store_dwordx2 v130, v[116:117], s[10:11] offset:1024
	s_nop 0
	v_mul_f32_e32 v28, v28, v139
	v_mul_f32_e32 v28, v12, v28
	v_fma_f32 v28, v92, v28, v108
	v_mul_f32_e32 v29, v29, v139
	v_mul_f32_e32 v29, v13, v29
	v_fma_f32 v29, v93, v29, v109
	v_mul_f32_e32 v30, v30, v139
	v_mul_f32_e32 v30, v14, v30
	v_fma_f32 v30, v94, v30, v110
	v_mul_f32_e32 v31, v31, v139
	v_mul_f32_e32 v31, v15, v31
	v_fma_f32 v31, v95, v31, v111
	v_cvt_pk_bf16_f32 v116, v28, v29
	v_cvt_pk_bf16_f32 v117, v30, v31
	global_store_dwordx2 v130, v[116:117], s[10:11] offset:1536
	s_nop 0
	v_mul_f32_e32 v32, v32, v140
	v_mul_f32_e32 v32, v0, v32
	v_fma_f32 v32, v80, v32, v96
	v_mul_f32_e32 v33, v33, v140
	v_mul_f32_e32 v33, v1, v33
	v_fma_f32 v33, v81, v33, v97
	v_mul_f32_e32 v34, v34, v140
	v_mul_f32_e32 v34, v2, v34
	v_fma_f32 v34, v82, v34, v98
	v_mul_f32_e32 v35, v35, v140
	v_mul_f32_e32 v35, v3, v35
	v_fma_f32 v35, v83, v35, v99
	v_cvt_pk_bf16_f32 v116, v32, v33
	v_cvt_pk_bf16_f32 v117, v34, v35
	global_store_dwordx2 v130, v[116:117], s[10:11] offset:2048
	s_nop 0
	v_mul_f32_e32 v36, v36, v140
	v_mul_f32_e32 v36, v4, v36
	v_fma_f32 v36, v84, v36, v100
	v_mul_f32_e32 v37, v37, v140
	v_mul_f32_e32 v37, v5, v37
	v_fma_f32 v37, v85, v37, v101
	v_mul_f32_e32 v38, v38, v140
	v_mul_f32_e32 v38, v6, v38
	v_fma_f32 v38, v86, v38, v102
	v_mul_f32_e32 v39, v39, v140
	v_mul_f32_e32 v39, v7, v39
	v_fma_f32 v39, v87, v39, v103
	v_cvt_pk_bf16_f32 v116, v36, v37
	v_cvt_pk_bf16_f32 v117, v38, v39
	global_store_dwordx2 v130, v[116:117], s[10:11] offset:2560
	s_nop 0
	v_mul_f32_e32 v40, v40, v140
	v_mul_f32_e32 v40, v8, v40
	v_fma_f32 v40, v88, v40, v104
	v_mul_f32_e32 v41, v41, v140
	v_mul_f32_e32 v41, v9, v41
	v_fma_f32 v41, v89, v41, v105
	v_mul_f32_e32 v42, v42, v140
	v_mul_f32_e32 v42, v10, v42
	v_fma_f32 v42, v90, v42, v106
	v_mul_f32_e32 v43, v43, v140
	v_mul_f32_e32 v43, v11, v43
	v_fma_f32 v43, v91, v43, v107
	v_cvt_pk_bf16_f32 v116, v40, v41
	v_cvt_pk_bf16_f32 v117, v42, v43
	global_store_dwordx2 v130, v[116:117], s[10:11] offset:3072
	s_nop 0
	v_mul_f32_e32 v44, v44, v140
	v_mul_f32_e32 v44, v12, v44
	v_fma_f32 v44, v92, v44, v108
	v_mul_f32_e32 v45, v45, v140
	v_mul_f32_e32 v45, v13, v45
	v_fma_f32 v45, v93, v45, v109
	v_mul_f32_e32 v46, v46, v140
	v_mul_f32_e32 v46, v14, v46
	v_fma_f32 v46, v94, v46, v110
	v_mul_f32_e32 v47, v47, v140
	v_mul_f32_e32 v47, v15, v47
	v_fma_f32 v47, v95, v47, v111
	v_cvt_pk_bf16_f32 v116, v44, v45
	v_cvt_pk_bf16_f32 v117, v46, v47
	global_store_dwordx2 v130, v[116:117], s[10:11] offset:3584
	s_nop 0
	s_mov_b32 s2, s12
	s_branch .Lp1x_top1
.Lp1x_last0:
	s_waitcnt vmcnt(0)
	v_pk_mul_f32 v[114:115], v[16:17], v[16:17]
	v_pk_fma_f32 v[114:115], v[18:19], v[18:19], v[114:115]
	v_pk_fma_f32 v[114:115], v[20:21], v[20:21], v[114:115]
	v_pk_fma_f32 v[114:115], v[22:23], v[22:23], v[114:115]
	v_pk_fma_f32 v[114:115], v[24:25], v[24:25], v[114:115]
	v_pk_fma_f32 v[114:115], v[26:27], v[26:27], v[114:115]
	v_pk_fma_f32 v[114:115], v[28:29], v[28:29], v[114:115]
	v_pk_fma_f32 v[114:115], v[30:31], v[30:31], v[114:115]
	v_pk_mul_f32 v[116:117], v[32:33], v[32:33]
	v_pk_fma_f32 v[116:117], v[34:35], v[34:35], v[116:117]
	v_pk_fma_f32 v[116:117], v[36:37], v[36:37], v[116:117]
	v_pk_fma_f32 v[116:117], v[38:39], v[38:39], v[116:117]
	v_pk_fma_f32 v[116:117], v[40:41], v[40:41], v[116:117]
	v_pk_fma_f32 v[116:117], v[42:43], v[42:43], v[116:117]
	v_pk_fma_f32 v[116:117], v[44:45], v[44:45], v[116:117]
	v_pk_fma_f32 v[116:117], v[46:47], v[46:47], v[116:117]
	v_add_f32_e32 v112, v114, v115
	v_add_f32_e32 v113, v116, v117
	v_add_f32_dpp v112, v112, v112 quad_perm:[1,0,3,2] row_mask:0xf bank_mask:0xf bound_ctrl:1
	v_add_f32_dpp v113, v113, v113 quad_perm:[1,0,3,2] row_mask:0xf bank_mask:0xf bound_ctrl:1
	s_nop 0
	v_add_f32_dpp v112, v112, v112 quad_perm:[2,3,0,1] row_mask:0xf bank_mask:0xf bound_ctrl:1
	v_add_f32_dpp v113, v113, v113 quad_perm:[2,3,0,1] row_mask:0xf bank_mask:0xf bound_ctrl:1
	s_nop 0
	v_add_f32_dpp v112, v112, v112 row_half_mirror row_mask:0xf bank_mask:0xf bound_ctrl:1
	v_add_f32_dpp v113, v113, v113 row_half_mirror row_mask:0xf bank_mask:0xf bound_ctrl:1
	s_nop 0
	v_add_f32_dpp v112, v112, v112 row_mirror row_mask:0xf bank_mask:0xf bound_ctrl:1
	v_add_f32_dpp v113, v113, v113 row_mirror row_mask:0xf bank_mask:0xf bound_ctrl:1
	s_nop 1
	v_readlane_b32 s20, v112, 0
	v_readlane_b32 s24, v113, 0
	v_readlane_b32 s21, v112, 16
	v_readlane_b32 s25, v113, 16
	v_readlane_b32 s22, v112, 32
	v_readlane_b32 s26, v113, 32
	v_readlane_b32 s23, v112, 48
	v_readlane_b32 s28, v113, 48
	s_nop 1
	v_mov_b32_e32 v112, s21
	v_mov_b32_e32 v114, s23
	v_mov_b32_e32 v113, s25
	v_mov_b32_e32 v115, s28
	v_add_f32_e32 v112, s20, v112
	v_add_f32_e32 v114, s22, v114
	v_add_f32_e32 v113, s24, v113
	v_add_f32_e32 v115, s26, v115
	v_add_f32_e32 v112, v112, v114
	v_add_f32_e32 v113, v113, v115
	v_fmamk_f32 v112, v112, 0x3a800000, v138
	v_mul_f32_e32 v114, 0x4b800000, v112
	v_cmp_gt_f32_e32 vcc, s29, v112
	s_nop 1
	v_cndmask_b32_e32 v112, v112, v114, vcc
	v_rsq_f32_e32 v139, v112
	s_nop 0
	v_mul_f32_e32 v114, 0x45800000, v139
	v_cndmask_b32_e32 v139, v139, v114, vcc
	v_fmamk_f32 v113, v113, 0x3a800000, v138
	v_mul_f32_e32 v114, 0x4b800000, v113
	v_cmp_gt_f32_e32 vcc, s29, v113
	s_nop 1
	v_cndmask_b32_e32 v113, v113, v114, vcc
	v_rsq_f32_e32 v140, v113
	s_nop 0
	v_mul_f32_e32 v114, 0x45800000, v140
	v_cndmask_b32_e32 v140, v140, v114, vcc
	v_add_f32_e32 v80, 1.0, v80
	v_add_f32_e32 v81, 1.0, v81
	v_add_f32_e32 v82, 1.0, v82
	v_add_f32_e32 v83, 1.0, v83
	v_add_f32_e32 v84, 1.0, v84
	v_add_f32_e32 v85, 1.0, v85
	v_add_f32_e32 v86, 1.0, v86
	v_add_f32_e32 v87, 1.0, v87
	v_add_f32_e32 v88, 1.0, v88
	v_add_f32_e32 v89, 1.0, v89
	v_add_f32_e32 v90, 1.0, v90
	v_add_f32_e32 v91, 1.0, v91
	v_add_f32_e32 v92, 1.0, v92
	v_add_f32_e32 v93, 1.0, v93
	v_add_f32_e32 v94, 1.0, v94
	v_add_f32_e32 v95, 1.0, v95
	v_mul_f32_e32 v16, v16, v139
	v_mul_f32_e32 v16, v0, v16
	v_fma_f32 v16, v80, v16, v96
	v_mul_f32_e32 v17, v17, v139
	v_mul_f32_e32 v17, v1, v17
	v_fma_f32 v17, v81, v17, v97
	v_mul_f32_e32 v18, v18, v139
	v_mul_f32_e32 v18, v2, v18
	v_fma_f32 v18, v82, v18, v98
	v_mul_f32_e32 v19, v19, v139
	v_mul_f32_e32 v19, v3, v19
	v_fma_f32 v19, v83, v19, v99
	v_cvt_pk_bf16_f32 v116, v16, v17
	v_cvt_pk_bf16_f32 v117, v18, v19
	global_store_dwordx2 v130, v[116:117], s[10:11]
	s_nop 0
	v_mul_f32_e32 v20, v20, v139
	v_mul_f32_e32 v20, v4, v20
	v_fma_f32 v20, v84, v20, v100
	v_mul_f32_e32 v21, v21, v139
	v_mul_f32_e32 v21, v5, v21
	v_fma_f32 v21, v85, v21, v101
	v_mul_f32_e32 v22, v22, v139
	v_mul_f32_e32 v22, v6, v22
	v_fma_f32 v22, v86, v22, v102
	v_mul_f32_e32 v23, v23, v139
	v_mul_f32_e32 v23, v7, v23
	v_fma_f32 v23, v87, v23, v103
	v_cvt_pk_bf16_f32 v116, v20, v21
	v_cvt_pk_bf16_f32 v117, v22, v23
	global_store_dwordx2 v130, v[116:117], s[10:11] offset:512
	s_nop 0
	v_mul_f32_e32 v24, v24, v139
	v_mul_f32_e32 v24, v8, v24
	v_fma_f32 v24, v88, v24, v104
	v_mul_f32_e32 v25, v25, v139
	v_mul_f32_e32 v25, v9, v25
	v_fma_f32 v25, v89, v25, v105
	v_mul_f32_e32 v26, v26, v139
	v_mul_f32_e32 v26, v10, v26
	v_fma_f32 v26, v90, v26, v106
	v_mul_f32_e32 v27, v27, v139
	v_mul_f32_e32 v27, v11, v27
	v_fma_f32 v27, v91, v27, v107
	v_cvt_pk_bf16_f32 v116, v24, v25
	v_cvt_pk_bf16_f32 v117, v26, v27
	global_store_dwordx2 v130, v[116:117], s[10:11] offset:1024
	s_nop 0
	v_mul_f32_e32 v28, v28, v139
	v_mul_f32_e32 v28, v12, v28
	v_fma_f32 v28, v92, v28, v108
	v_mul_f32_e32 v29, v29, v139
	v_mul_f32_e32 v29, v13, v29
	v_fma_f32 v29, v93, v29, v109
	v_mul_f32_e32 v30, v30, v139
	v_mul_f32_e32 v30, v14, v30
	v_fma_f32 v30, v94, v30, v110
	v_mul_f32_e32 v31, v31, v139
	v_mul_f32_e32 v31, v15, v31
	v_fma_f32 v31, v95, v31, v111
	v_cvt_pk_bf16_f32 v116, v28, v29
	v_cvt_pk_bf16_f32 v117, v30, v31
	global_store_dwordx2 v130, v[116:117], s[10:11] offset:1536
	s_nop 0
	v_mul_f32_e32 v32, v32, v140
	v_mul_f32_e32 v32, v0, v32
	v_fma_f32 v32, v80, v32, v96
	v_mul_f32_e32 v33, v33, v140
	v_mul_f32_e32 v33, v1, v33
	v_fma_f32 v33, v81, v33, v97
	v_mul_f32_e32 v34, v34, v140
	v_mul_f32_e32 v34, v2, v34
	v_fma_f32 v34, v82, v34, v98
	v_mul_f32_e32 v35, v35, v140
	v_mul_f32_e32 v35, v3, v35
	v_fma_f32 v35, v83, v35, v99
	v_cvt_pk_bf16_f32 v116, v32, v33
	v_cvt_pk_bf16_f32 v117, v34, v35
	global_store_dwordx2 v130, v[116:117], s[10:11] offset:2048
	s_nop 0
	v_mul_f32_e32 v36, v36, v140
	v_mul_f32_e32 v36, v4, v36
	v_fma_f32 v36, v84, v36, v100
	v_mul_f32_e32 v37, v37, v140
	v_mul_f32_e32 v37, v5, v37
	v_fma_f32 v37, v85, v37, v101
	v_mul_f32_e32 v38, v38, v140
	v_mul_f32_e32 v38, v6, v38
	v_fma_f32 v38, v86, v38, v102
	v_mul_f32_e32 v39, v39, v140
	v_mul_f32_e32 v39, v7, v39
	v_fma_f32 v39, v87, v39, v103
	v_cvt_pk_bf16_f32 v116, v36, v37
	v_cvt_pk_bf16_f32 v117, v38, v39
	global_store_dwordx2 v130, v[116:117], s[10:11] offset:2560
	s_nop 0
	v_mul_f32_e32 v40, v40, v140
	v_mul_f32_e32 v40, v8, v40
	v_fma_f32 v40, v88, v40, v104
	v_mul_f32_e32 v41, v41, v140
	v_mul_f32_e32 v41, v9, v41
	v_fma_f32 v41, v89, v41, v105
	v_mul_f32_e32 v42, v42, v140
	v_mul_f32_e32 v42, v10, v42
	v_fma_f32 v42, v90, v42, v106
	v_mul_f32_e32 v43, v43, v140
	v_mul_f32_e32 v43, v11, v43
	v_fma_f32 v43, v91, v43, v107
	v_cvt_pk_bf16_f32 v116, v40, v41
	v_cvt_pk_bf16_f32 v117, v42, v43
	global_store_dwordx2 v130, v[116:117], s[10:11] offset:3072
	s_nop 0
	v_mul_f32_e32 v44, v44, v140
	v_mul_f32_e32 v44, v12, v44
	v_fma_f32 v44, v92, v44, v108
	v_mul_f32_e32 v45, v45, v140
	v_mul_f32_e32 v45, v13, v45
	v_fma_f32 v45, v93, v45, v109
	v_mul_f32_e32 v46, v46, v140
	v_mul_f32_e32 v46, v14, v46
	v_fma_f32 v46, v94, v46, v110
	v_mul_f32_e32 v47, v47, v140
	v_mul_f32_e32 v47, v15, v47
	v_fma_f32 v47, v95, v47, v111
	v_cvt_pk_bf16_f32 v116, v44, v45
	v_cvt_pk_bf16_f32 v117, v46, v47
	global_store_dwordx2 v130, v[116:117], s[10:11] offset:3584
	s_nop 0
	s_branch .LBB0_179
.Lp1x_top1:
	s_lshr_b32 s4, s2, 8
	s_mul_i32 s4, s4, 0x3000
	s_add_u32 s16, s18, s4
	s_addc_u32 s17, s19, 0
	global_load_dwordx4 v[96:99], v128, s[16:17]
	global_load_dwordx4 v[100:103], v128, s[16:17] offset:1024
	global_load_dwordx4 v[104:107], v128, s[16:17] offset:2048
	global_load_dwordx4 v[108:111], v128, s[16:17] offset:3072
	global_load_dwordx4 v[80:83], v129, s[16:17]
	global_load_dwordx4 v[84:87], v129, s[16:17] offset:1024
	global_load_dwordx4 v[88:91], v129, s[16:17] offset:2048
	global_load_dwordx4 v[92:95], v129, s[16:17] offset:3072
	s_lshl_b32 s4, s2, 4
	s_add_u32 s4, s4, s3
	s_lshl_b32 s4, s4, 11
	s_add_u32 s10, s94, s4
	s_addc_u32 s11, s95, 0
	s_add_u32 s12, s2, 0xe0
	s_cmp_lt_u32 s12, 0x800
	s_cbranch_scc0 .Lp1x_last1
	s_lshl_b32 s4, s12, 4
	s_add_u32 s4, s4, s3
	s_lshl_b32 s5, s4, 12
	s_add_u32 s14, s52, s5
	s_addc_u32 s15, s53, 0
	global_load_dwordx4 v[16:19], v128, s[14:15]
	global_load_dwordx4 v[20:23], v128, s[14:15] offset:1024
	global_load_dwordx4 v[24:27], v128, s[14:15] offset:2048
	global_load_dwordx4 v[28:31], v128, s[14:15] offset:3072
	global_load_dwordx4 v[32:35], v129, s[14:15]
	global_load_dwordx4 v[36:39], v129, s[14:15] offset:1024
	global_load_dwordx4 v[40:43], v129, s[14:15] offset:2048
	global_load_dwordx4 v[44:47], v129, s[14:15] offset:3072
	s_waitcnt vmcnt(8)
	v_pk_mul_f32 v[114:115], v[48:49], v[48:49]
	v_pk_fma_f32 v[114:115], v[50:51], v[50:51], v[114:115]
	v_pk_fma_f32 v[114:115], v[52:53], v[52:53], v[114:115]
	v_pk_fma_f32 v[114:115], v[54:55], v[54:55], v[114:115]
	v_pk_fma_f32 v[114:115], v[56:57], v[56:57], v[114:115]
	v_pk_fma_f32 v[114:115], v[58:59], v[58:59], v[114:115]
	v_pk_fma_f32 v[114:115], v[60:61], v[60:61], v[114:115]
	v_pk_fma_f32 v[114:115], v[62:63], v[62:63], v[114:115]
	v_pk_mul_f32 v[116:117], v[64:65], v[64:65]
	v_pk_fma_f32 v[116:117], v[66:67], v[66:67], v[116:117]
	v_pk_fma_f32 v[116:117], v[68:69], v[68:69], v[116:117]
	v_pk_fma_f32 v[116:117], v[70:71], v[70:71], v[116:117]
	v_pk_fma_f32 v[116:117], v[72:73], v[72:73], v[116:117]
	v_pk_fma_f32 v[116:117], v[74:75], v[74:75], v[116:117]
	v_pk_fma_f32 v[116:117], v[76:77], v[76:77], v[116:117]
	v_pk_fma_f32 v[116:117], v[78:79], v[78:79], v[116:117]
	v_add_f32_e32 v112, v114, v115
	v_add_f32_e32 v113, v116, v117
	v_add_f32_dpp v112, v112, v112 quad_perm:[1,0,3,2] row_mask:0xf bank_mask:0xf bound_ctrl:1
	v_add_f32_dpp v113, v113, v113 quad_perm:[1,0,3,2] row_mask:0xf bank_mask:0xf bound_ctrl:1
	s_nop 0
	v_add_f32_dpp v112, v112, v112 quad_perm:[2,3,0,1] row_mask:0xf bank_mask:0xf bound_ctrl:1
	v_add_f32_dpp v113, v113, v113 quad_perm:[2,3,0,1] row_mask:0xf bank_mask:0xf bound_ctrl:1
	s_nop 0
	v_add_f32_dpp v112, v112, v112 row_half_mirror row_mask:0xf bank_mask:0xf bound_ctrl:1
	v_add_f32_dpp v113, v113, v113 row_half_mirror row_mask:0xf bank_mask:0xf bound_ctrl:1
	s_nop 0
	v_add_f32_dpp v112, v112, v112 row_mirror row_mask:0xf bank_mask:0xf bound_ctrl:1
	v_add_f32_dpp v113, v113, v113 row_mirror row_mask:0xf bank_mask:0xf bound_ctrl:1
	s_nop 1
	v_readlane_b32 s20, v112, 0
	v_readlane_b32 s24, v113, 0
	v_readlane_b32 s21, v112, 16
	v_readlane_b32 s25, v113, 16
	v_readlane_b32 s22, v112, 32
	v_readlane_b32 s26, v113, 32
	v_readlane_b32 s23, v112, 48
	v_readlane_b32 s28, v113, 48
	s_nop 1
	v_mov_b32_e32 v112, s21
	v_mov_b32_e32 v114, s23
	v_mov_b32_e32 v113, s25
	v_mov_b32_e32 v115, s28
	v_add_f32_e32 v112, s20, v112
	v_add_f32_e32 v114, s22, v114
	v_add_f32_e32 v113, s24, v113
	v_add_f32_e32 v115, s26, v115
	v_add_f32_e32 v112, v112, v114
	v_add_f32_e32 v113, v113, v115
	v_fmamk_f32 v112, v112, 0x3a800000, v138
	v_mul_f32_e32 v114, 0x4b800000, v112
	v_cmp_gt_f32_e32 vcc, s29, v112
	s_nop 1
	v_cndmask_b32_e32 v112, v112, v114, vcc
	v_rsq_f32_e32 v139, v112
	s_nop 0
	v_mul_f32_e32 v114, 0x45800000, v139
	v_cndmask_b32_e32 v139, v139, v114, vcc
	v_fmamk_f32 v113, v113, 0x3a800000, v138
	v_mul_f32_e32 v114, 0x4b800000, v113
	v_cmp_gt_f32_e32 vcc, s29, v113
	s_nop 1
	v_cndmask_b32_e32 v113, v113, v114, vcc
	v_rsq_f32_e32 v140, v113
	s_nop 0
	v_mul_f32_e32 v114, 0x45800000, v140
	v_cndmask_b32_e32 v140, v140, v114, vcc
	v_add_f32_e32 v80, 1.0, v80
	v_add_f32_e32 v81, 1.0, v81
	v_add_f32_e32 v82, 1.0, v82
	v_add_f32_e32 v83, 1.0, v83
	v_add_f32_e32 v84, 1.0, v84
	v_add_f32_e32 v85, 1.0, v85
	v_add_f32_e32 v86, 1.0, v86
	v_add_f32_e32 v87, 1.0, v87
	v_add_f32_e32 v88, 1.0, v88
	v_add_f32_e32 v89, 1.0, v89
	v_add_f32_e32 v90, 1.0, v90
	v_add_f32_e32 v91, 1.0, v91
	v_add_f32_e32 v92, 1.0, v92
	v_add_f32_e32 v93, 1.0, v93
	v_add_f32_e32 v94, 1.0, v94
	v_add_f32_e32 v95, 1.0, v95
	v_mul_f32_e32 v48, v48, v139
	v_mul_f32_e32 v48, v0, v48
	v_fma_f32 v48, v80, v48, v96
	v_mul_f32_e32 v49, v49, v139
	v_mul_f32_e32 v49, v1, v49
	v_fma_f32 v49, v81, v49, v97
	v_mul_f32_e32 v50, v50, v139
	v_mul_f32_e32 v50, v2, v50
	v_fma_f32 v50, v82, v50, v98
	v_mul_f32_e32 v51, v51, v139
	v_mul_f32_e32 v51, v3, v51
	v_fma_f32 v51, v83, v51, v99
	v_cvt_pk_bf16_f32 v116, v48, v49
	v_cvt_pk_bf16_f32 v117, v50, v51
	global_store_dwordx2 v130, v[116:117], s[10:11]
	s_nop 0
	v_mul_f32_e32 v52, v52, v139
	v_mul_f32_e32 v52, v4, v52
	v_fma_f32 v52, v84, v52, v100
	v_mul_f32_e32 v53, v53, v139
	v_mul_f32_e32 v53, v5, v53
	v_fma_f32 v53, v85, v53, v101
	v_mul_f32_e32 v54, v54, v139
	v_mul_f32_e32 v54, v6, v54
	v_fma_f32 v54, v86, v54, v102
	v_mul_f32_e32 v55, v55, v139
	v_mul_f32_e32 v55, v7, v55
	v_fma_f32 v55, v87, v55, v103
	v_cvt_pk_bf16_f32 v116, v52, v53
	v_cvt_pk_bf16_f32 v117, v54, v55
	global_store_dwordx2 v130, v[116:117], s[10:11] offset:512
	s_nop 0
	v_mul_f32_e32 v56, v56, v139
	v_mul_f32_e32 v56, v8, v56
	v_fma_f32 v56, v88, v56, v104
	v_mul_f32_e32 v57, v57, v139
	v_mul_f32_e32 v57, v9, v57
	v_fma_f32 v57, v89, v57, v105
	v_mul_f32_e32 v58, v58, v139
	v_mul_f32_e32 v58, v10, v58
	v_fma_f32 v58, v90, v58, v106
	v_mul_f32_e32 v59, v59, v139
	v_mul_f32_e32 v59, v11, v59
	v_fma_f32 v59, v91, v59, v107
	v_cvt_pk_bf16_f32 v116, v56, v57
	v_cvt_pk_bf16_f32 v117, v58, v59
	global_store_dwordx2 v130, v[116:117], s[10:11] offset:1024
	s_nop 0
	v_mul_f32_e32 v60, v60, v139
	v_mul_f32_e32 v60, v12, v60
	v_fma_f32 v60, v92, v60, v108
	v_mul_f32_e32 v61, v61, v139
	v_mul_f32_e32 v61, v13, v61
	v_fma_f32 v61, v93, v61, v109
	v_mul_f32_e32 v62, v62, v139
	v_mul_f32_e32 v62, v14, v62
	v_fma_f32 v62, v94, v62, v110
	v_mul_f32_e32 v63, v63, v139
	v_mul_f32_e32 v63, v15, v63
	v_fma_f32 v63, v95, v63, v111
	v_cvt_pk_bf16_f32 v116, v60, v61
	v_cvt_pk_bf16_f32 v117, v62, v63
	global_store_dwordx2 v130, v[116:117], s[10:11] offset:1536
	s_nop 0
	v_mul_f32_e32 v64, v64, v140
	v_mul_f32_e32 v64, v0, v64
	v_fma_f32 v64, v80, v64, v96
	v_mul_f32_e32 v65, v65, v140
	v_mul_f32_e32 v65, v1, v65
	v_fma_f32 v65, v81, v65, v97
	v_mul_f32_e32 v66, v66, v140
	v_mul_f32_e32 v66, v2, v66
	v_fma_f32 v66, v82, v66, v98
	v_mul_f32_e32 v67, v67, v140
	v_mul_f32_e32 v67, v3, v67
	v_fma_f32 v67, v83, v67, v99
	v_cvt_pk_bf16_f32 v116, v64, v65
	v_cvt_pk_bf16_f32 v117, v66, v67
	global_store_dwordx2 v130, v[116:117], s[10:11] offset:2048
	s_nop 0
	v_mul_f32_e32 v68, v68, v140
	v_mul_f32_e32 v68, v4, v68
	v_fma_f32 v68, v84, v68, v100
	v_mul_f32_e32 v69, v69, v140
	v_mul_f32_e32 v69, v5, v69
	v_fma_f32 v69, v85, v69, v101
	v_mul_f32_e32 v70, v70, v140
	v_mul_f32_e32 v70, v6, v70
	v_fma_f32 v70, v86, v70, v102
	v_mul_f32_e32 v71, v71, v140
	v_mul_f32_e32 v71, v7, v71
	v_fma_f32 v71, v87, v71, v103
	v_cvt_pk_bf16_f32 v116, v68, v69
	v_cvt_pk_bf16_f32 v117, v70, v71
	global_store_dwordx2 v130, v[116:117], s[10:11] offset:2560
	s_nop 0
	v_mul_f32_e32 v72, v72, v140
	v_mul_f32_e32 v72, v8, v72
	v_fma_f32 v72, v88, v72, v104
	v_mul_f32_e32 v73, v73, v140
	v_mul_f32_e32 v73, v9, v73
	v_fma_f32 v73, v89, v73, v105
	v_mul_f32_e32 v74, v74, v140
	v_mul_f32_e32 v74, v10, v74
	v_fma_f32 v74, v90, v74, v106
	v_mul_f32_e32 v75, v75, v140
	v_mul_f32_e32 v75, v11, v75
	v_fma_f32 v75, v91, v75, v107
	v_cvt_pk_bf16_f32 v116, v72, v73
	v_cvt_pk_bf16_f32 v117, v74, v75
	global_store_dwordx2 v130, v[116:117], s[10:11] offset:3072
	s_nop 0
	v_mul_f32_e32 v76, v76, v140
	v_mul_f32_e32 v76, v12, v76
	v_fma_f32 v76, v92, v76, v108
	v_mul_f32_e32 v77, v77, v140
	v_mul_f32_e32 v77, v13, v77
	v_fma_f32 v77, v93, v77, v109
	v_mul_f32_e32 v78, v78, v140
	v_mul_f32_e32 v78, v14, v78
	v_fma_f32 v78, v94, v78, v110
	v_mul_f32_e32 v79, v79, v140
	v_mul_f32_e32 v79, v15, v79
	v_fma_f32 v79, v95, v79, v111
	v_cvt_pk_bf16_f32 v116, v76, v77
	v_cvt_pk_bf16_f32 v117, v78, v79
	global_store_dwordx2 v130, v[116:117], s[10:11] offset:3584
	s_nop 0
	s_mov_b32 s2, s12
	s_branch .Lp1x_top0
.Lp1x_last1:
	s_waitcnt vmcnt(0)
	v_pk_mul_f32 v[114:115], v[48:49], v[48:49]
	v_pk_fma_f32 v[114:115], v[50:51], v[50:51], v[114:115]
	v_pk_fma_f32 v[114:115], v[52:53], v[52:53], v[114:115]
	v_pk_fma_f32 v[114:115], v[54:55], v[54:55], v[114:115]
	v_pk_fma_f32 v[114:115], v[56:57], v[56:57], v[114:115]
	v_pk_fma_f32 v[114:115], v[58:59], v[58:59], v[114:115]
	v_pk_fma_f32 v[114:115], v[60:61], v[60:61], v[114:115]
	v_pk_fma_f32 v[114:115], v[62:63], v[62:63], v[114:115]
	v_pk_mul_f32 v[116:117], v[64:65], v[64:65]
	v_pk_fma_f32 v[116:117], v[66:67], v[66:67], v[116:117]
	v_pk_fma_f32 v[116:117], v[68:69], v[68:69], v[116:117]
	v_pk_fma_f32 v[116:117], v[70:71], v[70:71], v[116:117]
	v_pk_fma_f32 v[116:117], v[72:73], v[72:73], v[116:117]
	v_pk_fma_f32 v[116:117], v[74:75], v[74:75], v[116:117]
	v_pk_fma_f32 v[116:117], v[76:77], v[76:77], v[116:117]
	v_pk_fma_f32 v[116:117], v[78:79], v[78:79], v[116:117]
	v_add_f32_e32 v112, v114, v115
	v_add_f32_e32 v113, v116, v117
	v_add_f32_dpp v112, v112, v112 quad_perm:[1,0,3,2] row_mask:0xf bank_mask:0xf bound_ctrl:1
	v_add_f32_dpp v113, v113, v113 quad_perm:[1,0,3,2] row_mask:0xf bank_mask:0xf bound_ctrl:1
	s_nop 0
	v_add_f32_dpp v112, v112, v112 quad_perm:[2,3,0,1] row_mask:0xf bank_mask:0xf bound_ctrl:1
	v_add_f32_dpp v113, v113, v113 quad_perm:[2,3,0,1] row_mask:0xf bank_mask:0xf bound_ctrl:1
	s_nop 0
	v_add_f32_dpp v112, v112, v112 row_half_mirror row_mask:0xf bank_mask:0xf bound_ctrl:1
	v_add_f32_dpp v113, v113, v113 row_half_mirror row_mask:0xf bank_mask:0xf bound_ctrl:1
	s_nop 0
	v_add_f32_dpp v112, v112, v112 row_mirror row_mask:0xf bank_mask:0xf bound_ctrl:1
	v_add_f32_dpp v113, v113, v113 row_mirror row_mask:0xf bank_mask:0xf bound_ctrl:1
	s_nop 1
	v_readlane_b32 s20, v112, 0
	v_readlane_b32 s24, v113, 0
	v_readlane_b32 s21, v112, 16
	v_readlane_b32 s25, v113, 16
	v_readlane_b32 s22, v112, 32
	v_readlane_b32 s26, v113, 32
	v_readlane_b32 s23, v112, 48
	v_readlane_b32 s28, v113, 48
	s_nop 1
	v_mov_b32_e32 v112, s21
	v_mov_b32_e32 v114, s23
	v_mov_b32_e32 v113, s25
	v_mov_b32_e32 v115, s28
	v_add_f32_e32 v112, s20, v112
	v_add_f32_e32 v114, s22, v114
	v_add_f32_e32 v113, s24, v113
	v_add_f32_e32 v115, s26, v115
	v_add_f32_e32 v112, v112, v114
	v_add_f32_e32 v113, v113, v115
	v_fmamk_f32 v112, v112, 0x3a800000, v138
	v_mul_f32_e32 v114, 0x4b800000, v112
	v_cmp_gt_f32_e32 vcc, s29, v112
	s_nop 1
	v_cndmask_b32_e32 v112, v112, v114, vcc
	v_rsq_f32_e32 v139, v112
	s_nop 0
	v_mul_f32_e32 v114, 0x45800000, v139
	v_cndmask_b32_e32 v139, v139, v114, vcc
	v_fmamk_f32 v113, v113, 0x3a800000, v138
	v_mul_f32_e32 v114, 0x4b800000, v113
	v_cmp_gt_f32_e32 vcc, s29, v113
	s_nop 1
	v_cndmask_b32_e32 v113, v113, v114, vcc
	v_rsq_f32_e32 v140, v113
	s_nop 0
	v_mul_f32_e32 v114, 0x45800000, v140
	v_cndmask_b32_e32 v140, v140, v114, vcc
	v_add_f32_e32 v80, 1.0, v80
	v_add_f32_e32 v81, 1.0, v81
	v_add_f32_e32 v82, 1.0, v82
	v_add_f32_e32 v83, 1.0, v83
	v_add_f32_e32 v84, 1.0, v84
	v_add_f32_e32 v85, 1.0, v85
	v_add_f32_e32 v86, 1.0, v86
	v_add_f32_e32 v87, 1.0, v87
	v_add_f32_e32 v88, 1.0, v88
	v_add_f32_e32 v89, 1.0, v89
	v_add_f32_e32 v90, 1.0, v90
	v_add_f32_e32 v91, 1.0, v91
	v_add_f32_e32 v92, 1.0, v92
	v_add_f32_e32 v93, 1.0, v93
	v_add_f32_e32 v94, 1.0, v94
	v_add_f32_e32 v95, 1.0, v95
	v_mul_f32_e32 v48, v48, v139
	v_mul_f32_e32 v48, v0, v48
	v_fma_f32 v48, v80, v48, v96
	v_mul_f32_e32 v49, v49, v139
	v_mul_f32_e32 v49, v1, v49
	v_fma_f32 v49, v81, v49, v97
	v_mul_f32_e32 v50, v50, v139
	v_mul_f32_e32 v50, v2, v50
	v_fma_f32 v50, v82, v50, v98
	v_mul_f32_e32 v51, v51, v139
	v_mul_f32_e32 v51, v3, v51
	v_fma_f32 v51, v83, v51, v99
	v_cvt_pk_bf16_f32 v116, v48, v49
	v_cvt_pk_bf16_f32 v117, v50, v51
	global_store_dwordx2 v130, v[116:117], s[10:11]
	s_nop 0
	v_mul_f32_e32 v52, v52, v139
	v_mul_f32_e32 v52, v4, v52
	v_fma_f32 v52, v84, v52, v100
	v_mul_f32_e32 v53, v53, v139
	v_mul_f32_e32 v53, v5, v53
	v_fma_f32 v53, v85, v53, v101
	v_mul_f32_e32 v54, v54, v139
	v_mul_f32_e32 v54, v6, v54
	v_fma_f32 v54, v86, v54, v102
	v_mul_f32_e32 v55, v55, v139
	v_mul_f32_e32 v55, v7, v55
	v_fma_f32 v55, v87, v55, v103
	v_cvt_pk_bf16_f32 v116, v52, v53
	v_cvt_pk_bf16_f32 v117, v54, v55
	global_store_dwordx2 v130, v[116:117], s[10:11] offset:512
	s_nop 0
	v_mul_f32_e32 v56, v56, v139
	v_mul_f32_e32 v56, v8, v56
	v_fma_f32 v56, v88, v56, v104
	v_mul_f32_e32 v57, v57, v139
	v_mul_f32_e32 v57, v9, v57
	v_fma_f32 v57, v89, v57, v105
	v_mul_f32_e32 v58, v58, v139
	v_mul_f32_e32 v58, v10, v58
	v_fma_f32 v58, v90, v58, v106
	v_mul_f32_e32 v59, v59, v139
	v_mul_f32_e32 v59, v11, v59
	v_fma_f32 v59, v91, v59, v107
	v_cvt_pk_bf16_f32 v116, v56, v57
	v_cvt_pk_bf16_f32 v117, v58, v59
	global_store_dwordx2 v130, v[116:117], s[10:11] offset:1024
	s_nop 0
	v_mul_f32_e32 v60, v60, v139
	v_mul_f32_e32 v60, v12, v60
	v_fma_f32 v60, v92, v60, v108
	v_mul_f32_e32 v61, v61, v139
	v_mul_f32_e32 v61, v13, v61
	v_fma_f32 v61, v93, v61, v109
	v_mul_f32_e32 v62, v62, v139
	v_mul_f32_e32 v62, v14, v62
	v_fma_f32 v62, v94, v62, v110
	v_mul_f32_e32 v63, v63, v139
	v_mul_f32_e32 v63, v15, v63
	v_fma_f32 v63, v95, v63, v111
	v_cvt_pk_bf16_f32 v116, v60, v61
	v_cvt_pk_bf16_f32 v117, v62, v63
	global_store_dwordx2 v130, v[116:117], s[10:11] offset:1536
	s_nop 0
	v_mul_f32_e32 v64, v64, v140
	v_mul_f32_e32 v64, v0, v64
	v_fma_f32 v64, v80, v64, v96
	v_mul_f32_e32 v65, v65, v140
	v_mul_f32_e32 v65, v1, v65
	v_fma_f32 v65, v81, v65, v97
	v_mul_f32_e32 v66, v66, v140
	v_mul_f32_e32 v66, v2, v66
	v_fma_f32 v66, v82, v66, v98
	v_mul_f32_e32 v67, v67, v140
	v_mul_f32_e32 v67, v3, v67
	v_fma_f32 v67, v83, v67, v99
	v_cvt_pk_bf16_f32 v116, v64, v65
	v_cvt_pk_bf16_f32 v117, v66, v67
	global_store_dwordx2 v130, v[116:117], s[10:11] offset:2048
	s_nop 0
	v_mul_f32_e32 v68, v68, v140
	v_mul_f32_e32 v68, v4, v68
	v_fma_f32 v68, v84, v68, v100
	v_mul_f32_e32 v69, v69, v140
	v_mul_f32_e32 v69, v5, v69
	v_fma_f32 v69, v85, v69, v101
	v_mul_f32_e32 v70, v70, v140
	v_mul_f32_e32 v70, v6, v70
	v_fma_f32 v70, v86, v70, v102
	v_mul_f32_e32 v71, v71, v140
	v_mul_f32_e32 v71, v7, v71
	v_fma_f32 v71, v87, v71, v103
	v_cvt_pk_bf16_f32 v116, v68, v69
	v_cvt_pk_bf16_f32 v117, v70, v71
	global_store_dwordx2 v130, v[116:117], s[10:11] offset:2560
	s_nop 0
	v_mul_f32_e32 v72, v72, v140
	v_mul_f32_e32 v72, v8, v72
	v_fma_f32 v72, v88, v72, v104
	v_mul_f32_e32 v73, v73, v140
	v_mul_f32_e32 v73, v9, v73
	v_fma_f32 v73, v89, v73, v105
	v_mul_f32_e32 v74, v74, v140
	v_mul_f32_e32 v74, v10, v74
	v_fma_f32 v74, v90, v74, v106
	v_mul_f32_e32 v75, v75, v140
	v_mul_f32_e32 v75, v11, v75
	v_fma_f32 v75, v91, v75, v107
	v_cvt_pk_bf16_f32 v116, v72, v73
	v_cvt_pk_bf16_f32 v117, v74, v75
	global_store_dwordx2 v130, v[116:117], s[10:11] offset:3072
	s_nop 0
	v_mul_f32_e32 v76, v76, v140
	v_mul_f32_e32 v76, v12, v76
	v_fma_f32 v76, v92, v76, v108
	v_mul_f32_e32 v77, v77, v140
	v_mul_f32_e32 v77, v13, v77
	v_fma_f32 v77, v93, v77, v109
	v_mul_f32_e32 v78, v78, v140
	v_mul_f32_e32 v78, v14, v78
	v_fma_f32 v78, v94, v78, v110
	v_mul_f32_e32 v79, v79, v140
	v_mul_f32_e32 v79, v15, v79
	v_fma_f32 v79, v95, v79, v111
	v_cvt_pk_bf16_f32 v116, v76, v77
	v_cvt_pk_bf16_f32 v117, v78, v79
	global_store_dwordx2 v130, v[116:117], s[10:11] offset:3584
	s_nop 0
	s_branch .LBB0_179
